# speedup vs baseline: 1.0221x; 1.0077x over previous
; __device__ __forceinline__ float fexp2(float x) { return __builtin_amdgcn_exp2f(x); }
; __device__ __forceinline__ void ret_out_item(const Params& p, int j, int b, int cc, int h, const u16* __restrict__ Z,
;                                              const u16* __restrict__ RVT, const float* __restrict__ U, u16* sVT) {
;     ...
;   const int r0 = chunk_row0(b, cc), key0 = chunk_key0(cc);
;   const float lgf2 = log_sigmoid(p.ret_dec_f[j * 4 + h]) * LOG2E, lgb2 = log_sigmoid(p.ret_dec_b[j * 4 + h]) * LOG2E;
;   __syncthreads();
;   {
;     const u16* vt = RVT + (size_t)(b * 4 + h) * 128 * KEYS + key0;
;     {
;       uint4 vreg[8];
; #pragma unroll
;       for (int i = 0; i < 8; ++i) {
;         int c = tid + i * 256, e = c >> 4, kc = c & 15;
;         vreg[i] = *(const uint4*)(vt + (size_t)e * KEYS + kc * 8);
;       }
; #pragma unroll
;       for (int i = 0; i < 8; ++i) {
;         int c = tid + i * 256, e = c >> 4, kc = c & 15;
;         *(uint4*)(sVT + e * 136 + kc * 8) = vreg[i];
;       }
;     }
;   }
;   __syncthreads();
;   bf16x8 qf[2][2], qff[2][2], qfb[2][2];
; #pragma unroll
;   for (int qb = 0; qb < 2; ++qb) {
;     const int qpos = wave * 32 + qb * 16 + fr;
;     const float sf = fexp2((float)(qpos + 1) * lgf2), sb = fexp2((float)(128 - qpos) * lgb2);
; #pragma unroll
;     for (int ks = 0; ks < 2; ++ks) {
;       qf[qb][ks] = *(const bf16x8*)(Z + (size_t)(r0 + qpos) * 2304 + 1024 + h * 64 + ks * 32 + fq * 8);
;       qff[qb][ks] = scale8(qf[qb][ks], sf);
;       qfb[qb][ks] = scale8(qf[qb][ks], sb);
;     }
.LBB0_693:
	s_lshl_b32 s1, s7, 2
	s_or_b32 s1, s1, s22
	s_add_i32 s0, s12, s11
	s_mul_hi_i32 s8, s1, 0x90000
	s_mul_i32 s1, s1, 0x90000
	s_add_u32 s9, s78, s1
	s_addc_u32 s8, s79, s8
	s_ashr_i32 s1, s0, 31
	s_lshl_b64 s[0:1], s[0:1], 1
	v_mul_f32_e32 v163, 0xbfb8aa3b, v0
	s_add_u32 s0, s9, s0
	v_lshlrev_b32_e32 v0, 4, v2
	v_bfe_u32 v18, v2, 4, 4
	s_addc_u32 s1, s8, s1
	v_and_b32_e32 v0, 0xf0, v0
	v_mul_u32_u24_e32 v6, 0x900, v18
	v_lshl_add_u64 v[4:5], s[0:1], 0, v[0:1]
	v_lshlrev_b32_e32 v6, 1, v6
	v_mov_b32_e32 v7, v1
	v_lshl_add_u64 v[8:9], v[4:5], 0, v[6:7]
	v_add_u32_e32 v10, 0x48000, v6
	v_mov_b32_e32 v11, v1
	v_add_u32_e32 v12, 0x5a000, v6
	v_mov_b32_e32 v13, v1
	v_add_u32_e32 v14, 0x6c000, v6
	v_mov_b32_e32 v15, v1
	v_add_u32_e32 v6, 0x7e000, v6
	v_lshl_add_u64 v[10:11], v[4:5], 0, v[10:11]
	v_lshl_add_u64 v[12:13], v[4:5], 0, v[12:13]
	v_lshl_add_u64 v[14:15], v[4:5], 0, v[14:15]
	v_lshl_add_u64 v[16:17], v[4:5], 0, v[6:7]
	v_mul_u32_u24_e32 v4, 0x110, v18
	s_barrier
	v_add3_u32 v0, s58, v0, v4
	global_load_dwordx4 v[208:211], v[8:9], off
	s_mov_b32 s0, 0x12000
	v_and_b32_e32 v118, 15, v2
	s_movk_i32 s11, 0x60
	v_bfe_u32 v112, v2, 4, 2
	v_mul_f32_e32 v162, 0xbfb8aa3b, v3
	v_mov_b64_e32 v[140:141], s[70:71]
	s_lshl_b32 s34, s22, 7
	v_lshlrev_b32_e32 v136, 4, v112
	v_mov_b32_e32 v137, v1
	s_mul_i32 s7, s7, 18
	s_ashr_i32 s8, s6, 31
	v_lshlrev_b32_e32 v110, 7, v118
	v_mov_b32_e32 v111, v1
	v_add_u32_e32 v171, s10, v118
	v_add_co_u32_e32 v4, vcc, s0, v8
	s_mov_b32 s0, 0x24000
	s_nop 0
	v_addc_co_u32_e32 v5, vcc, 0, v9, vcc
	global_load_dwordx4 v[212:215], v[4:5], off
	v_add_co_u32_e32 v4, vcc, s0, v8
	s_mov_b32 s0, 0x36000
	s_nop 0
	v_addc_co_u32_e32 v5, vcc, 0, v9, vcc
	global_load_dwordx4 v[216:219], v[4:5], off
	v_add_co_u32_e32 v4, vcc, s0, v8
	s_nop 1
	v_addc_co_u32_e32 v5, vcc, 0, v9, vcc
	global_load_dwordx4 v[220:223], v[4:5], off
	global_load_dwordx4 v[224:227], v[10:11], off
	global_load_dwordx4 v[228:231], v[12:13], off
	global_load_dwordx4 v[232:235], v[14:15], off
	global_load_dwordx4 v[236:239], v[16:17], off
	s_waitcnt vmcnt(0)
	ds_write_b128 v0, v[208:211]
	ds_write_b128 v0, v[212:215] offset:4352
	ds_write_b128 v0, v[216:219] offset:8704
	ds_write_b128 v0, v[220:223] offset:13056
	ds_write_b128 v0, v[224:227] offset:17408
	ds_write_b128 v0, v[228:231] offset:21760
	ds_write_b128 v0, v[232:235] offset:26112
	ds_write_b128 v0, v[236:239] offset:30464
	v_lshrrev_b32_e32 v0, 1, v2
	v_and_or_b32 v113, v0, s11, v118
	v_add_u32_e32 v2, 1, v113
	v_cvt_f32_ubyte0_e32 v2, v2
	v_mul_f32_e32 v2, v163, v2
	v_exp_f32_e32 v6, v2
	v_sub_u32_e32 v2, 0x80, v113
	v_cvt_f32_ubyte0_e32 v2, v2
	v_add_u32_e32 v138, s10, v113
	v_mul_f32_e32 v2, v162, v2
	v_mad_i64_i32 v[142:143], s[0:1], v138, s26, v[140:141]
	v_exp_f32_e32 v8, v2
	v_lshl_add_u64 v[2:3], v[142:143], 0, s[34:35]
	v_lshl_add_u64 v[10:11], v[2:3], 0, v[136:137]
	s_waitcnt lgkmcnt(0)
	s_barrier
	global_load_dwordx4 v[2:5], v[10:11], off offset:2048
	v_lshlrev_b32_e32 v0, 3, v112
	v_ashrrev_i32_e32 v139, 31, v138
	s_waitcnt vmcnt(0)
	v_lshlrev_b32_e32 v12, 16, v2
	v_and_b32_e32 v13, 0xffff0000, v2
	v_pk_mul_f32 v[14:15], v[6:7], v[12:13] op_sel_hi:[0,1]
	v_pk_mul_f32 v[12:13], v[8:9], v[12:13] op_sel_hi:[0,1]
	v_cvt_pk_bf16_f32 v26, v12, v13
	v_lshlrev_b32_e32 v12, 16, v3
	v_and_b32_e32 v13, 0xffff0000, v3
	v_cvt_pk_bf16_f32 v22, v14, v15
	v_pk_mul_f32 v[14:15], v[6:7], v[12:13] op_sel_hi:[0,1]
	v_pk_mul_f32 v[12:13], v[8:9], v[12:13] op_sel_hi:[0,1]
	v_cvt_pk_bf16_f32 v27, v12, v13
	v_lshlrev_b32_e32 v12, 16, v4
	v_and_b32_e32 v13, 0xffff0000, v4
	v_cvt_pk_bf16_f32 v23, v14, v15
	v_pk_mul_f32 v[14:15], v[6:7], v[12:13] op_sel_hi:[0,1]
	v_pk_mul_f32 v[12:13], v[8:9], v[12:13] op_sel_hi:[0,1]
	v_cvt_pk_bf16_f32 v28, v12, v13
	v_lshlrev_b32_e32 v12, 16, v5
	v_and_b32_e32 v13, 0xffff0000, v5
	v_cvt_pk_bf16_f32 v24, v14, v15
	v_pk_mul_f32 v[14:15], v[6:7], v[12:13] op_sel_hi:[0,1]
	v_cvt_pk_bf16_f32 v25, v14, v15
	global_load_dwordx4 v[14:17], v[10:11], off offset:2112
	v_pk_mul_f32 v[12:13], v[8:9], v[12:13] op_sel_hi:[0,1]
	v_cvt_pk_bf16_f32 v29, v12, v13
	s_waitcnt vmcnt(0)
	v_lshlrev_b32_e32 v10, 16, v14
	v_and_b32_e32 v11, 0xffff0000, v14
	v_pk_mul_f32 v[12:13], v[6:7], v[10:11] op_sel_hi:[0,1]
	v_pk_mul_f32 v[10:11], v[8:9], v[10:11] op_sel_hi:[0,1]
	v_cvt_pk_bf16_f32 v34, v10, v11
	v_lshlrev_b32_e32 v10, 16, v15
	v_and_b32_e32 v11, 0xffff0000, v15
	v_cvt_pk_bf16_f32 v30, v12, v13
	v_pk_mul_f32 v[12:13], v[6:7], v[10:11] op_sel_hi:[0,1]
	v_pk_mul_f32 v[10:11], v[8:9], v[10:11] op_sel_hi:[0,1]
	v_cvt_pk_bf16_f32 v35, v10, v11
	v_lshlrev_b32_e32 v10, 16, v16
	v_and_b32_e32 v11, 0xffff0000, v16
	v_cvt_pk_bf16_f32 v31, v12, v13
	v_pk_mul_f32 v[12:13], v[6:7], v[10:11] op_sel_hi:[0,1]
	v_pk_mul_f32 v[10:11], v[8:9], v[10:11] op_sel_hi:[0,1]
	v_cvt_pk_bf16_f32 v36, v10, v11
	v_lshlrev_b32_e32 v10, 16, v17
	v_and_b32_e32 v11, 0xffff0000, v17
	v_pk_mul_f32 v[6:7], v[6:7], v[10:11] op_sel_hi:[0,1]
	v_cvt_pk_bf16_f32 v33, v6, v7
	v_pk_mul_f32 v[6:7], v[8:9], v[10:11] op_sel_hi:[0,1]
	v_cvt_pk_bf16_f32 v37, v6, v7
	v_add_u32_e32 v7, 17, v113
	v_cvt_f32_ubyte0_e32 v7, v7
	v_or_b32_e32 v6, 16, v113
	v_mul_f32_e32 v7, v163, v7
	v_exp_f32_e32 v18, v7
	v_sub_u32_e32 v7, 0x80, v6
	v_cvt_f32_ubyte0_e32 v7, v7
	v_mul_f32_e32 v7, v162, v7
	v_add_u32_e32 v6, s10, v6
	v_exp_f32_e32 v20, v7
	v_mad_i64_i32 v[6:7], s[0:1], v6, s26, v[140:141]
	v_lshl_add_u64 v[6:7], v[6:7], 0, s[34:35]
	v_lshl_add_u64 v[10:11], v[6:7], 0, v[136:137]
	global_load_dwordx4 v[6:9], v[10:11], off offset:2048
	v_cvt_pk_bf16_f32 v32, v12, v13
	s_ashr_i32 s1, s7, 31
	s_add_u32 s0, s7, s6
	s_addc_u32 s1, s1, s8
	s_lshl_b64 s[0:1], s[0:1], 16
	s_add_u32 s0, s76, s0
	s_addc_u32 s1, s77, s1
	s_lshl_b32 s6, s22, 14
	s_add_u32 s0, s0, s6
	s_addc_u32 s1, s1, 0
	v_lshl_add_u64 v[90:91], s[0:1], 0, v[136:137]
	s_mov_b64 s[0:1], 0x2400000
	v_lshl_add_u64 v[92:93], v[90:91], 0, s[0:1]
	s_add_u32 s0, s70, s34
	s_addc_u32 s1, s71, 0
	v_lshl_add_u64 v[144:145], s[0:1], 0, v[136:137]
	s_movk_i32 s6, 0x62
	s_lshl_b32 s34, s22, 8
	s_waitcnt vmcnt(0)
; __device__ __forceinline__ float fexp2(float x) { return __builtin_amdgcn_exp2f(x); }
; __device__ __forceinline__ void ret_out_item(const Params& p, int j, int b, int cc, int h, const u16* __restrict__ Z,
;                                              const u16* __restrict__ RVT, const float* __restrict__ U, u16* sVT) {
;     ...
;   bf16x8 qf[2][2], qff[2][2], qfb[2][2];
; #pragma unroll
;   for (int qb = 0; qb < 2; ++qb) {
;     const int qpos = wave * 32 + qb * 16 + fr;
;     const float sf = fexp2((float)(qpos + 1) * lgf2), sb = fexp2((float)(128 - qpos) * lgb2);
; #pragma unroll
;     for (int ks = 0; ks < 2; ++ks) {
;       qf[qb][ks] = *(const bf16x8*)(Z + (size_t)(r0 + qpos) * 2304 + 1024 + h * 64 + ks * 32 + fq * 8);
;       qff[qb][ks] = scale8(qf[qb][ks], sf);
;       qfb[qb][ks] = scale8(qf[qb][ks], sb);
;     }
;   }
;   f32x4 o[2][8];
; #pragma unroll
;   for (int a = 0; a < 2; ++a)
; #pragma unroll
;     for (int c = 0; c < 8; ++c) o[a][c] = (f32x4){0.f, 0.f, 0.f, 0.f};
;   {
;     const u16* Sf = (const u16*)U + ((((size_t)0 * 32 + b) * 18 + cc) * 4 + h) * 8192;
;     const u16* Sb = (const u16*)U + ((((size_t)1 * 32 + b) * 18 + cc) * 4 + h) * 8192;
; #pragma unroll
;     for (int eb = 0; eb < 8; ++eb)
; #pragma unroll
;       for (int ks = 0; ks < 2; ++ks) {
;         bf16x8 sf = *(const bf16x8*)(Sf + (eb * 16 + fr) * 64 + ks * 32 + fq * 8);
;         bf16x8 sb = *(const bf16x8*)(Sb + (eb * 16 + fr) * 64 + ks * 32 + fq * 8);
; #pragma unroll
;         for (int qb = 0; qb < 2; ++qb) {
;           o[qb][eb] = mfma16(sf, qff[qb][ks], o[qb][eb]);
;           o[qb][eb] = mfma16(sb, qfb[qb][ks], o[qb][eb]);
;         }
;       }
	v_lshlrev_b32_e32 v12, 16, v6
	v_and_b32_e32 v13, 0xffff0000, v6
	v_pk_mul_f32 v[38:39], v[18:19], v[12:13] op_sel_hi:[0,1]
	v_pk_mul_f32 v[12:13], v[20:21], v[12:13] op_sel_hi:[0,1]
	v_cvt_pk_bf16_f32 v58, v12, v13
	v_lshlrev_b32_e32 v12, 16, v7
	v_and_b32_e32 v13, 0xffff0000, v7
	v_cvt_pk_bf16_f32 v54, v38, v39
	v_pk_mul_f32 v[38:39], v[18:19], v[12:13] op_sel_hi:[0,1]
	v_pk_mul_f32 v[12:13], v[20:21], v[12:13] op_sel_hi:[0,1]
	v_cvt_pk_bf16_f32 v59, v12, v13
	v_lshlrev_b32_e32 v12, 16, v8
	v_and_b32_e32 v13, 0xffff0000, v8
	v_cvt_pk_bf16_f32 v55, v38, v39
	v_pk_mul_f32 v[38:39], v[18:19], v[12:13] op_sel_hi:[0,1]
	v_pk_mul_f32 v[12:13], v[20:21], v[12:13] op_sel_hi:[0,1]
	v_cvt_pk_bf16_f32 v60, v12, v13
	v_lshlrev_b32_e32 v12, 16, v9
	v_and_b32_e32 v13, 0xffff0000, v9
	v_cvt_pk_bf16_f32 v56, v38, v39
	v_pk_mul_f32 v[38:39], v[18:19], v[12:13] op_sel_hi:[0,1]
	v_pk_mul_f32 v[12:13], v[20:21], v[12:13] op_sel_hi:[0,1]
	v_cvt_pk_bf16_f32 v61, v12, v13
	global_load_dwordx4 v[10:13], v[10:11], off offset:2112
	v_cvt_pk_bf16_f32 v57, v38, v39
	s_waitcnt vmcnt(0)
	v_lshlrev_b32_e32 v38, 16, v10
	v_and_b32_e32 v39, 0xffff0000, v10
	v_pk_mul_f32 v[40:41], v[18:19], v[38:39] op_sel_hi:[0,1]
	v_pk_mul_f32 v[38:39], v[20:21], v[38:39] op_sel_hi:[0,1]
	v_cvt_pk_bf16_f32 v50, v38, v39
	v_lshlrev_b32_e32 v38, 16, v11
	v_and_b32_e32 v39, 0xffff0000, v11
	v_cvt_pk_bf16_f32 v42, v40, v41
	v_pk_mul_f32 v[40:41], v[18:19], v[38:39] op_sel_hi:[0,1]
	v_pk_mul_f32 v[38:39], v[20:21], v[38:39] op_sel_hi:[0,1]
	v_cvt_pk_bf16_f32 v51, v38, v39
	v_lshlrev_b32_e32 v38, 16, v12
	v_and_b32_e32 v39, 0xffff0000, v12
	v_cvt_pk_bf16_f32 v43, v40, v41
	v_pk_mul_f32 v[40:41], v[18:19], v[38:39] op_sel_hi:[0,1]
	v_pk_mul_f32 v[38:39], v[20:21], v[38:39] op_sel_hi:[0,1]
	v_cvt_pk_bf16_f32 v52, v38, v39
	v_lshlrev_b32_e32 v38, 16, v13
	v_and_b32_e32 v39, 0xffff0000, v13
	v_pk_mul_f32 v[18:19], v[18:19], v[38:39] op_sel_hi:[0,1]
	v_cvt_pk_bf16_f32 v44, v40, v41
	v_cvt_pk_bf16_f32 v45, v18, v19
	v_pk_mul_f32 v[18:19], v[20:21], v[38:39] op_sel_hi:[0,1]
	v_lshl_add_u64 v[40:41], v[90:91], 0, v[110:111]
	v_cvt_pk_bf16_f32 v53, v18, v19
	v_lshl_add_u64 v[38:39], v[92:93], 0, v[110:111]
	global_load_dwordx4 v[18:21], v[40:41], off
	global_load_dwordx4 v[46:49], v[38:39], off
	global_load_dwordx4 v[66:69], v[40:41], off offset:64
	global_load_dwordx4 v[70:73], v[38:39], off offset:64
	s_waitcnt vmcnt(3)
	v_mfma_f32_16x16x32_bf16 v[62:65], v[18:21], v[22:25], 0
	v_mfma_f32_16x16x32_bf16 v[18:21], v[18:21], v[54:57], 0
	s_waitcnt vmcnt(2)
	v_mfma_f32_16x16x32_bf16 v[62:65], v[46:49], v[26:29], v[62:65]
	v_mfma_f32_16x16x32_bf16 v[46:49], v[46:49], v[58:61], v[18:21]
	s_waitcnt vmcnt(1)
	v_mfma_f32_16x16x32_bf16 v[18:21], v[66:69], v[30:33], v[62:65]
	v_mfma_f32_16x16x32_bf16 v[46:49], v[66:69], v[42:45], v[46:49]
	s_nop 3
	global_load_dwordx4 v[62:65], v[40:41], off offset:2048
	global_load_dwordx4 v[66:69], v[38:39], off offset:2048
	s_waitcnt vmcnt(2)
	v_mfma_f32_16x16x32_bf16 v[18:21], v[70:73], v[34:37], v[18:21]
	v_mfma_f32_16x16x32_bf16 v[46:49], v[70:73], v[50:53], v[46:49]
	s_waitcnt vmcnt(1)
	v_mfma_f32_16x16x32_bf16 v[70:73], v[62:65], v[22:25], 0
	v_mfma_f32_16x16x32_bf16 v[62:65], v[62:65], v[54:57], 0
	s_waitcnt vmcnt(0)
	v_mfma_f32_16x16x32_bf16 v[70:73], v[66:69], v[26:29], v[70:73]
	v_mfma_f32_16x16x32_bf16 v[62:65], v[66:69], v[58:61], v[62:65]
	global_load_dwordx4 v[66:69], v[40:41], off offset:2112
	global_load_dwordx4 v[74:77], v[38:39], off offset:2112
	s_waitcnt vmcnt(1)
	v_mfma_f32_16x16x32_bf16 v[62:65], v[66:69], v[42:45], v[62:65]
	v_mfma_f32_16x16x32_bf16 v[38:41], v[66:69], v[30:33], v[70:73]
	s_waitcnt vmcnt(0)
	v_mfma_f32_16x16x32_bf16 v[66:69], v[74:77], v[50:53], v[62:65]
	s_nop 4
	v_or_b32_e32 v62, 0x1000, v110
	v_mov_b32_e32 v63, v1
	v_lshl_add_u64 v[78:79], v[90:91], 0, v[62:63]
	v_lshl_add_u64 v[82:83], v[92:93], 0, v[62:63]
	global_load_dwordx4 v[62:65], v[78:79], off
	global_load_dwordx4 v[70:73], v[82:83], off
	s_nop 0
	global_load_dwordx4 v[78:81], v[78:79], off offset:64
	s_nop 0
	global_load_dwordx4 v[82:85], v[82:83], off offset:64
	v_mfma_f32_16x16x32_bf16 v[38:41], v[74:77], v[34:37], v[38:41]
	s_waitcnt vmcnt(3)
	v_mfma_f32_16x16x32_bf16 v[74:77], v[62:65], v[22:25], 0
	v_mfma_f32_16x16x32_bf16 v[62:65], v[62:65], v[54:57], 0
	s_waitcnt vmcnt(2)
	v_mfma_f32_16x16x32_bf16 v[74:77], v[70:73], v[26:29], v[74:77]
	v_mfma_f32_16x16x32_bf16 v[70:73], v[70:73], v[58:61], v[62:65]
	s_waitcnt vmcnt(1)
	v_mfma_f32_16x16x32_bf16 v[62:65], v[78:81], v[30:33], v[74:77]
	s_nop 4
	v_or_b32_e32 v74, 0x1800, v110
	v_mov_b32_e32 v75, v1
	v_lshl_add_u64 v[86:87], v[90:91], 0, v[74:75]
	v_mfma_f32_16x16x32_bf16 v[70:73], v[78:81], v[42:45], v[70:73]
	v_lshl_add_u64 v[94:95], v[92:93], 0, v[74:75]
	global_load_dwordx4 v[74:77], v[86:87], off
	global_load_dwordx4 v[78:81], v[94:95], off
	s_nop 0
	global_load_dwordx4 v[86:89], v[86:87], off offset:64
	s_nop 0
	global_load_dwordx4 v[94:97], v[94:95], off offset:64
	s_waitcnt vmcnt(4)
	v_mfma_f32_16x16x32_bf16 v[62:65], v[82:85], v[34:37], v[62:65]
	v_mfma_f32_16x16x32_bf16 v[70:73], v[82:85], v[50:53], v[70:73]
	s_waitcnt vmcnt(3)
	v_mfma_f32_16x16x32_bf16 v[82:85], v[74:77], v[22:25], 0
	v_mfma_f32_16x16x32_bf16 v[74:77], v[74:77], v[54:57], 0
	s_waitcnt vmcnt(2)
	v_mfma_f32_16x16x32_bf16 v[82:85], v[78:81], v[26:29], v[82:85]
	v_mfma_f32_16x16x32_bf16 v[78:81], v[78:81], v[58:61], v[74:77]
	s_waitcnt vmcnt(1)
	v_mfma_f32_16x16x32_bf16 v[74:77], v[86:89], v[30:33], v[82:85]
	v_mfma_f32_16x16x32_bf16 v[78:81], v[86:89], v[42:45], v[78:81]
	s_waitcnt vmcnt(0)
; __device__ __forceinline__ float fexp2(float x) { return __builtin_amdgcn_exp2f(x); }
; __device__ __forceinline__ void ret_out_item(const Params& p, int j, int b, int cc, int h, const u16* __restrict__ Z,
;                                              const u16* __restrict__ RVT, const float* __restrict__ U, u16* sVT) {
;     ...
;   {
;     const u16* Sf = (const u16*)U + ((((size_t)0 * 32 + b) * 18 + cc) * 4 + h) * 8192;
;     const u16* Sb = (const u16*)U + ((((size_t)1 * 32 + b) * 18 + cc) * 4 + h) * 8192;
; #pragma unroll
;     for (int eb = 0; eb < 8; ++eb)
; #pragma unroll
;       for (int ks = 0; ks < 2; ++ks) {
;         bf16x8 sf = *(const bf16x8*)(Sf + (eb * 16 + fr) * 64 + ks * 32 + fq * 8);
;         bf16x8 sb = *(const bf16x8*)(Sb + (eb * 16 + fr) * 64 + ks * 32 + fq * 8);
; #pragma unroll
;         for (int qb = 0; qb < 2; ++qb) {
;           o[qb][eb] = mfma16(sf, qff[qb][ks], o[qb][eb]);
;           o[qb][eb] = mfma16(sb, qfb[qb][ks], o[qb][eb]);
;         }
;       }
;     ...
;   for (int kk = 0; kk < 4; ++kk) {
;     f32x4 s[2][2];
; #pragma unroll
;     for (int kb2 = 0; kb2 < 2; ++kb2) {
;       const int kb = kk * 2 + kb2;
;       bf16x8 kf[2];
; #pragma unroll
;       for (int ks = 0; ks < 2; ++ks) kf[ks] = *(const bf16x8*)(Z + (size_t)(r0 + kb * 16 + fr) * 2304 + h * 64 + ks * 32 + fq * 8);
; #pragma unroll
;       for (int qb = 0; qb < 2; ++qb) {
;         f32x4 a = (f32x4){0.f, 0.f, 0.f, 0.f};
;         a = mfma16(kf[0], qf[qb][0], a);
;         a = mfma16(kf[1], qf[qb][1], a);
;         const int qpos = wave * 32 + qb * 16 + fr;
; #pragma unroll
;         for (int r = 0; r < 4; ++r) {
;           int d = qpos - (kb * 16 + fq * 4 + r);
;           float w = 0.f;
;           if (d >= 0) w += fexp2((float)d * lgf2);
;           if (d <= 0) w += fexp2((float)(-d) * lgb2);
;           a[r] *= w;
;         }
;         s[qb][kb2] = a;
;       }
;     }
	v_mfma_f32_16x16x32_bf16 v[74:77], v[94:97], v[34:37], v[74:77]
	v_mfma_f32_16x16x32_bf16 v[94:97], v[94:97], v[50:53], v[78:81]
	s_nop 4
	v_or_b32_e32 v78, 0x2000, v110
	v_mov_b32_e32 v79, v1
	v_lshl_add_u64 v[98:99], v[90:91], 0, v[78:79]
	v_lshl_add_u64 v[102:103], v[92:93], 0, v[78:79]
	global_load_dwordx4 v[78:81], v[98:99], off
	global_load_dwordx4 v[82:85], v[102:103], off
	s_nop 0
	global_load_dwordx4 v[98:101], v[98:99], off offset:64
	s_nop 0
	global_load_dwordx4 v[102:105], v[102:103], off offset:64
	s_waitcnt vmcnt(3)
	v_mfma_f32_16x16x32_bf16 v[86:89], v[78:81], v[22:25], 0
	v_mfma_f32_16x16x32_bf16 v[78:81], v[78:81], v[54:57], 0
	s_waitcnt vmcnt(2)
	v_mfma_f32_16x16x32_bf16 v[86:89], v[82:85], v[26:29], v[86:89]
	v_mfma_f32_16x16x32_bf16 v[82:85], v[82:85], v[58:61], v[78:81]
	s_waitcnt vmcnt(1)
	v_mfma_f32_16x16x32_bf16 v[82:85], v[98:101], v[42:45], v[82:85]
	v_mfma_f32_16x16x32_bf16 v[78:81], v[98:101], v[30:33], v[86:89]
	s_waitcnt vmcnt(0)
	v_mfma_f32_16x16x32_bf16 v[98:101], v[102:105], v[50:53], v[82:85]
	s_nop 4
	v_or_b32_e32 v82, 0x2800, v110
	v_mov_b32_e32 v83, v1
	v_lshl_add_u64 v[106:107], v[90:91], 0, v[82:83]
	v_lshl_add_u64 v[114:115], v[92:93], 0, v[82:83]
	global_load_dwordx4 v[82:85], v[106:107], off
	global_load_dwordx4 v[86:89], v[114:115], off
	s_nop 0
	global_load_dwordx4 v[106:109], v[106:107], off offset:64
	s_nop 0
	global_load_dwordx4 v[114:117], v[114:115], off offset:64
	v_mfma_f32_16x16x32_bf16 v[78:81], v[102:105], v[34:37], v[78:81]
	s_waitcnt vmcnt(3)
	v_mfma_f32_16x16x32_bf16 v[102:105], v[82:85], v[22:25], 0
	v_mfma_f32_16x16x32_bf16 v[82:85], v[82:85], v[54:57], 0
	s_waitcnt vmcnt(2)
	v_mfma_f32_16x16x32_bf16 v[102:105], v[86:89], v[26:29], v[102:105]
	v_mfma_f32_16x16x32_bf16 v[86:89], v[86:89], v[58:61], v[82:85]
	s_waitcnt vmcnt(1)
	v_mfma_f32_16x16x32_bf16 v[86:89], v[106:109], v[42:45], v[86:89]
	v_mfma_f32_16x16x32_bf16 v[82:85], v[106:109], v[30:33], v[102:105]
	s_waitcnt vmcnt(0)
	v_mfma_f32_16x16x32_bf16 v[102:105], v[114:117], v[50:53], v[86:89]
	s_nop 4
	v_or_b32_e32 v86, 0x3000, v110
	v_mov_b32_e32 v87, v1
	v_lshl_add_u64 v[120:121], v[90:91], 0, v[86:87]
	v_lshl_add_u64 v[124:125], v[92:93], 0, v[86:87]
	global_load_dwordx4 v[86:89], v[120:121], off
	global_load_dwordx4 v[106:109], v[124:125], off
	s_nop 0
	global_load_dwordx4 v[120:123], v[120:121], off offset:64
	s_nop 0
	global_load_dwordx4 v[124:127], v[124:125], off offset:64
	v_mfma_f32_16x16x32_bf16 v[82:85], v[114:117], v[34:37], v[82:85]
	v_or_b32_e32 v110, 0x3800, v110
	s_waitcnt vmcnt(3)
	v_mfma_f32_16x16x32_bf16 v[114:117], v[86:89], v[22:25], 0
	v_mfma_f32_16x16x32_bf16 v[86:89], v[86:89], v[54:57], 0
	s_waitcnt vmcnt(2)
	v_mfma_f32_16x16x32_bf16 v[114:117], v[106:109], v[26:29], v[114:117]
	v_mfma_f32_16x16x32_bf16 v[106:109], v[106:109], v[58:61], v[86:89]
	s_waitcnt vmcnt(1)
	v_mfma_f32_16x16x32_bf16 v[86:89], v[120:123], v[30:33], v[114:117]
	v_mfma_f32_16x16x32_bf16 v[106:109], v[120:123], v[42:45], v[106:109]
	v_lshl_add_u64 v[120:121], v[90:91], 0, v[110:111]
	v_lshl_add_u64 v[110:111], v[92:93], 0, v[110:111]
	global_load_dwordx4 v[90:93], v[120:121], off
	s_nop 0
	global_load_dwordx4 v[114:117], v[110:111], off
	s_waitcnt vmcnt(1)
	v_mfma_f32_16x16x32_bf16 v[22:25], v[90:93], v[22:25], 0
	s_waitcnt vmcnt(0)
	v_mfma_f32_16x16x32_bf16 v[22:25], v[114:117], v[26:29], v[22:25]
	v_mfma_f32_16x16x32_bf16 v[26:29], v[90:93], v[54:57], 0
	v_mfma_f32_16x16x32_bf16 v[26:29], v[114:117], v[58:61], v[26:29]
	global_load_dwordx4 v[54:57], v[120:121], off offset:64
	global_load_dwordx4 v[58:61], v[110:111], off offset:64
	s_waitcnt vmcnt(1)
	v_mfma_f32_16x16x32_bf16 v[22:25], v[54:57], v[30:33], v[22:25]
	s_waitcnt vmcnt(0)
	v_mfma_f32_16x16x32_bf16 v[90:93], v[58:61], v[34:37], v[22:25]
	v_mfma_f32_16x16x32_bf16 v[22:25], v[54:57], v[42:45], v[26:29]
	v_mfma_f32_16x16x32_bf16 v[106:109], v[124:127], v[50:53], v[106:109]
	v_mfma_f32_16x16x32_bf16 v[50:53], v[58:61], v[50:53], v[22:25]
	s_nop 5
	v_mad_i64_i32 v[22:23], s[0:1], v171, s26, v[144:145]
	global_load_dwordx4 v[26:29], v[22:23], off
	global_load_dwordx4 v[30:33], v[22:23], off offset:64
	v_lshlrev_b32_e32 v24, 2, v112
	v_sub_u32_e32 v137, v113, v24
	s_waitcnt vmcnt(1)
	v_mfma_f32_16x16x32_bf16 v[22:25], v[26:29], v[2:5], 0
	v_add_u32_e32 v114, -16, v137
	v_add_u32_e32 v42, -2, v137
	v_add_u32_e32 v43, -3, v137
	v_mfma_f32_16x16x32_bf16 v[26:29], v[26:29], v[6:9], 0
	v_cvt_f32_u32_e32 v42, v42
	v_cvt_f32_u32_e32 v43, v43
	v_cmp_lt_i32_e32 vcc, -1, v137
	s_waitcnt vmcnt(0)
	v_mfma_f32_16x16x32_bf16 v[22:25], v[30:33], v[14:17], v[22:25]
	v_cmp_lt_i32_e64 s[8:9], 0, v137
	v_mul_f32_e32 v42, v163, v42
	v_mul_f32_e32 v43, v163, v43
	v_mfma_f32_16x16x32_bf16 v[26:29], v[30:33], v[10:13], v[26:29]
	v_add_u32_e32 v30, 16, v137
	v_add_u32_e32 v31, 15, v137
	v_cvt_f32_u32_e32 v30, v30
	v_cvt_f32_u32_e32 v31, v31
	v_mfma_f32_16x16x32_bf16 v[86:89], v[124:127], v[34:37], v[86:89]
	v_add_u32_e32 v35, -1, v137
	v_mul_f32_e32 v30, v163, v30
	v_mul_f32_e32 v31, v163, v31
	v_exp_f32_e32 v30, v30
	v_exp_f32_e32 v31, v31
	v_cvt_f32_u32_e32 v34, v137
	v_cvt_f32_u32_e32 v35, v35
	v_exp_f32_e32 v44, v42
	v_pk_add_f32 v[30:31], v[30:31], 0 op_sel_hi:[1,0]
	v_mul_f32_e32 v34, v163, v34
	v_pk_mul_f32 v[54:55], v[30:31], v[26:27]
	v_add_u32_e32 v26, 14, v137
	v_add_u32_e32 v27, 13, v137
	v_cvt_f32_u32_e32 v26, v26
	v_cvt_f32_u32_e32 v27, v27
	v_mul_f32_e32 v35, v163, v35
	v_exp_f32_e32 v36, v34
	v_mul_f32_e32 v26, v163, v26
	v_mul_f32_e32 v27, v163, v27
	v_exp_f32_e32 v26, v26
	v_exp_f32_e32 v27, v27
	v_sub_u32_e32 v34, 0, v137
	v_exp_f32_e32 v37, v35
	v_sub_u32_e32 v35, 1, v137
	v_pk_add_f32 v[26:27], v[26:27], 0 op_sel_hi:[1,0]
	v_cvt_f32_u32_e32 v34, v34
	v_pk_mul_f32 v[56:57], v[26:27], v[28:29]
	v_add_u32_e32 v26, 16, v171
	v_mad_i64_i32 v[30:31], s[0:1], v26, s26, v[144:145]
	global_load_dwordx4 v[26:29], v[30:31], off
	s_nop 0
	global_load_dwordx4 v[30:33], v[30:31], off offset:64
	s_waitcnt vmcnt(1)
; __device__ __forceinline__ float fexp2(float x) { return __builtin_amdgcn_exp2f(x); }
; __device__ __forceinline__ void ret_out_item(const Params& p, int j, int b, int cc, int h, const u16* __restrict__ Z,
;                                              const u16* __restrict__ RVT, const float* __restrict__ U, u16* sVT) {
;     ...
;   for (int kk = 0; kk < 4; ++kk) {
;     f32x4 s[2][2];
; #pragma unroll
;     for (int kb2 = 0; kb2 < 2; ++kb2) {
;       const int kb = kk * 2 + kb2;
;       bf16x8 kf[2];
; #pragma unroll
;       for (int ks = 0; ks < 2; ++ks) kf[ks] = *(const bf16x8*)(Z + (size_t)(r0 + kb * 16 + fr) * 2304 + h * 64 + ks * 32 + fq * 8);
; #pragma unroll
;       for (int qb = 0; qb < 2; ++qb) {
;         f32x4 a = (f32x4){0.f, 0.f, 0.f, 0.f};
;         a = mfma16(kf[0], qf[qb][0], a);
;         a = mfma16(kf[1], qf[qb][1], a);
;         const int qpos = wave * 32 + qb * 16 + fr;
; #pragma unroll
;         for (int r = 0; r < 4; ++r) {
;           int d = qpos - (kb * 16 + fq * 4 + r);
;           float w = 0.f;
;           if (d >= 0) w += fexp2((float)d * lgf2);
;           if (d <= 0) w += fexp2((float)(-d) * lgb2);
;           a[r] *= w;
;         }
;         s[qb][kb2] = a;
;       }
;     }
;     bf16x8 pf[2];
; #pragma unroll
;     for (int qb = 0; qb < 2; ++qb)
;       pf[qb] = mk8(pack2(s[qb][0][0], s[qb][0][1]), pack2(s[qb][0][2], s[qb][0][3]),
;                    pack2(s[qb][1][0], s[qb][1][1]), pack2(s[qb][1][2], s[qb][1][3]));
; #pragma unroll
;     for (int eb = 0; eb < 8; ++eb) {
;       uint2 v0 = *(const uint2*)(sVT + (eb * 16 + fr) * 136 + kk * 32 + fq * 4);
;       uint2 v1 = *(const uint2*)(sVT + (eb * 16 + fr) * 136 + kk * 32 + 16 + fq * 4);
;       bf16x8 vf = mk8(v0.x, v0.y, v1.x, v1.y);
; #pragma unroll
;       for (int qb = 0; qb < 2; ++qb) o[qb][eb] = mfma16(vf, pf[qb], o[qb][eb]);
;     }
	v_mfma_f32_16x16x32_bf16 v[58:61], v[26:29], v[2:5], 0
	v_cvt_f32_u32_e32 v35, v35
	v_mul_f32_e32 v34, v162, v34
	v_exp_f32_e32 v34, v34
	s_waitcnt vmcnt(0)
	v_mfma_f32_16x16x32_bf16 v[110:113], v[30:33], v[14:17], v[58:61]
	v_mul_f32_e32 v35, v162, v35
	v_exp_f32_e32 v35, v35
	v_sub_u32_e32 v42, 2, v137
	v_cvt_f32_u32_e32 v58, v114
	v_mfma_f32_16x16x32_bf16 v[26:29], v[26:29], v[6:9], 0
	v_exp_f32_e32 v45, v43
	v_sub_u32_e32 v43, 3, v137
	v_mul_f32_e32 v58, v163, v58
	v_exp_f32_e32 v116, v58
	v_sub_u32_e32 v58, 16, v137
	v_cvt_f32_u32_e32 v58, v58
	v_mfma_f32_16x16x32_bf16 v[26:29], v[30:33], v[10:13], v[26:29]
	v_add_f32_e64 v30, v36, 0
	v_add_f32_e64 v31, v37, 0
	v_cvt_f32_u32_e32 v42, v42
	v_mul_f32_e32 v58, v162, v58
	v_exp_f32_e32 v154, v58
	v_subrev_u32_e32 v58, 17, v137
	v_cvt_f32_u32_e32 v58, v58
	v_cndmask_b32_e64 v33, 0, v31, s[8:9]
	v_cndmask_b32_e32 v32, 0, v30, vcc
	v_cmp_gt_i32_e32 vcc, 1, v137
	v_mul_f32_e32 v58, v163, v58
	v_exp_f32_e32 v117, v58
	v_sub_u32_e32 v58, 17, v137
	v_cvt_f32_u32_e32 v58, v58
	v_cmp_gt_i32_e64 s[8:9], 2, v137
	v_pk_add_f32 v[32:33], v[32:33], v[34:35]
	v_cvt_f32_u32_e32 v43, v43
	v_mul_f32_e32 v58, v162, v58
	v_exp_f32_e32 v155, v58
	v_subrev_u32_e32 v58, 18, v137
	v_cvt_f32_u32_e32 v58, v58
	v_cndmask_b32_e64 v31, v31, v33, s[8:9]
	v_cndmask_b32_e32 v30, v30, v32, vcc
	v_pk_mul_f32 v[22:23], v[30:31], v[22:23]
	v_mul_f32_e32 v58, v163, v58
	v_exp_f32_e32 v158, v58
	v_sub_u32_e32 v58, 18, v137
	v_cvt_f32_u32_e32 v58, v58
	v_cvt_pk_bf16_f32 v114, v22, v23
	v_mul_u32_u24_e32 v22, 0x88, v118
	v_lshlrev_b32_e32 v22, 1, v22
	v_mul_f32_e32 v58, v162, v58
	v_exp_f32_e32 v156, v58
	v_subrev_u32_e32 v58, 19, v137
	v_cvt_f32_u32_e32 v58, v58
	v_add3_u32 v172, s58, v22, v0
	v_add_u32_e32 v168, 0x3000, v172
	v_mul_f32_e32 v42, v162, v42
	v_mul_f32_e32 v43, v162, v43
	ds_read2_b64 v[130:133], v168 offset0:96 offset1:100
	v_exp_f32_e32 v42, v42
	v_exp_f32_e32 v43, v43
	v_mul_f32_e32 v58, v163, v58
	v_exp_f32_e32 v159, v58
	v_sub_u32_e32 v58, 19, v137
	v_cvt_f32_u32_e32 v58, v58
	v_pk_mul_f32 v[26:27], v[30:31], v[26:27]
	v_cmp_lt_i32_e32 vcc, 1, v137
	v_cmp_lt_i32_e64 s[8:9], 2, v137
	v_pk_add_f32 v[30:31], v[44:45], 0 op_sel_hi:[1,0]
	v_mul_f32_e32 v58, v162, v58
	v_cndmask_b32_e64 v33, 0, v31, s[8:9]
	v_cndmask_b32_e32 v32, 0, v30, vcc
	v_cmp_gt_i32_e32 vcc, 3, v137
	v_cmp_gt_i32_e64 s[8:9], 4, v137
	v_pk_add_f32 v[32:33], v[32:33], v[42:43]
	v_exp_f32_e32 v157, v58
	v_cndmask_b32_e64 v31, v31, v33, s[8:9]
	v_cndmask_b32_e32 v30, v30, v32, vcc
	v_pk_mul_f32 v[28:29], v[30:31], v[28:29]
	v_cvt_pk_bf16_f32 v58, v54, v55
	v_cvt_pk_bf16_f32 v59, v56, v57
	v_cvt_pk_bf16_f32 v60, v26, v27
	v_cvt_pk_bf16_f32 v61, v28, v29
	v_add_u32_e32 v167, 0x4000, v172
	v_add_u32_e32 v166, 0x5000, v172
	s_waitcnt lgkmcnt(0)
	v_mfma_f32_16x16x32_bf16 v[34:37], v[130:133], v[58:61], v[94:97]
	ds_read2_b64 v[118:121], v172 offset1:4
	v_pk_mul_f32 v[24:25], v[30:31], v[24:25]
	v_add_u32_e32 v165, 0x6000, v172
	ds_read2_b64 v[94:97], v167 offset0:128 offset1:132
	s_waitcnt lgkmcnt(0)
	v_mfma_f32_16x16x32_bf16 v[42:45], v[94:97], v[58:61], v[98:101]
	s_nop 2
	ds_read2_b64 v[98:101], v166 offset0:160 offset1:164
	v_cvt_pk_bf16_f32 v115, v24, v25
	v_add_u32_e32 v170, 0x1000, v172
	v_mfma_f32_16x16x32_bf16 v[22:25], v[118:121], v[58:61], v[46:49]
	v_add_u32_e32 v169, 0x2000, v172
	v_add_u32_e32 v164, 0x7000, v172
	ds_read2_b64 v[122:125], v170 offset0:32 offset1:36
	s_waitcnt lgkmcnt(1)
	v_mfma_f32_16x16x32_bf16 v[46:49], v[98:101], v[58:61], v[102:105]
	ds_read2_b64 v[126:129], v169 offset0:64 offset1:68
	s_nop 1
	ds_read2_b64 v[102:105], v165 offset0:192 offset1:196
	v_subrev_u32_e32 v134, 32, v137
	s_waitcnt lgkmcnt(0)
	v_mfma_f32_16x16x32_bf16 v[54:57], v[102:105], v[58:61], v[106:109]
	s_nop 2
	ds_read2_b64 v[106:109], v164 offset0:224 offset1:228
	v_cvt_f32_u32_e32 v134, v134
	v_cmp_lt_i32_e32 vcc, 15, v137
	v_mfma_f32_16x16x32_bf16 v[26:29], v[122:125], v[58:61], v[66:69]
	v_cmp_lt_i32_e64 s[8:9], 16, v137
	v_mul_f32_e32 v134, v163, v134
	v_exp_f32_e32 v148, v134
	v_mfma_f32_16x16x32_bf16 v[30:33], v[126:129], v[58:61], v[70:73]
	v_sub_u32_e32 v134, 32, v137
	v_cvt_f32_u32_e32 v134, v134
	v_cmp_gt_i32_e64 s[12:13], s6, v137
	s_waitcnt lgkmcnt(0)
	v_mfma_f32_16x16x32_bf16 v[58:61], v[106:109], v[58:61], v[50:53]
	v_mul_f32_e32 v134, v162, v134
	v_exp_f32_e32 v146, v134
	s_nop 0
	v_add_u32_e32 v50, 32, v171
	v_mad_i64_i32 v[50:51], s[0:1], v50, s26, v[144:145]
	global_load_dwordx4 v[66:69], v[50:51], off
	global_load_dwordx4 v[70:73], v[50:51], off offset:64
	v_subrev_u32_e32 v134, 33, v137
	v_cvt_f32_u32_e32 v134, v134
	s_waitcnt vmcnt(1)
	v_mfma_f32_16x16x32_bf16 v[50:53], v[66:69], v[2:5], 0
	v_mul_f32_e32 v134, v163, v134
	v_exp_f32_e32 v149, v134
	v_sub_u32_e32 v134, 33, v137
	v_cvt_f32_u32_e32 v134, v134
	v_mfma_f32_16x16x32_bf16 v[66:69], v[66:69], v[6:9], 0
	v_mul_f32_e32 v134, v162, v134
	v_exp_f32_e32 v147, v134
	v_subrev_u32_e32 v134, 34, v137
	v_cvt_f32_u32_e32 v134, v134
	s_waitcnt vmcnt(0)
; __device__ __forceinline__ float fexp2(float x) { return __builtin_amdgcn_exp2f(x); }
; __device__ __forceinline__ void ret_out_item(const Params& p, int j, int b, int cc, int h, const u16* __restrict__ Z,
;                                              const u16* __restrict__ RVT, const float* __restrict__ U, u16* sVT) {
;     ...
;   for (int kk = 0; kk < 4; ++kk) {
;     f32x4 s[2][2];
; #pragma unroll
;     for (int kb2 = 0; kb2 < 2; ++kb2) {
;       const int kb = kk * 2 + kb2;
;       bf16x8 kf[2];
; #pragma unroll
;       for (int ks = 0; ks < 2; ++ks) kf[ks] = *(const bf16x8*)(Z + (size_t)(r0 + kb * 16 + fr) * 2304 + h * 64 + ks * 32 + fq * 8);
; #pragma unroll
;       for (int qb = 0; qb < 2; ++qb) {
;         f32x4 a = (f32x4){0.f, 0.f, 0.f, 0.f};
;         a = mfma16(kf[0], qf[qb][0], a);
;         a = mfma16(kf[1], qf[qb][1], a);
;         const int qpos = wave * 32 + qb * 16 + fr;
; #pragma unroll
;         for (int r = 0; r < 4; ++r) {
;           int d = qpos - (kb * 16 + fq * 4 + r);
;           float w = 0.f;
;           if (d >= 0) w += fexp2((float)d * lgf2);
;           if (d <= 0) w += fexp2((float)(-d) * lgb2);
;           a[r] *= w;
;         }
;         s[qb][kb2] = a;
;       }
;     }
;     bf16x8 pf[2];
; #pragma unroll
;     for (int qb = 0; qb < 2; ++qb)
;       pf[qb] = mk8(pack2(s[qb][0][0], s[qb][0][1]), pack2(s[qb][0][2], s[qb][0][3]),
;                    pack2(s[qb][1][0], s[qb][1][1]), pack2(s[qb][1][2], s[qb][1][3]));
; #pragma unroll
;     for (int eb = 0; eb < 8; ++eb) {
;       uint2 v0 = *(const uint2*)(sVT + (eb * 16 + fr) * 136 + kk * 32 + fq * 4);
;       uint2 v1 = *(const uint2*)(sVT + (eb * 16 + fr) * 136 + kk * 32 + 16 + fq * 4);
;       bf16x8 vf = mk8(v0.x, v0.y, v1.x, v1.y);
; #pragma unroll
;       for (int qb = 0; qb < 2; ++qb) o[qb][eb] = mfma16(vf, pf[qb], o[qb][eb]);
;     }
	v_mfma_f32_16x16x32_bf16 v[174:177], v[70:73], v[10:13], v[66:69]
	v_mul_f32_e32 v134, v163, v134
	v_exp_f32_e32 v152, v134
	v_sub_u32_e32 v134, 34, v137
	v_cvt_f32_u32_e32 v134, v134
	v_pk_add_f32 v[66:67], v[116:117], 0 op_sel_hi:[1,0]
	v_mfma_f32_16x16x32_bf16 v[50:53], v[70:73], v[14:17], v[50:53]
	v_cndmask_b32_e64 v69, 0, v67, s[8:9]
	v_mul_f32_e32 v134, v162, v134
	v_exp_f32_e32 v150, v134
	v_subrev_u32_e32 v134, 35, v137
	v_cvt_f32_u32_e32 v134, v134
	v_cndmask_b32_e32 v68, 0, v66, vcc
	v_cmp_gt_i32_e32 vcc, 17, v137
	v_cmp_gt_i32_e64 s[8:9], 18, v137
	v_mul_f32_e32 v134, v163, v134
	v_exp_f32_e32 v153, v134
	v_sub_u32_e32 v134, 35, v137
	v_cvt_f32_u32_e32 v134, v134
	v_pk_add_f32 v[68:69], v[68:69], v[154:155]
	v_mul_f32_e32 v134, v162, v134
	v_cndmask_b32_e64 v67, v67, v69, s[8:9]
	v_cndmask_b32_e32 v66, v66, v68, vcc
	v_pk_mul_f32 v[68:69], v[66:67], v[110:111]
	v_pk_mul_f32 v[110:111], v[66:67], v[174:175]
	v_cmp_lt_i32_e32 vcc, 17, v137
	v_cmp_lt_i32_e64 s[8:9], 18, v137
	v_pk_add_f32 v[66:67], v[158:159], 0 op_sel_hi:[1,0]
	v_cvt_pk_bf16_f32 v116, v68, v69
	v_cndmask_b32_e64 v69, 0, v67, s[8:9]
	v_cndmask_b32_e32 v68, 0, v66, vcc
	v_cmp_gt_i32_e32 vcc, 19, v137
	v_cmp_gt_i32_e64 s[8:9], 20, v137
	v_pk_add_f32 v[68:69], v[68:69], v[156:157]
	v_exp_f32_e32 v151, v134
	v_cndmask_b32_e64 v135, v67, v69, s[8:9]
	v_cndmask_b32_e32 v134, v66, v68, vcc
	v_pk_mul_f32 v[66:67], v[134:135], v[112:113]
	v_cmp_lt_i32_e32 vcc, 31, v137
	v_cvt_pk_bf16_f32 v117, v66, v67
	v_cmp_lt_i32_e64 s[8:9], 32, v137
	s_nop 0
	v_mfma_f32_16x16x32_bf16 v[66:69], v[118:121], v[114:117], v[18:21]
	s_nop 2
	v_add_u32_e32 v18, 48, v171
	v_mfma_f32_16x16x32_bf16 v[70:73], v[126:129], v[114:117], v[62:65]
	v_cvt_pk_bf16_f32 v126, v110, v111
	s_nop 1
	v_mad_i64_i32 v[62:63], s[0:1], v18, s26, v[144:145]
	v_mfma_f32_16x16x32_bf16 v[78:81], v[94:97], v[114:117], v[78:81]
	global_load_dwordx4 v[18:21], v[62:63], off
	global_load_dwordx4 v[94:97], v[62:63], off offset:64
	ds_read2_b64 v[110:113], v168 offset0:104 offset1:108
	ds_read2_b64 v[118:121], v166 offset0:168 offset1:172
	v_mfma_f32_16x16x32_bf16 v[82:85], v[98:101], v[114:117], v[82:85]
	v_subrev_u32_e32 v100, 48, v137
	v_cvt_f32_u32_e32 v100, v100
	v_pk_mul_f32 v[98:99], v[134:135], v[176:177]
	s_waitcnt vmcnt(1)
	v_mfma_f32_16x16x32_bf16 v[62:65], v[18:21], v[2:5], 0
	v_mul_f32_e32 v100, v163, v100
	v_exp_f32_e32 v156, v100
	v_sub_u32_e32 v100, 48, v137
	v_cvt_f32_u32_e32 v100, v100
	v_mfma_f32_16x16x32_bf16 v[18:21], v[18:21], v[6:9], 0
	v_cvt_pk_bf16_f32 v127, v98, v99
	v_mul_f32_e32 v100, v162, v100
	v_exp_f32_e32 v154, v100
	v_subrev_u32_e32 v100, 49, v137
	v_cvt_f32_u32_e32 v100, v100
	s_waitcnt vmcnt(0)
	v_mfma_f32_16x16x32_bf16 v[62:65], v[94:97], v[14:17], v[62:65]
	v_mul_f32_e32 v100, v163, v100
	v_exp_f32_e32 v157, v100
	v_sub_u32_e32 v100, 49, v137
	v_cvt_f32_u32_e32 v100, v100
	v_mfma_f32_16x16x32_bf16 v[18:21], v[94:97], v[10:13], v[18:21]
	v_add_f32_e64 v94, v148, 0
	v_add_f32_e64 v95, v149, 0
	v_mul_f32_e32 v100, v162, v100
	v_exp_f32_e32 v155, v100
	v_subrev_u32_e32 v100, 50, v137
	v_cvt_f32_u32_e32 v100, v100
	v_mfma_f32_16x16x32_bf16 v[38:41], v[122:125], v[114:117], v[38:41]
	v_cndmask_b32_e64 v97, 0, v95, s[8:9]
	v_cndmask_b32_e32 v96, 0, v94, vcc
	v_mul_f32_e32 v100, v163, v100
	v_exp_f32_e32 v160, v100
	v_sub_u32_e32 v100, 50, v137
	v_cvt_f32_u32_e32 v100, v100
	v_mfma_f32_16x16x32_bf16 v[74:77], v[130:133], v[114:117], v[74:77]
	v_cmp_gt_i32_e32 vcc, 33, v137
	v_cmp_gt_i32_e64 s[8:9], 34, v137
	v_mul_f32_e32 v100, v162, v100
	v_exp_f32_e32 v158, v100
	v_subrev_u32_e32 v100, 51, v137
	v_cvt_f32_u32_e32 v100, v100
	v_mfma_f32_16x16x32_bf16 v[86:89], v[102:105], v[114:117], v[86:89]
	ds_read2_b64 v[102:105], v170 offset0:40 offset1:44
	v_pk_add_f32 v[96:97], v[96:97], v[146:147]
	v_mul_f32_e32 v100, v163, v100
	v_exp_f32_e32 v161, v100
	v_sub_u32_e32 v100, 51, v137
	v_cvt_f32_u32_e32 v100, v100
	v_mfma_f32_16x16x32_bf16 v[90:93], v[106:109], v[114:117], v[90:93]
	ds_read2_b64 v[106:109], v169 offset0:72 offset1:76
	ds_read2_b64 v[114:117], v167 offset0:136 offset1:140
	v_mul_f32_e32 v100, v162, v100
	v_exp_f32_e32 v159, v100
	ds_read2_b64 v[98:101], v172 offset0:8 offset1:12
	v_cndmask_b32_e64 v95, v95, v97, s[8:9]
	v_cndmask_b32_e32 v94, v94, v96, vcc
	v_pk_mul_f32 v[50:51], v[94:95], v[50:51]
	v_pk_mul_f32 v[18:19], v[94:95], v[18:19]
	v_cmp_lt_i32_e32 vcc, 33, v137
	v_cmp_lt_i32_e64 s[8:9], 34, v137
	v_pk_add_f32 v[94:95], v[152:153], 0 op_sel_hi:[1,0]
	v_cvt_pk_bf16_f32 v128, v18, v19
	v_cndmask_b32_e64 v97, 0, v95, s[8:9]
	v_cndmask_b32_e32 v96, 0, v94, vcc
	v_cmp_gt_i32_e32 vcc, 35, v137
	v_cmp_gt_i32_e64 s[8:9], 36, v137
	v_pk_add_f32 v[96:97], v[96:97], v[150:151]
	ds_read2_b64 v[122:125], v164 offset0:232 offset1:236
	v_cndmask_b32_e64 v95, v95, v97, s[8:9]
	v_cndmask_b32_e32 v94, v94, v96, vcc
	v_pk_mul_f32 v[20:21], v[94:95], v[20:21]
	v_pk_mul_f32 v[52:53], v[94:95], v[52:53]
	v_cvt_pk_bf16_f32 v129, v20, v21
	v_cvt_pk_bf16_f32 v94, v50, v51
	v_cvt_pk_bf16_f32 v95, v52, v53
	s_waitcnt lgkmcnt(1)
	v_mfma_f32_16x16x32_bf16 v[18:21], v[98:101], v[126:129], v[22:25]
	v_subrev_u32_e32 v96, 64, v137
	v_cvt_f32_u32_e32 v96, v96
	v_cmp_lt_i32_e32 vcc, 47, v137
	v_mfma_f32_16x16x32_bf16 v[22:25], v[102:105], v[126:129], v[26:29]
	v_cmp_lt_i32_e64 s[8:9], 48, v137
	v_mul_f32_e32 v96, v163, v96
	v_exp_f32_e32 v132, v96
	v_mfma_f32_16x16x32_bf16 v[26:29], v[106:109], v[126:129], v[30:33]
	v_sub_u32_e32 v96, 64, v137
	v_cvt_f32_u32_e32 v96, v96
	v_mul_f32_e32 v96, v162, v96
	v_mfma_f32_16x16x32_bf16 v[30:33], v[110:113], v[126:129], v[34:37]
	v_mfma_f32_16x16x32_bf16 v[34:37], v[114:117], v[126:129], v[42:45]
	s_nop 2
	v_add_u32_e32 v42, 64, v171
	v_mad_i64_i32 v[42:43], s[0:1], v42, s26, v[144:145]
	v_mfma_f32_16x16x32_bf16 v[50:53], v[118:121], v[126:129], v[46:49]
	s_nop 2
	ds_read2_b64 v[46:49], v165 offset0:200 offset1:204
	global_load_dwordx4 v[146:149], v[42:43], off
	global_load_dwordx4 v[150:153], v[42:43], off offset:64
	s_waitcnt lgkmcnt(0)
; __device__ __forceinline__ float fexp2(float x) { return __builtin_amdgcn_exp2f(x); }
; __device__ __forceinline__ void ret_out_item(const Params& p, int j, int b, int cc, int h, const u16* __restrict__ Z,
;                                              const u16* __restrict__ RVT, const float* __restrict__ U, u16* sVT) {
;     ...
;   for (int kk = 0; kk < 4; ++kk) {
;     f32x4 s[2][2];
; #pragma unroll
;     for (int kb2 = 0; kb2 < 2; ++kb2) {
;       const int kb = kk * 2 + kb2;
;       bf16x8 kf[2];
; #pragma unroll
;       for (int ks = 0; ks < 2; ++ks) kf[ks] = *(const bf16x8*)(Z + (size_t)(r0 + kb * 16 + fr) * 2304 + h * 64 + ks * 32 + fq * 8);
; #pragma unroll
;       for (int qb = 0; qb < 2; ++qb) {
;         f32x4 a = (f32x4){0.f, 0.f, 0.f, 0.f};
;         a = mfma16(kf[0], qf[qb][0], a);
;         a = mfma16(kf[1], qf[qb][1], a);
;         const int qpos = wave * 32 + qb * 16 + fr;
; #pragma unroll
;         for (int r = 0; r < 4; ++r) {
;           int d = qpos - (kb * 16 + fq * 4 + r);
;           float w = 0.f;
;           if (d >= 0) w += fexp2((float)d * lgf2);
;           if (d <= 0) w += fexp2((float)(-d) * lgb2);
;           a[r] *= w;
;         }
;         s[qb][kb2] = a;
;       }
;     }
;     bf16x8 pf[2];
; #pragma unroll
;     for (int qb = 0; qb < 2; ++qb)
;       pf[qb] = mk8(pack2(s[qb][0][0], s[qb][0][1]), pack2(s[qb][0][2], s[qb][0][3]),
;                    pack2(s[qb][1][0], s[qb][1][1]), pack2(s[qb][1][2], s[qb][1][3]));
; #pragma unroll
;     for (int eb = 0; eb < 8; ++eb) {
;       uint2 v0 = *(const uint2*)(sVT + (eb * 16 + fr) * 136 + kk * 32 + fq * 4);
;       uint2 v1 = *(const uint2*)(sVT + (eb * 16 + fr) * 136 + kk * 32 + 16 + fq * 4);
;       bf16x8 vf = mk8(v0.x, v0.y, v1.x, v1.y);
; #pragma unroll
;       for (int qb = 0; qb < 2; ++qb) o[qb][eb] = mfma16(vf, pf[qb], o[qb][eb]);
;     }
	v_mfma_f32_16x16x32_bf16 v[54:57], v[46:49], v[126:129], v[54:57]
	v_mfma_f32_16x16x32_bf16 v[58:61], v[122:125], v[126:129], v[58:61]
	v_exp_f32_e32 v128, v96
	v_add_u32_e32 v96, 0xffffffbf, v137
	v_cvt_f32_u32_e32 v96, v96
	s_waitcnt vmcnt(1)
	v_mfma_f32_16x16x32_bf16 v[42:45], v[146:149], v[2:5], 0
	v_mul_f32_e32 v96, v163, v96
	v_exp_f32_e32 v133, v96
	v_sub_u32_e32 v96, 0x41, v137
	v_cvt_f32_u32_e32 v96, v96
	v_mfma_f32_16x16x32_bf16 v[146:149], v[146:149], v[6:9], 0
	v_mul_f32_e32 v96, v162, v96
	v_exp_f32_e32 v129, v96
	v_add_u32_e32 v96, 0xffffffbe, v137
	v_cvt_f32_u32_e32 v96, v96
	s_waitcnt vmcnt(0)
	v_mfma_f32_16x16x32_bf16 v[146:149], v[150:153], v[10:13], v[146:149]
	v_mul_f32_e32 v96, v163, v96
	v_exp_f32_e32 v130, v96
	v_sub_u32_e32 v96, 0x42, v137
	v_cvt_f32_u32_e32 v96, v96
	v_mfma_f32_16x16x32_bf16 v[42:45], v[150:153], v[14:17], v[42:45]
	v_mul_f32_e32 v96, v162, v96
	v_exp_f32_e32 v126, v96
	v_add_u32_e32 v96, 0xffffffbd, v137
	v_cvt_f32_u32_e32 v96, v96
	v_mul_f32_e32 v96, v163, v96
	v_exp_f32_e32 v131, v96
	v_sub_u32_e32 v96, 0x43, v137
	v_cvt_f32_u32_e32 v96, v96
	v_mul_f32_e32 v96, v162, v96
	v_exp_f32_e32 v127, v96
	v_pk_add_f32 v[96:97], v[156:157], 0 op_sel_hi:[1,0]
	s_nop 0
	v_cndmask_b32_e64 v135, 0, v97, s[8:9]
	v_cndmask_b32_e32 v134, 0, v96, vcc
	v_cmp_gt_i32_e32 vcc, 49, v137
	v_cmp_gt_i32_e64 s[8:9], 50, v137
	v_pk_add_f32 v[134:135], v[134:135], v[154:155]
	s_nop 0
	v_cndmask_b32_e64 v135, v97, v135, s[8:9]
	v_cndmask_b32_e32 v134, v96, v134, vcc
	v_pk_mul_f32 v[62:63], v[134:135], v[62:63]
	v_cmp_lt_i32_e32 vcc, 49, v137
	v_cvt_pk_bf16_f32 v96, v62, v63
	v_cmp_lt_i32_e64 s[8:9], 50, v137
	v_pk_add_f32 v[62:63], v[160:161], 0 op_sel_hi:[1,0]
	v_pk_mul_f32 v[146:147], v[134:135], v[146:147]
	v_cndmask_b32_e64 v135, 0, v63, s[8:9]
	v_cndmask_b32_e32 v134, 0, v62, vcc
	v_cmp_gt_i32_e32 vcc, 51, v137
	v_cmp_gt_i32_e64 s[8:9], 52, v137
	v_pk_add_f32 v[134:135], v[134:135], v[158:159]
	s_nop 0
	v_cndmask_b32_e64 v135, v63, v135, s[8:9]
	v_cndmask_b32_e32 v134, v62, v134, vcc
	v_pk_mul_f32 v[62:63], v[134:135], v[64:65]
	v_cmp_lt_i32_e32 vcc, 63, v137
	v_cvt_pk_bf16_f32 v97, v62, v63
	v_cmp_lt_i32_e64 s[8:9], 64, v137
	s_nop 0
	v_mfma_f32_16x16x32_bf16 v[62:65], v[98:101], v[94:97], v[66:69]
	v_add_u32_e32 v100, 0xffffffb0, v137
	v_cvt_f32_u32_e32 v100, v100
	v_pk_mul_f32 v[98:99], v[134:135], v[148:149]
	v_mfma_f32_16x16x32_bf16 v[66:69], v[102:105], v[94:97], v[38:41]
	v_cvt_pk_bf16_f32 v102, v146, v147
	v_mul_f32_e32 v100, v163, v100
	v_exp_f32_e32 v148, v100
	v_add_u32_e32 v38, 0x50, v171
	v_mfma_f32_16x16x32_bf16 v[86:89], v[46:49], v[94:97], v[86:89]
	v_mad_i64_i32 v[46:47], s[0:1], v38, s26, v[144:145]
	global_load_dwordx4 v[38:41], v[46:47], off
	s_nop 0
	global_load_dwordx4 v[46:49], v[46:47], off offset:64
	v_sub_u32_e32 v100, 0x50, v137
	v_cvt_f32_u32_e32 v100, v100
	v_mfma_f32_16x16x32_bf16 v[70:73], v[106:109], v[94:97], v[70:73]
	s_movk_i32 s1, 0x41
	s_movk_i32 s0, 0x42
	v_mul_f32_e32 v100, v162, v100
	v_exp_f32_e32 v108, v100
	v_add_u32_e32 v100, 0xffffffaf, v137
	v_cvt_f32_u32_e32 v100, v100
	v_mfma_f32_16x16x32_bf16 v[74:77], v[110:113], v[94:97], v[74:77]
	v_cvt_pk_bf16_f32 v103, v98, v99
	ds_read2_b64 v[110:113], v170 offset0:48 offset1:52
	v_mul_f32_e32 v100, v163, v100
	v_exp_f32_e32 v149, v100
	v_sub_u32_e32 v100, 0x51, v137
	v_cvt_f32_u32_e32 v100, v100
	v_mfma_f32_16x16x32_bf16 v[78:81], v[114:117], v[94:97], v[78:81]
	ds_read2_b64 v[114:117], v169 offset0:80 offset1:84
	v_add_u32_e32 v134, 0xffffffa0, v137
	v_mul_f32_e32 v100, v162, v100
	v_exp_f32_e32 v109, v100
	v_add_u32_e32 v100, 0xffffffae, v137
	v_cvt_f32_u32_e32 v100, v100
	v_mfma_f32_16x16x32_bf16 v[82:85], v[118:121], v[94:97], v[82:85]
	ds_read2_b64 v[118:121], v168 offset0:112 offset1:116
	v_cvt_f32_u32_e32 v134, v134
	v_mul_f32_e32 v100, v163, v100
	v_mfma_f32_16x16x32_bf16 v[90:93], v[122:125], v[94:97], v[90:93]
	v_exp_f32_e32 v158, v100
	v_sub_u32_e32 v100, 0x52, v137
	v_cvt_f32_u32_e32 v100, v100
	s_waitcnt vmcnt(1)
	v_mfma_f32_16x16x32_bf16 v[94:97], v[38:41], v[2:5], 0
	v_mul_f32_e32 v100, v162, v100
	v_exp_f32_e32 v156, v100
	v_add_u32_e32 v100, 0xffffffad, v137
	v_mfma_f32_16x16x32_bf16 v[38:41], v[38:41], v[6:9], 0
	v_cvt_f32_u32_e32 v100, v100
	ds_read2_b64 v[122:125], v167 offset0:144 offset1:148
	v_mul_f32_e32 v134, v163, v134
	s_waitcnt vmcnt(0)
	v_mfma_f32_16x16x32_bf16 v[94:97], v[46:49], v[14:17], v[94:97]
	v_mul_f32_e32 v100, v163, v100
	v_exp_f32_e32 v159, v100
	v_sub_u32_e32 v100, 0x53, v137
	v_mfma_f32_16x16x32_bf16 v[38:41], v[46:49], v[10:13], v[38:41]
	v_add_f32_e64 v46, v132, 0
	v_add_f32_e64 v47, v133, 0
	v_cvt_f32_u32_e32 v100, v100
	v_cndmask_b32_e64 v49, 0, v47, s[8:9]
	v_cndmask_b32_e32 v48, 0, v46, vcc
	v_cmp_gt_i32_e32 vcc, s1, v137
	v_cmp_gt_i32_e64 s[8:9], s0, v137
	v_pk_add_f32 v[48:49], v[48:49], v[128:129]
	v_mul_f32_e32 v100, v162, v100
	v_cndmask_b32_e64 v47, v47, v49, s[8:9]
	v_cndmask_b32_e32 v46, v46, v48, vcc
	v_pk_mul_f32 v[42:43], v[46:47], v[42:43]
	v_pk_mul_f32 v[38:39], v[46:47], v[38:39]
	v_cmp_lt_i32_e32 vcc, s1, v137
	v_cmp_lt_i32_e64 s[8:9], s0, v137
	v_pk_add_f32 v[46:47], v[130:131], 0 op_sel_hi:[1,0]
	s_movk_i32 s0, 0x43
	v_cndmask_b32_e64 v49, 0, v47, s[8:9]
	v_cndmask_b32_e32 v48, 0, v46, vcc
	v_pk_add_f32 v[48:49], v[48:49], v[126:127]
	ds_read2_b64 v[126:129], v166 offset0:176 offset1:180
	v_cmp_gt_i32_e32 vcc, s0, v137
	s_movk_i32 s0, 0x44
	v_cmp_gt_i32_e64 s[8:9], s0, v137
	v_cndmask_b32_e32 v46, v46, v48, vcc
	v_cvt_pk_bf16_f32 v104, v38, v39
	v_cndmask_b32_e64 v47, v47, v49, s[8:9]
	v_pk_mul_f32 v[40:41], v[46:47], v[40:41]
	v_exp_f32_e32 v157, v100
	v_cvt_pk_bf16_f32 v105, v40, v41
	ds_read2_b64 v[98:101], v172 offset0:16 offset1:20
	ds_read2_b64 v[130:133], v164 offset0:240 offset1:244
	s_waitcnt lgkmcnt(3)
; __device__ __forceinline__ float fexp2(float x) { return __builtin_amdgcn_exp2f(x); }
; __device__ __forceinline__ void ret_out_item(const Params& p, int j, int b, int cc, int h, const u16* __restrict__ Z,
;                                              const u16* __restrict__ RVT, const float* __restrict__ U, u16* sVT) {
;     ...
;   for (int kk = 0; kk < 4; ++kk) {
;     f32x4 s[2][2];
; #pragma unroll
;     for (int kb2 = 0; kb2 < 2; ++kb2) {
;       const int kb = kk * 2 + kb2;
;       bf16x8 kf[2];
; #pragma unroll
;       for (int ks = 0; ks < 2; ++ks) kf[ks] = *(const bf16x8*)(Z + (size_t)(r0 + kb * 16 + fr) * 2304 + h * 64 + ks * 32 + fq * 8);
; #pragma unroll
;       for (int qb = 0; qb < 2; ++qb) {
;         f32x4 a = (f32x4){0.f, 0.f, 0.f, 0.f};
;         a = mfma16(kf[0], qf[qb][0], a);
;         a = mfma16(kf[1], qf[qb][1], a);
;         const int qpos = wave * 32 + qb * 16 + fr;
; #pragma unroll
;         for (int r = 0; r < 4; ++r) {
;           int d = qpos - (kb * 16 + fq * 4 + r);
;           float w = 0.f;
;           if (d >= 0) w += fexp2((float)d * lgf2);
;           if (d <= 0) w += fexp2((float)(-d) * lgb2);
;           a[r] *= w;
;         }
;         s[qb][kb2] = a;
;       }
;     }
;     bf16x8 pf[2];
; #pragma unroll
;     for (int qb = 0; qb < 2; ++qb)
;       pf[qb] = mk8(pack2(s[qb][0][0], s[qb][0][1]), pack2(s[qb][0][2], s[qb][0][3]),
;                    pack2(s[qb][1][0], s[qb][1][1]), pack2(s[qb][1][2], s[qb][1][3]));
; #pragma unroll
;     for (int eb = 0; eb < 8; ++eb) {
;       uint2 v0 = *(const uint2*)(sVT + (eb * 16 + fr) * 136 + kk * 32 + fq * 4);
;       uint2 v1 = *(const uint2*)(sVT + (eb * 16 + fr) * 136 + kk * 32 + 16 + fq * 4);
;       bf16x8 vf = mk8(v0.x, v0.y, v1.x, v1.y);
; #pragma unroll
;       for (int qb = 0; qb < 2; ++qb) o[qb][eb] = mfma16(vf, pf[qb], o[qb][eb]);
;     }
	v_mfma_f32_16x16x32_bf16 v[38:41], v[122:125], v[102:105], v[34:37]
	v_mul_f32_e64 v44, v46, v44
	v_mul_f32_e64 v45, v47, v45
	v_cvt_pk_bf16_f32 v106, v42, v43
	v_cvt_pk_bf16_f32 v107, v44, v45
	s_waitcnt lgkmcnt(2)
	v_mfma_f32_16x16x32_bf16 v[34:37], v[126:129], v[102:105], v[50:53]
	v_exp_f32_e32 v154, v134
	v_sub_u32_e32 v134, 0x60, v137
	v_cvt_f32_u32_e32 v134, v134
	ds_read2_b64 v[50:53], v165 offset0:208 offset1:212
	s_waitcnt lgkmcnt(2)
	v_mfma_f32_16x16x32_bf16 v[46:49], v[98:101], v[102:105], v[18:21]
	v_mul_f32_e32 v134, v162, v134
	v_exp_f32_e32 v152, v134
	v_mfma_f32_16x16x32_bf16 v[18:21], v[118:121], v[102:105], v[30:33]
	v_add_u32_e32 v134, 0xffffff9f, v137
	v_cvt_f32_u32_e32 v134, v134
	v_mul_f32_e32 v134, v163, v134
	s_waitcnt lgkmcnt(0)
	v_mfma_f32_16x16x32_bf16 v[30:33], v[50:53], v[102:105], v[54:57]
	v_exp_f32_e32 v155, v134
	v_sub_u32_e32 v134, 0x61, v137
	v_cvt_f32_u32_e32 v134, v134
	v_add_u32_e32 v54, 0x60, v171
	v_mfma_f32_16x16x32_bf16 v[42:45], v[110:113], v[102:105], v[22:25]
	v_mul_f32_e32 v134, v162, v134
	v_exp_f32_e32 v153, v134
	v_mfma_f32_16x16x32_bf16 v[22:25], v[114:117], v[102:105], v[26:29]
	v_add_u32_e32 v134, 0xffffff9e, v137
	v_cvt_f32_u32_e32 v134, v134
	v_mul_f32_e32 v134, v163, v134
	v_mfma_f32_16x16x32_bf16 v[26:29], v[130:133], v[102:105], v[58:61]
	v_exp_f32_e32 v150, v134
	v_sub_u32_e32 v134, 0x62, v137
	v_cvt_f32_u32_e32 v134, v134
	v_mad_i64_i32 v[58:59], s[0:1], v54, s26, v[144:145]
	global_load_dwordx4 v[54:57], v[58:59], off
	s_nop 0
	global_load_dwordx4 v[58:61], v[58:59], off offset:64
	v_mul_f32_e32 v134, v162, v134
	v_exp_f32_e32 v146, v134
	v_add_u32_e32 v134, 0xffffff9d, v137
	s_waitcnt vmcnt(1)
	v_mfma_f32_16x16x32_bf16 v[102:105], v[54:57], v[2:5], 0
	v_cvt_f32_u32_e32 v134, v134
	s_movk_i32 s0, 0x4f
	v_cmp_lt_i32_e32 vcc, s0, v137
	v_mfma_f32_16x16x32_bf16 v[54:57], v[54:57], v[6:9], 0
	s_movk_i32 s0, 0x50
	v_mul_f32_e32 v134, v163, v134
	v_cmp_lt_i32_e64 s[8:9], s0, v137
	s_waitcnt vmcnt(0)
	v_mfma_f32_16x16x32_bf16 v[174:177], v[58:61], v[10:13], v[54:57]
	v_exp_f32_e32 v151, v134
	v_sub_u32_e32 v134, 0x63, v137
	s_movk_i32 s0, 0x51
	v_pk_add_f32 v[54:55], v[148:149], 0 op_sel_hi:[1,0]
	s_movk_i32 s1, 0x52
	v_cndmask_b32_e64 v57, 0, v55, s[8:9]
	v_cndmask_b32_e32 v56, 0, v54, vcc
	v_cvt_f32_u32_e32 v134, v134
	v_cmp_gt_i32_e32 vcc, s0, v137
	v_cmp_gt_i32_e64 s[8:9], s1, v137
	v_pk_add_f32 v[56:57], v[56:57], v[108:109]
	v_mul_f32_e32 v134, v162, v134
	v_cndmask_b32_e64 v55, v55, v57, s[8:9]
	v_cndmask_b32_e32 v54, v54, v56, vcc
	v_pk_mul_f32 v[56:57], v[54:55], v[94:95]
	v_pk_mul_f32 v[148:149], v[54:55], v[174:175]
	v_cmp_lt_i32_e32 vcc, s0, v137
	v_cmp_lt_i32_e64 s[8:9], s1, v137
	v_pk_add_f32 v[54:55], v[158:159], 0 op_sel_hi:[1,0]
	s_movk_i32 s0, 0x53
	v_cvt_pk_bf16_f32 v108, v56, v57
	v_cndmask_b32_e64 v57, 0, v55, s[8:9]
	v_cndmask_b32_e32 v56, 0, v54, vcc
	v_cmp_gt_i32_e32 vcc, s0, v137
	s_movk_i32 s0, 0x54
	v_cmp_gt_i32_e64 s[8:9], s0, v137
	v_pk_add_f32 v[56:57], v[56:57], v[156:157]
	v_exp_f32_e32 v147, v134
	v_cndmask_b32_e64 v135, v55, v57, s[8:9]
	v_cndmask_b32_e32 v134, v54, v56, vcc
	v_pk_mul_f32 v[54:55], v[134:135], v[96:97]
	v_mfma_f32_16x16x32_bf16 v[102:105], v[58:61], v[14:17], v[102:105]
	v_cvt_pk_bf16_f32 v109, v54, v55
	v_cmp_lt_i32_e64 s[8:9], s11, v137
	s_nop 0
	v_mfma_f32_16x16x32_bf16 v[94:97], v[110:113], v[106:109], v[66:69]
	v_mfma_f32_16x16x32_bf16 v[66:69], v[118:121], v[106:109], v[74:77]
	s_nop 2
	v_add_u32_e32 v74, 0x70, v171
	v_mfma_f32_16x16x32_bf16 v[98:101], v[98:101], v[106:109], v[62:65]
	v_mfma_f32_16x16x32_bf16 v[62:65], v[122:125], v[106:109], v[78:81]
	s_nop 2
	v_mad_i64_i32 v[78:79], s[0:1], v74, s26, v[144:145]
	global_load_dwordx4 v[74:77], v[78:79], off
	s_nop 0
	global_load_dwordx4 v[78:81], v[78:79], off offset:64
	s_waitcnt vmcnt(1)
	v_mfma_f32_16x16x32_bf16 v[2:5], v[74:77], v[2:5], 0
	s_movk_i32 s0, 0x5f
	v_cmp_lt_i32_e32 vcc, s0, v137
	s_movk_i32 s0, 0xffef
	s_waitcnt vmcnt(0)
	v_mfma_f32_16x16x32_bf16 v[2:5], v[78:81], v[14:17], v[2:5]
	v_sub_u32_e32 v14, 0x70, v137
	v_sub_u32_e32 v15, 0x71, v137
	v_cvt_f32_u32_e32 v14, v14
	v_cvt_f32_u32_e32 v15, v15
	v_mfma_f32_16x16x32_bf16 v[58:61], v[126:129], v[106:109], v[82:85]
	s_movk_i32 s1, 0x61
	v_mul_f32_e32 v14, v162, v14
	v_mul_f32_e32 v15, v162, v15
	v_exp_f32_e32 v14, v14
	v_exp_f32_e32 v15, v15
	v_add_u32_e32 v84, 0xffffff90, v137
	v_cmp_gt_i32_e64 s[10:11], s1, v137
	v_mfma_f32_16x16x32_bf16 v[54:57], v[50:53], v[106:109], v[86:89]
	v_add_f32_e64 v14, v14, 0
	v_add_f32_e64 v15, v15, 0
	v_pk_mul_f32 v[82:83], v[134:135], v[176:177]
	v_pk_mul_f32 v[14:15], v[14:15], v[2:3]
	v_sub_u32_e32 v2, 0x72, v137
	v_sub_u32_e32 v3, 0x73, v137
	v_cvt_f32_u32_e32 v2, v2
	v_cvt_f32_u32_e32 v3, v3
	v_cvt_pk_bf16_f32 v85, v82, v83
	v_mfma_f32_16x16x32_bf16 v[70:73], v[114:117], v[106:109], v[70:73]
	v_mul_f32_e32 v2, v162, v2
	v_mul_f32_e32 v3, v162, v3
	v_exp_f32_e32 v2, v2
	v_exp_f32_e32 v3, v3
	v_mfma_f32_16x16x32_bf16 v[50:53], v[130:133], v[106:109], v[90:93]
	v_add_f32_e64 v2, v2, 0
	v_add_f32_e64 v3, v3, 0
	v_pk_mul_f32 v[16:17], v[2:3], v[4:5]
	v_mfma_f32_16x16x32_bf16 v[2:5], v[74:77], v[6:9], 0
	v_add_f32_e64 v6, v154, 0
	v_add_f32_e64 v7, v155, 0
	v_cndmask_b32_e64 v9, 0, v7, s[8:9]
	v_mfma_f32_16x16x32_bf16 v[2:5], v[78:81], v[10:13], v[2:5]
	v_cndmask_b32_e32 v8, 0, v6, vcc
	v_cmp_lt_u32_e32 vcc, s0, v84
	v_cmp_lt_u32_e64 s[8:9], -16, v84
	v_pk_add_f32 v[8:9], v[8:9], v[152:153]
	v_cndmask_b32_e32 v10, 0, v6, vcc
	v_cndmask_b32_e64 v11, 0, v7, s[8:9]
	v_cmp_gt_u32_e32 vcc, -15, v84
	v_cmp_gt_u32_e64 s[8:9], -14, v84
	v_pk_add_f32 v[10:11], v[10:11], v[152:153]
	v_cndmask_b32_e64 v9, v7, v9, s[12:13]
	v_cndmask_b32_e64 v8, v6, v8, s[10:11]
	v_cndmask_b32_e64 v7, v7, v11, s[8:9]
	v_cndmask_b32_e32 v6, v6, v10, vcc
	v_pk_mul_f32 v[6:7], v[6:7], v[2:3]
	v_pk_add_f32 v[2:3], v[150:151], 0 op_sel_hi:[1,0]
	v_cmp_lt_i32_e32 vcc, s1, v137
	v_cmp_lt_i32_e64 s[8:9], s6, v137
	s_movk_i32 s0, 0x63
	v_cndmask_b32_e32 v10, 0, v2, vcc
	v_cndmask_b32_e64 v11, 0, v3, s[8:9]
	v_cmp_lt_u32_e32 vcc, -15, v84
	v_cmp_lt_u32_e64 s[8:9], -14, v84
	v_cmp_gt_i32_e64 s[10:11], s0, v137
	s_movk_i32 s0, 0x64
	v_cndmask_b32_e64 v13, 0, v3, s[8:9]
	v_cndmask_b32_e32 v12, 0, v2, vcc
	v_cmp_gt_i32_e64 s[12:13], s0, v137
	v_pk_add_f32 v[10:11], v[10:11], v[146:147]
	v_cmp_gt_u32_e32 vcc, -13, v84
	v_cmp_gt_u32_e64 s[8:9], -12, v84
	v_pk_add_f32 v[12:13], v[12:13], v[146:147]
	v_pk_mul_f32 v[8:9], v[8:9], v[102:103]
	v_cndmask_b32_e64 v11, v3, v11, s[12:13]
	v_cndmask_b32_e64 v10, v2, v10, s[10:11]
	v_cndmask_b32_e64 v3, v3, v13, s[8:9]
	v_cndmask_b32_e32 v2, v2, v12, vcc
	v_pk_mul_f32 v[12:13], v[2:3], v[4:5]
	v_cvt_pk_bf16_f32 v2, v8, v9
	v_cvt_pk_bf16_f32 v86, v6, v7
	ds_read2_b64 v[6:9], v172 offset0:24 offset1:28
	v_pk_mul_f32 v[10:11], v[10:11], v[104:105]
	v_cvt_pk_bf16_f32 v4, v14, v15
	v_cvt_pk_bf16_f32 v3, v10, v11
	v_cvt_pk_bf16_f32 v5, v16, v17
	v_cvt_pk_bf16_f32 v84, v148, v149
	v_cvt_pk_bf16_f32 v87, v12, v13
	s_waitcnt lgkmcnt(0)
; __device__ __forceinline__ float lo_bf(unsigned u) { return __uint_as_float(u << 16); }
; __device__ __forceinline__ float hi_bf(unsigned u) { return __uint_as_float(u & 0xffff0000u); }
; __device__ __forceinline__ float siluf(float x) { return x * __builtin_amdgcn_rcpf(1.f + __expf(-x)); }
; __device__ __forceinline__ void ret_out_item(const Params& p, int j, int b, int cc, int h, const u16* __restrict__ Z,
;                                              const u16* __restrict__ RVT, const float* __restrict__ U, u16* sVT) {
;     ...
; #pragma unroll
;     for (int eb = 0; eb < 8; ++eb) {
;       uint2 v0 = *(const uint2*)(sVT + (eb * 16 + fr) * 136 + kk * 32 + fq * 4);
;       uint2 v1 = *(const uint2*)(sVT + (eb * 16 + fr) * 136 + kk * 32 + 16 + fq * 4);
;       bf16x8 vf = mk8(v0.x, v0.y, v1.x, v1.y);
; #pragma unroll
;       for (int qb = 0; qb < 2; ++qb) o[qb][eb] = mfma16(vf, pf[qb], o[qb][eb]);
;     }
;   }
; #pragma unroll
;   for (int qb = 0; qb < 2; ++qb) {
;     const int qpos = wave * 32 + qb * 16 + fr;
;     float ss = 0.f;
; #pragma unroll
;     for (int eb = 0; eb < 8; ++eb)
; #pragma unroll
;       for (int r = 0; r < 4; ++r) ss += o[qb][eb][r] * o[qb][eb][r];
;     ss += __shfl_xor(ss, 16);
;     ss += __shfl_xor(ss, 32);
;     const float rstd = rsqrtf(ss * (1.f / 128.f) + EPSV);
; #pragma unroll
;     for (int eb = 0; eb < 8; ++eb) {
;       const int e = eb * 16 + fq * 4;
;       uint2 gg = *(const uint2*)(Z + (size_t)(r0 + qpos) * 2304 + 1280 + h * 128 + e);
;       float4 rn = *(const float4*)(p.ret_norm + j * 512 + h * 128 + e);
;       f32x4 v;
;       v[0] = o[qb][eb][0] * rstd * rn.x * siluf(lo_bf(gg.x));
;       v[1] = o[qb][eb][1] * rstd * rn.y * siluf(hi_bf(gg.x));
;       v[2] = o[qb][eb][2] * rstd * rn.z * siluf(lo_bf(gg.y));
;       v[3] = o[qb][eb][3] * rstd * rn.w * siluf(hi_bf(gg.y));
;       store4bf(p.XN + (size_t)(r0 + qpos) * 1024 + h * 128 + e, v);
	v_mfma_f32_16x16x32_bf16 v[78:81], v[6:9], v[2:5], v[98:101]
	v_cmp_lt_i32_e32 vcc, v200, v198
	s_lshl_b32 s0, s22, 9
	s_add_u32 s10, s15, s0
	v_mfma_f32_16x16x32_bf16 v[46:49], v[6:9], v[84:87], v[46:49]
	ds_read2_b64 v[6:9], v170 offset0:56 offset1:60
	s_addc_u32 s11, s17, 0
	s_nop 1
	v_mov_b32_e32 v89, v79
	s_waitcnt lgkmcnt(0)
	v_mfma_f32_16x16x32_bf16 v[74:77], v[6:9], v[2:5], v[94:97]
	s_nop 0
	v_mov_b32_e32 v88, v47
	v_pk_mul_f32 v[88:89], v[88:89], v[88:89]
	s_brev_b32 s0, 60
	v_mfma_f32_16x16x32_bf16 v[42:45], v[6:9], v[84:87], v[42:45]
	ds_read2_b64 v[6:9], v169 offset0:88 offset1:92
	s_waitcnt lgkmcnt(0)
	v_mfma_f32_16x16x32_bf16 v[70:73], v[6:9], v[2:5], v[70:73]
	v_mfma_f32_16x16x32_bf16 v[22:25], v[6:9], v[84:87], v[22:25]
	ds_read2_b64 v[6:9], v168 offset0:120 offset1:124
	s_waitcnt lgkmcnt(0)
	v_mfma_f32_16x16x32_bf16 v[66:69], v[6:9], v[2:5], v[66:69]
	v_mfma_f32_16x16x32_bf16 v[18:21], v[6:9], v[84:87], v[18:21]
	ds_read2_b64 v[6:9], v167 offset0:152 offset1:156
	s_waitcnt lgkmcnt(0)
	v_mfma_f32_16x16x32_bf16 v[62:65], v[6:9], v[2:5], v[62:65]
	v_mfma_f32_16x16x32_bf16 v[14:17], v[6:9], v[84:87], v[38:41]
	ds_read2_b64 v[6:9], v166 offset0:184 offset1:188
	s_waitcnt lgkmcnt(0)
	v_mfma_f32_16x16x32_bf16 v[38:41], v[6:9], v[2:5], v[58:61]
	v_mfma_f32_16x16x32_bf16 v[10:13], v[6:9], v[84:87], v[34:37]
	ds_read2_b64 v[6:9], v165 offset0:216 offset1:220
	s_waitcnt lgkmcnt(0)
	v_mfma_f32_16x16x32_bf16 v[34:37], v[6:9], v[2:5], v[54:57]
	s_nop 2
	ds_read2_b64 v[54:57], v164 offset0:248 offset1:252
	s_nop 3
	v_pk_mul_f32 v[60:61], v[34:35], v[34:35]
	v_mfma_f32_16x16x32_bf16 v[6:9], v[6:9], v[84:87], v[30:33]
	v_mul_f32_e64 v58, v36, v36
	v_mul_f32_e64 v59, v37, v37
	s_waitcnt lgkmcnt(0)
	v_mfma_f32_16x16x32_bf16 v[30:33], v[54:57], v[2:5], v[50:53]
	s_nop 2
	v_lshlrev_b64 v[50:51], 11, v[138:139]
	v_mfma_f32_16x16x32_bf16 v[2:5], v[54:57], v[84:87], v[26:29]
	v_mul_f32_e64 v92, v6, v6
	v_mul_f32_e64 v93, v7, v7
	v_pk_mul_f32 v[90:91], v[8:9], v[8:9]
	v_pk_mul_f32 v[56:57], v[30:31], v[30:31]
	v_cndmask_b32_e32 v26, v197, v200, vcc
	v_cmp_lt_i32_e32 vcc, v199, v198
	v_lshlrev_b32_e32 v96, 2, v26
	s_nop 0
	v_pk_mul_f32 v[94:95], v[2:3], v[2:3]
	v_cndmask_b32_e32 v26, v197, v199, vcc
	v_lshlrev_b32_e32 v97, 2, v26
	v_lshl_add_u64 v[26:27], v[142:143], 0, s[34:35]
	v_lshl_add_u64 v[52:53], v[26:27], 0, v[0:1]
	global_load_dwordx2 v[84:85], v[52:53], off offset:2560
	global_load_dwordx4 v[26:29], v136, s[10:11]
	global_load_dwordx4 v[202:205], v136, s[10:11]
	global_load_dwordx4 v[208:211], v136, s[10:11] offset:64
	global_load_dwordx4 v[212:215], v136, s[10:11] offset:128
	global_load_dwordx4 v[216:219], v136, s[10:11] offset:192
	global_load_dwordx4 v[220:223], v136, s[10:11] offset:256
	global_load_dwordx4 v[224:227], v136, s[10:11] offset:320
	global_load_dwordx4 v[228:231], v136, s[10:11] offset:384
	global_load_dwordx4 v[232:235], v136, s[10:11] offset:448
	global_load_dwordx2 v[236:237], v[52:53], off offset:2592
	global_load_dwordx2 v[238:239], v[52:53], off offset:2624
	global_load_dwordx2 v[240:241], v[52:53], off offset:2656
	global_load_dwordx2 v[242:243], v[52:53], off offset:2688
	global_load_dwordx2 v[244:245], v[52:53], off offset:2720
	global_load_dwordx2 v[246:247], v[52:53], off offset:2752
	global_load_dwordx2 v[248:249], v[52:53], off offset:2784
	v_mov_b32_e32 v250, 0x12000
	v_mov_b32_e32 v251, 0
	v_lshl_add_u64 v[250:251], v[52:53], 0, v[250:251]
	global_load_dwordx2 v[178:179], v[250:251], off offset:2560
	global_load_dwordx2 v[180:181], v[250:251], off offset:2592
	global_load_dwordx2 v[182:183], v[250:251], off offset:2624
	global_load_dwordx2 v[184:185], v[250:251], off offset:2656
	global_load_dwordx2 v[186:187], v[250:251], off offset:2688
	global_load_dwordx2 v[188:189], v[250:251], off offset:2720
	global_load_dwordx2 v[190:191], v[250:251], off offset:2752
	global_load_dwordx2 v[192:193], v[250:251], off offset:2784
	v_pk_mul_f32 v[54:55], v[32:33], v[32:33]
	v_lshl_add_u64 v[50:51], s[42:43], 0, v[50:51]
	v_lshl_add_u64 v[50:51], v[50:51], 0, s[34:35]
	v_lshl_add_u64 v[50:51], v[50:51], 0, v[0:1]
	s_waitcnt vmcnt(0)
	v_lshlrev_b32_e32 v82, 16, v84
	v_and_b32_e32 v83, 0xffff0000, v84
	v_mul_f32_e32 v84, 0xbfb8aa3b, v82
	v_exp_f32_e32 v84, v84
	s_nop 0
	v_add_f32_e32 v84, 1.0, v84
	v_rcp_f32_e32 v86, v84
	v_mul_f32_e32 v84, 0xbfb8aa3b, v83
	v_exp_f32_e32 v84, v84
	s_nop 0
	v_add_f32_e32 v84, 1.0, v84
	v_rcp_f32_e32 v87, v84
	v_lshlrev_b32_e32 v84, 16, v85
	v_and_b32_e32 v85, 0xffff0000, v85
	v_pk_mul_f32 v[82:83], v[86:87], v[82:83]
	v_mul_f32_e32 v86, 0xbfb8aa3b, v84
	v_mul_f32_e32 v87, 0xbfb8aa3b, v85
	v_exp_f32_e32 v86, v86
	v_exp_f32_e32 v87, v87
	v_add_f32_e32 v86, 1.0, v86
	v_add_f32_e32 v87, 1.0, v87
	v_rcp_f32_e32 v86, v86
	v_rcp_f32_e32 v87, v87
	s_nop 0
	v_pk_mul_f32 v[84:85], v[86:87], v[84:85]
	v_mov_b32_e32 v86, v46
	v_mov_b32_e32 v87, v78
	v_pk_fma_f32 v[86:87], v[86:87], v[86:87], v[88:89]
	v_mov_b32_e32 v88, v48
	v_mov_b32_e32 v89, v80
	v_pk_fma_f32 v[86:87], v[88:89], v[88:89], v[86:87]
	v_mov_b32_e32 v88, v49
	v_mov_b32_e32 v89, v81
	v_pk_fma_f32 v[86:87], v[88:89], v[88:89], v[86:87]
	v_mov_b32_e32 v88, v42
	v_mov_b32_e32 v89, v74
	v_pk_fma_f32 v[86:87], v[88:89], v[88:89], v[86:87]
	v_mov_b32_e32 v88, v43
	v_mov_b32_e32 v89, v75
	v_pk_fma_f32 v[86:87], v[88:89], v[88:89], v[86:87]
	v_mov_b32_e32 v88, v44
	v_mov_b32_e32 v89, v76
	v_pk_fma_f32 v[86:87], v[88:89], v[88:89], v[86:87]
	v_mov_b32_e32 v88, v45
	v_mov_b32_e32 v89, v77
	v_pk_fma_f32 v[86:87], v[88:89], v[88:89], v[86:87]
	v_mov_b32_e32 v88, v22
	v_mov_b32_e32 v89, v70
	v_pk_fma_f32 v[86:87], v[88:89], v[88:89], v[86:87]
; __device__ __forceinline__ float lo_bf(unsigned u) { return __uint_as_float(u << 16); }
; __device__ __forceinline__ float hi_bf(unsigned u) { return __uint_as_float(u & 0xffff0000u); }
; __device__ __forceinline__ float siluf(float x) { return x * __builtin_amdgcn_rcpf(1.f + __expf(-x)); }
; __device__ __forceinline__ void ret_out_item(const Params& p, int j, int b, int cc, int h, const u16* __restrict__ Z,
;                                              const u16* __restrict__ RVT, const float* __restrict__ U, u16* sVT) {
;     ...
; #pragma unroll
;   for (int qb = 0; qb < 2; ++qb) {
;     const int qpos = wave * 32 + qb * 16 + fr;
;     float ss = 0.f;
; #pragma unroll
;     for (int eb = 0; eb < 8; ++eb)
; #pragma unroll
;       for (int r = 0; r < 4; ++r) ss += o[qb][eb][r] * o[qb][eb][r];
;     ss += __shfl_xor(ss, 16);
;     ss += __shfl_xor(ss, 32);
;     const float rstd = rsqrtf(ss * (1.f / 128.f) + EPSV);
; #pragma unroll
;     for (int eb = 0; eb < 8; ++eb) {
;       const int e = eb * 16 + fq * 4;
;       uint2 gg = *(const uint2*)(Z + (size_t)(r0 + qpos) * 2304 + 1280 + h * 128 + e);
;       float4 rn = *(const float4*)(p.ret_norm + j * 512 + h * 128 + e);
;       f32x4 v;
;       v[0] = o[qb][eb][0] * rstd * rn.x * siluf(lo_bf(gg.x));
;       v[1] = o[qb][eb][1] * rstd * rn.y * siluf(hi_bf(gg.x));
;       v[2] = o[qb][eb][2] * rstd * rn.z * siluf(lo_bf(gg.y));
;       v[3] = o[qb][eb][3] * rstd * rn.w * siluf(hi_bf(gg.y));
;       store4bf(p.XN + (size_t)(r0 + qpos) * 1024 + h * 128 + e, v);
;     }
	v_mov_b32_e32 v88, v23
	v_mov_b32_e32 v89, v71
	v_pk_fma_f32 v[86:87], v[88:89], v[88:89], v[86:87]
	v_mov_b32_e32 v88, v24
	v_mov_b32_e32 v89, v72
	v_pk_fma_f32 v[86:87], v[88:89], v[88:89], v[86:87]
	v_mov_b32_e32 v88, v25
	v_mov_b32_e32 v89, v73
	v_pk_fma_f32 v[86:87], v[88:89], v[88:89], v[86:87]
	v_mov_b32_e32 v88, v18
	v_mov_b32_e32 v89, v66
	v_pk_fma_f32 v[86:87], v[88:89], v[88:89], v[86:87]
	v_mov_b32_e32 v88, v19
	v_mov_b32_e32 v89, v67
	v_pk_fma_f32 v[86:87], v[88:89], v[88:89], v[86:87]
	v_mov_b32_e32 v88, v20
	v_mov_b32_e32 v89, v68
	v_pk_fma_f32 v[86:87], v[88:89], v[88:89], v[86:87]
	v_mov_b32_e32 v88, v21
	v_mov_b32_e32 v89, v69
	v_pk_fma_f32 v[86:87], v[88:89], v[88:89], v[86:87]
	v_mov_b32_e32 v88, v14
	v_mov_b32_e32 v89, v62
	v_pk_fma_f32 v[86:87], v[88:89], v[88:89], v[86:87]
	v_mov_b32_e32 v88, v15
	v_mov_b32_e32 v89, v63
	v_pk_fma_f32 v[86:87], v[88:89], v[88:89], v[86:87]
	v_mov_b32_e32 v88, v16
	v_mov_b32_e32 v89, v64
	v_pk_fma_f32 v[86:87], v[88:89], v[88:89], v[86:87]
	v_mov_b32_e32 v88, v17
	v_mov_b32_e32 v89, v65
	v_pk_fma_f32 v[86:87], v[88:89], v[88:89], v[86:87]
	v_mov_b32_e32 v88, v10
	v_mov_b32_e32 v89, v38
	v_pk_fma_f32 v[86:87], v[88:89], v[88:89], v[86:87]
	v_mov_b32_e32 v88, v11
	v_mov_b32_e32 v89, v39
	v_pk_fma_f32 v[86:87], v[88:89], v[88:89], v[86:87]
	v_mov_b32_e32 v88, v12
	v_mov_b32_e32 v89, v40
	v_pk_fma_f32 v[86:87], v[88:89], v[88:89], v[86:87]
	v_mov_b32_e32 v88, v13
	v_mov_b32_e32 v89, v41
	v_pk_fma_f32 v[86:87], v[88:89], v[88:89], v[86:87]
	v_mov_b32_e32 v88, v92
	v_mov_b32_e32 v89, v60
	v_pk_add_f32 v[86:87], v[86:87], v[88:89]
	v_mov_b32_e32 v60, v93
	v_pk_add_f32 v[60:61], v[60:61], v[86:87]
	v_mov_b32_e32 v86, v90
	v_mov_b32_e32 v87, v58
	v_pk_add_f32 v[60:61], v[86:87], v[60:61]
	v_mov_b32_e32 v58, v91
	v_pk_add_f32 v[58:59], v[58:59], v[60:61]
	v_mov_b32_e32 v60, v94
	v_mov_b32_e32 v61, v56
	v_pk_mul_f32 v[88:89], v[4:5], v[4:5]
	v_pk_add_f32 v[58:59], v[58:59], v[60:61]
	v_mov_b32_e32 v56, v95
	v_pk_add_f32 v[56:57], v[56:57], v[58:59]
	v_mov_b32_e32 v58, v88
	v_mov_b32_e32 v59, v54
	v_pk_add_f32 v[56:57], v[58:59], v[56:57]
	v_mov_b32_e32 v54, v89
	v_pk_add_f32 v[54:55], v[54:55], v[56:57]
	ds_bpermute_b32 v57, v96, v55
	ds_bpermute_b32 v56, v96, v54
	s_waitcnt lgkmcnt(0)
	v_pk_add_f32 v[54:55], v[54:55], v[56:57]
	ds_bpermute_b32 v57, v97, v55
	ds_bpermute_b32 v56, v97, v54
	s_waitcnt lgkmcnt(0)
	v_pk_add_f32 v[54:55], v[54:55], v[56:57]
	s_nop 0
	v_pk_fma_f32 v[54:55], v[54:55], s[0:1], v[252:253] op_sel_hi:[1,0,0]
	s_nop 0
	v_mul_f32_e32 v56, 0x4b800000, v55
	v_cmp_gt_f32_e64 s[8:9], s90, v55
	v_cmp_gt_f32_e32 vcc, s90, v54
	s_nop 0
	v_cndmask_b32_e64 v55, v55, v56, s[8:9]
	v_rsq_f32_e32 v55, v55
	s_nop 0
	v_mul_f32_e32 v56, 0x45800000, v55
	v_cndmask_b32_e64 v56, v55, v56, s[8:9]
	v_pk_mul_f32 v[58:59], v[78:79], v[56:57] op_sel_hi:[1,0]
	v_pk_mul_f32 v[74:75], v[74:75], v[56:57] op_sel_hi:[1,0]
	s_waitcnt vmcnt(0)
	v_pk_mul_f32 v[26:27], v[26:27], v[58:59]
	v_pk_mul_f32 v[58:59], v[80:81], v[56:57] op_sel_hi:[1,0]
	v_pk_mul_f32 v[26:27], v[82:83], v[26:27]
	v_pk_mul_f32 v[28:29], v[28:29], v[58:59]
	v_cvt_pk_bf16_f32 v26, v26, v27
	v_pk_mul_f32 v[28:29], v[84:85], v[28:29]
	v_pk_mul_f32 v[70:71], v[70:71], v[56:57] op_sel_hi:[1,0]
	v_cvt_pk_bf16_f32 v27, v28, v29
	global_store_dwordx2 v[50:51], v[26:27], off
	v_mov_b32_e32 v58, v236
	v_mov_b32_e32 v59, v237
	v_pk_mul_f32 v[66:67], v[66:67], v[56:57] op_sel_hi:[1,0]
	v_mov_b32_e32 v26, v208
	v_mov_b32_e32 v27, v209
	v_mov_b32_e32 v28, v210
	v_mov_b32_e32 v29, v211
	v_pk_mul_f32 v[62:63], v[62:63], v[56:57] op_sel_hi:[1,0]
	v_pk_mul_f32 v[38:39], v[38:39], v[56:57] op_sel_hi:[1,0]
	v_pk_mul_f32 v[40:41], v[40:41], v[56:57] op_sel_hi:[1,0]
	v_pk_mul_f32 v[34:35], v[34:35], v[56:57] op_sel_hi:[1,0]
	v_pk_mul_f32 v[36:37], v[36:37], v[56:57] op_sel_hi:[1,0]
	v_pk_mul_f32 v[30:31], v[30:31], v[56:57] op_sel_hi:[1,0]
	v_pk_mul_f32 v[32:33], v[32:33], v[56:57] op_sel_hi:[1,0]
	v_lshlrev_b32_e32 v60, 16, v58
	v_mul_f32_e32 v55, 0xbfb8aa3b, v60
	v_exp_f32_e32 v55, v55
	v_and_b32_e32 v61, 0xffff0000, v58
	v_lshlrev_b32_e32 v58, 16, v59
	v_pk_mul_f32 v[26:27], v[74:75], v[26:27]
	v_add_f32_e32 v55, 1.0, v55
	v_rcp_f32_e32 v78, v55
	v_mul_f32_e32 v55, 0xbfb8aa3b, v61
	v_exp_f32_e32 v55, v55
	v_and_b32_e32 v59, 0xffff0000, v59
	v_pk_mul_f32 v[74:75], v[76:77], v[56:57] op_sel_hi:[1,0]
	v_add_f32_e32 v55, 1.0, v55
	v_rcp_f32_e32 v79, v55
	v_mul_f32_e32 v55, 0xbfb8aa3b, v58
	v_exp_f32_e32 v55, v55
	v_pk_mul_f32 v[28:29], v[74:75], v[28:29]
	v_pk_mul_f32 v[60:61], v[78:79], v[60:61]
	v_add_f32_e32 v55, 1.0, v55
	v_pk_mul_f32 v[26:27], v[26:27], v[60:61]
	v_rcp_f32_e32 v60, v55
	v_mul_f32_e32 v55, 0xbfb8aa3b, v59
	v_exp_f32_e32 v55, v55
	v_cvt_pk_bf16_f32 v26, v26, v27
	v_add_f32_e32 v55, 1.0, v55
	v_rcp_f32_e32 v61, v55
	s_nop 0
	v_pk_mul_f32 v[58:59], v[60:61], v[58:59]
	s_nop 0
	v_pk_mul_f32 v[28:29], v[28:29], v[58:59]
	s_nop 0
	v_cvt_pk_bf16_f32 v27, v28, v29
	global_store_dwordx2 v[50:51], v[26:27], off offset:32
	v_mov_b32_e32 v58, v238
	v_mov_b32_e32 v59, v239
	v_lshlrev_b32_e32 v60, 16, v58
	v_mov_b32_e32 v26, v212
	v_mov_b32_e32 v27, v213
	v_mov_b32_e32 v28, v214
	v_mov_b32_e32 v29, v215
	v_mul_f32_e32 v55, 0xbfb8aa3b, v60
	v_exp_f32_e32 v55, v55
	v_and_b32_e32 v61, 0xffff0000, v58
	v_lshlrev_b32_e32 v58, 16, v59
	v_and_b32_e32 v59, 0xffff0000, v59
	v_add_f32_e32 v55, 1.0, v55
	v_rcp_f32_e32 v74, v55
	v_mul_f32_e32 v55, 0xbfb8aa3b, v61
	v_exp_f32_e32 v55, v55
	v_pk_mul_f32 v[26:27], v[70:71], v[26:27]
	v_add_f32_e32 v55, 1.0, v55
	v_rcp_f32_e32 v75, v55
	v_mul_f32_e32 v55, 0xbfb8aa3b, v58
	v_exp_f32_e32 v55, v55
; __device__ __forceinline__ float lo_bf(unsigned u) { return __uint_as_float(u << 16); }
; __device__ __forceinline__ float hi_bf(unsigned u) { return __uint_as_float(u & 0xffff0000u); }
; __device__ __forceinline__ float siluf(float x) { return x * __builtin_amdgcn_rcpf(1.f + __expf(-x)); }
; __device__ __forceinline__ void ret_out_item(const Params& p, int j, int b, int cc, int h, const u16* __restrict__ Z,
;                                              const u16* __restrict__ RVT, const float* __restrict__ U, u16* sVT) {
;     ...
; #pragma unroll
;     for (int eb = 0; eb < 8; ++eb) {
;       const int e = eb * 16 + fq * 4;
;       uint2 gg = *(const uint2*)(Z + (size_t)(r0 + qpos) * 2304 + 1280 + h * 128 + e);
;       float4 rn = *(const float4*)(p.ret_norm + j * 512 + h * 128 + e);
;       f32x4 v;
;       v[0] = o[qb][eb][0] * rstd * rn.x * siluf(lo_bf(gg.x));
;       v[1] = o[qb][eb][1] * rstd * rn.y * siluf(hi_bf(gg.x));
;       v[2] = o[qb][eb][2] * rstd * rn.z * siluf(lo_bf(gg.y));
;       v[3] = o[qb][eb][3] * rstd * rn.w * siluf(hi_bf(gg.y));
;       store4bf(p.XN + (size_t)(r0 + qpos) * 1024 + h * 128 + e, v);
;     }
	v_pk_mul_f32 v[70:71], v[72:73], v[56:57] op_sel_hi:[1,0]
	v_pk_mul_f32 v[60:61], v[74:75], v[60:61]
	v_pk_mul_f32 v[28:29], v[70:71], v[28:29]
	v_add_f32_e32 v55, 1.0, v55
	v_pk_mul_f32 v[26:27], v[26:27], v[60:61]
	v_rcp_f32_e32 v60, v55
	v_mul_f32_e32 v55, 0xbfb8aa3b, v59
	v_exp_f32_e32 v55, v55
	v_cvt_pk_bf16_f32 v26, v26, v27
	v_add_f32_e32 v55, 1.0, v55
	v_rcp_f32_e32 v61, v55
	s_nop 0
	v_pk_mul_f32 v[58:59], v[60:61], v[58:59]
	s_nop 0
	v_pk_mul_f32 v[28:29], v[28:29], v[58:59]
	s_nop 0
	v_cvt_pk_bf16_f32 v27, v28, v29
	global_store_dwordx2 v[50:51], v[26:27], off offset:64
	v_mov_b32_e32 v58, v240
	v_mov_b32_e32 v59, v241
	v_lshlrev_b32_e32 v60, 16, v58
	v_mov_b32_e32 v26, v216
	v_mov_b32_e32 v27, v217
	v_mov_b32_e32 v28, v218
	v_mov_b32_e32 v29, v219
	v_mul_f32_e32 v55, 0xbfb8aa3b, v60
	v_exp_f32_e32 v55, v55
	v_and_b32_e32 v61, 0xffff0000, v58
	v_lshlrev_b32_e32 v58, 16, v59
	v_and_b32_e32 v59, 0xffff0000, v59
	v_add_f32_e32 v55, 1.0, v55
	v_rcp_f32_e32 v70, v55
	v_mul_f32_e32 v55, 0xbfb8aa3b, v61
	v_exp_f32_e32 v55, v55
	v_pk_mul_f32 v[26:27], v[66:67], v[26:27]
	v_add_f32_e32 v55, 1.0, v55
	v_rcp_f32_e32 v71, v55
	v_mul_f32_e32 v55, 0xbfb8aa3b, v58
	v_exp_f32_e32 v55, v55
	v_pk_mul_f32 v[66:67], v[68:69], v[56:57] op_sel_hi:[1,0]
	v_pk_mul_f32 v[60:61], v[70:71], v[60:61]
	v_pk_mul_f32 v[28:29], v[66:67], v[28:29]
	v_add_f32_e32 v55, 1.0, v55
	v_pk_mul_f32 v[26:27], v[26:27], v[60:61]
	v_rcp_f32_e32 v60, v55
	v_mul_f32_e32 v55, 0xbfb8aa3b, v59
	v_exp_f32_e32 v55, v55
	v_cvt_pk_bf16_f32 v26, v26, v27
	v_add_f32_e32 v55, 1.0, v55
	v_rcp_f32_e32 v61, v55
	s_nop 0
	v_pk_mul_f32 v[58:59], v[60:61], v[58:59]
	s_nop 0
	v_pk_mul_f32 v[28:29], v[28:29], v[58:59]
	s_nop 0
	v_cvt_pk_bf16_f32 v27, v28, v29
	global_store_dwordx2 v[50:51], v[26:27], off offset:96
	v_mov_b32_e32 v58, v242
	v_mov_b32_e32 v59, v243
	v_lshlrev_b32_e32 v60, 16, v58
	v_mov_b32_e32 v26, v220
	v_mov_b32_e32 v27, v221
	v_mov_b32_e32 v28, v222
	v_mov_b32_e32 v29, v223
	v_mul_f32_e32 v55, 0xbfb8aa3b, v60
	v_exp_f32_e32 v55, v55
	v_and_b32_e32 v61, 0xffff0000, v58
	v_lshlrev_b32_e32 v58, 16, v59
	v_and_b32_e32 v59, 0xffff0000, v59
	v_add_f32_e32 v55, 1.0, v55
	v_rcp_f32_e32 v66, v55
	v_mul_f32_e32 v55, 0xbfb8aa3b, v61
	v_exp_f32_e32 v55, v55
	v_pk_mul_f32 v[26:27], v[62:63], v[26:27]
	v_add_f32_e32 v55, 1.0, v55
	v_rcp_f32_e32 v67, v55
	v_mul_f32_e32 v55, 0xbfb8aa3b, v58
	v_exp_f32_e32 v55, v55
	v_pk_mul_f32 v[62:63], v[64:65], v[56:57] op_sel_hi:[1,0]
	v_pk_mul_f32 v[60:61], v[66:67], v[60:61]
	v_pk_mul_f32 v[28:29], v[62:63], v[28:29]
	v_add_f32_e32 v55, 1.0, v55
	v_pk_mul_f32 v[26:27], v[26:27], v[60:61]
	v_rcp_f32_e32 v60, v55
	v_mul_f32_e32 v55, 0xbfb8aa3b, v59
	v_exp_f32_e32 v55, v55
	v_cvt_pk_bf16_f32 v26, v26, v27
	v_add_f32_e32 v55, 1.0, v55
	v_rcp_f32_e32 v61, v55
	s_nop 0
	v_pk_mul_f32 v[58:59], v[60:61], v[58:59]
	s_nop 0
	v_pk_mul_f32 v[28:29], v[28:29], v[58:59]
	s_nop 0
	v_cvt_pk_bf16_f32 v27, v28, v29
	global_store_dwordx2 v[50:51], v[26:27], off offset:128
	v_mov_b32_e32 v58, v244
	v_mov_b32_e32 v59, v245
	v_lshlrev_b32_e32 v60, 16, v58
	v_mov_b32_e32 v26, v224
	v_mov_b32_e32 v27, v225
	v_mov_b32_e32 v28, v226
	v_mov_b32_e32 v29, v227
	v_and_b32_e32 v61, 0xffff0000, v58
	v_mul_f32_e32 v55, 0xbfb8aa3b, v60
	v_exp_f32_e32 v55, v55
	v_pk_mul_f32 v[26:27], v[38:39], v[26:27]
	v_mul_f32_e32 v38, 0xbfb8aa3b, v61
	v_exp_f32_e32 v38, v38
	v_add_f32_e32 v55, 1.0, v55
	v_rcp_f32_e32 v62, v55
	v_pk_mul_f32 v[28:29], v[40:41], v[28:29]
	v_add_f32_e32 v38, 1.0, v38
	v_rcp_f32_e32 v63, v38
	s_nop 0
	v_pk_mul_f32 v[38:39], v[62:63], v[60:61]
	s_nop 0
	v_pk_mul_f32 v[26:27], v[26:27], v[38:39]
	v_lshlrev_b32_e32 v38, 16, v59
	v_and_b32_e32 v39, 0xffff0000, v59
	v_mul_f32_e32 v55, 0xbfb8aa3b, v38
	v_mul_f32_e32 v40, 0xbfb8aa3b, v39
	v_exp_f32_e32 v55, v55
	v_exp_f32_e32 v40, v40
	v_cvt_pk_bf16_f32 v26, v26, v27
	v_add_f32_e32 v55, 1.0, v55
	v_add_f32_e32 v40, 1.0, v40
	v_rcp_f32_e32 v58, v55
	v_rcp_f32_e32 v59, v40
	s_nop 0
	v_pk_mul_f32 v[38:39], v[58:59], v[38:39]
	s_nop 0
	v_pk_mul_f32 v[28:29], v[28:29], v[38:39]
	s_nop 0
	v_cvt_pk_bf16_f32 v27, v28, v29
	global_store_dwordx2 v[50:51], v[26:27], off offset:160
	v_mov_b32_e32 v38, v246
	v_mov_b32_e32 v39, v247
	v_lshlrev_b32_e32 v40, 16, v38
	v_mov_b32_e32 v26, v228
	v_mov_b32_e32 v27, v229
	v_mov_b32_e32 v28, v230
	v_mov_b32_e32 v29, v231
	v_and_b32_e32 v41, 0xffff0000, v38
	v_mul_f32_e32 v38, 0xbfb8aa3b, v40
	v_exp_f32_e32 v38, v38
	v_pk_mul_f32 v[26:27], v[34:35], v[26:27]
	v_mul_f32_e32 v34, 0xbfb8aa3b, v41
	v_exp_f32_e32 v34, v34
	v_add_f32_e32 v38, 1.0, v38
	v_rcp_f32_e32 v58, v38
	v_pk_mul_f32 v[28:29], v[36:37], v[28:29]
	v_add_f32_e32 v34, 1.0, v34
	v_rcp_f32_e32 v59, v34
	s_nop 0
	v_pk_mul_f32 v[34:35], v[58:59], v[40:41]
	s_nop 0
	v_pk_mul_f32 v[26:27], v[26:27], v[34:35]
	v_lshlrev_b32_e32 v34, 16, v39
	v_and_b32_e32 v35, 0xffff0000, v39
	v_mul_f32_e32 v38, 0xbfb8aa3b, v34
	v_mul_f32_e32 v36, 0xbfb8aa3b, v35
	v_exp_f32_e32 v38, v38
	v_exp_f32_e32 v36, v36
	v_cvt_pk_bf16_f32 v26, v26, v27
	v_add_f32_e32 v38, 1.0, v38
	v_add_f32_e32 v36, 1.0, v36
	v_rcp_f32_e32 v38, v38
	v_rcp_f32_e32 v39, v36
	s_nop 0
	v_pk_mul_f32 v[34:35], v[38:39], v[34:35]
	s_nop 0
	v_pk_mul_f32 v[28:29], v[28:29], v[34:35]
	s_nop 0
	v_cvt_pk_bf16_f32 v27, v28, v29
	global_store_dwordx2 v[50:51], v[26:27], off offset:192
	v_mov_b32_e32 v34, v248
	v_mov_b32_e32 v35, v249
	v_lshlrev_b32_e32 v36, 16, v34
	v_mov_b32_e32 v26, v232
	v_mov_b32_e32 v27, v233
	v_mov_b32_e32 v28, v234
	v_mov_b32_e32 v29, v235
	v_and_b32_e32 v37, 0xffff0000, v34
	v_mul_f32_e32 v34, 0xbfb8aa3b, v36
	v_exp_f32_e32 v34, v34
	v_pk_mul_f32 v[26:27], v[30:31], v[26:27]
; __device__ __forceinline__ float lo_bf(unsigned u) { return __uint_as_float(u << 16); }
; __device__ __forceinline__ float hi_bf(unsigned u) { return __uint_as_float(u & 0xffff0000u); }
; __device__ __forceinline__ float siluf(float x) { return x * __builtin_amdgcn_rcpf(1.f + __expf(-x)); }
; __device__ __forceinline__ void ret_out_item(const Params& p, int j, int b, int cc, int h, const u16* __restrict__ Z,
;                                              const u16* __restrict__ RVT, const float* __restrict__ U, u16* sVT) {
;     ...
; #pragma unroll
;     for (int eb = 0; eb < 8; ++eb) {
;       const int e = eb * 16 + fq * 4;
;       uint2 gg = *(const uint2*)(Z + (size_t)(r0 + qpos) * 2304 + 1280 + h * 128 + e);
;       float4 rn = *(const float4*)(p.ret_norm + j * 512 + h * 128 + e);
;       f32x4 v;
;       v[0] = o[qb][eb][0] * rstd * rn.x * siluf(lo_bf(gg.x));
;       v[1] = o[qb][eb][1] * rstd * rn.y * siluf(hi_bf(gg.x));
;       v[2] = o[qb][eb][2] * rstd * rn.z * siluf(lo_bf(gg.y));
;       v[3] = o[qb][eb][3] * rstd * rn.w * siluf(hi_bf(gg.y));
;       store4bf(p.XN + (size_t)(r0 + qpos) * 1024 + h * 128 + e, v);
;     }
	v_mul_f32_e32 v30, 0xbfb8aa3b, v37
	v_exp_f32_e32 v30, v30
	v_add_f32_e32 v34, 1.0, v34
	v_rcp_f32_e32 v38, v34
	v_pk_mul_f32 v[28:29], v[32:33], v[28:29]
	v_add_f32_e32 v30, 1.0, v30
	v_rcp_f32_e32 v39, v30
	s_nop 0
	v_pk_mul_f32 v[30:31], v[38:39], v[36:37]
	s_nop 0
	v_pk_mul_f32 v[26:27], v[26:27], v[30:31]
	v_lshlrev_b32_e32 v30, 16, v35
	v_and_b32_e32 v31, 0xffff0000, v35
	v_mul_f32_e32 v34, 0xbfb8aa3b, v30
	v_mul_f32_e32 v32, 0xbfb8aa3b, v31
	v_exp_f32_e32 v34, v34
	v_exp_f32_e32 v32, v32
	v_cvt_pk_bf16_f32 v26, v26, v27
	v_add_f32_e32 v34, 1.0, v34
	v_add_f32_e32 v32, 1.0, v32
	v_rcp_f32_e32 v34, v34
	v_rcp_f32_e32 v35, v32
	s_nop 0
	v_pk_mul_f32 v[30:31], v[34:35], v[30:31]
	s_nop 0
	v_pk_mul_f32 v[28:29], v[28:29], v[30:31]
	s_nop 0
	v_cvt_pk_bf16_f32 v27, v28, v29
	v_add_u32_e32 v28, 16, v138
	v_mad_i64_i32 v[30:31], s[0:1], v28, s26, v[140:141]
	v_lshl_add_u64 v[30:31], v[30:31], 0, s[34:35]
	global_store_dwordx2 v[50:51], v[26:27], off offset:224
	v_lshl_add_u64 v[30:31], v[30:31], 0, v[0:1]
	v_mov_b32_e32 v36, v178
	v_mov_b32_e32 v37, v179
	v_mov_b32_e32 v32, v202
	v_mov_b32_e32 v33, v203
	v_mov_b32_e32 v34, v204
	v_mov_b32_e32 v35, v205
	v_mul_f32_e32 v26, 0x4b800000, v54
	v_cndmask_b32_e32 v26, v54, v26, vcc
	v_rsq_f32_e32 v26, v26
	v_ashrrev_i32_e32 v29, 31, v28
	v_lshlrev_b64 v[28:29], 11, v[28:29]
	v_lshl_add_u64 v[28:29], s[42:43], 0, v[28:29]
	v_mul_f32_e32 v27, 0x45800000, v26
	v_cndmask_b32_e32 v26, v26, v27, vcc
	v_lshl_add_u64 v[28:29], v[28:29], 0, s[34:35]
	v_lshl_add_u64 v[28:29], v[28:29], 0, v[0:1]
	v_lshlrev_b32_e32 v38, 16, v36
	v_mul_f32_e32 v27, 0xbfb8aa3b, v38
	v_exp_f32_e32 v27, v27
	v_and_b32_e32 v39, 0xffff0000, v36
	v_lshlrev_b32_e32 v36, 16, v37
	v_and_b32_e32 v37, 0xffff0000, v37
	v_add_f32_e32 v27, 1.0, v27
	v_rcp_f32_e32 v40, v27
	v_pk_mul_f32 v[46:47], v[46:47], v[26:27] op_sel_hi:[1,0]
	v_mul_f32_e32 v27, 0xbfb8aa3b, v39
	v_exp_f32_e32 v27, v27
	v_pk_mul_f32 v[32:33], v[32:33], v[46:47]
	v_add_f32_e32 v27, 1.0, v27
	v_rcp_f32_e32 v41, v27
	v_mul_f32_e32 v27, 0xbfb8aa3b, v36
	v_exp_f32_e32 v27, v27
	v_pk_mul_f32 v[38:39], v[40:41], v[38:39]
	s_nop 0
	v_pk_mul_f32 v[32:33], v[38:39], v[32:33]
	v_add_f32_e32 v27, 1.0, v27
	v_rcp_f32_e32 v38, v27
	v_pk_mul_f32 v[40:41], v[48:49], v[26:27] op_sel_hi:[1,0]
	v_mul_f32_e32 v27, 0xbfb8aa3b, v37
	v_exp_f32_e32 v27, v27
	v_pk_mul_f32 v[34:35], v[34:35], v[40:41]
	v_cvt_pk_bf16_f32 v32, v32, v33
	v_add_f32_e32 v27, 1.0, v27
	v_rcp_f32_e32 v39, v27
	v_pk_mul_f32 v[42:43], v[42:43], v[26:27] op_sel_hi:[1,0]
	v_pk_mul_f32 v[22:23], v[22:23], v[26:27] op_sel_hi:[1,0]
	v_pk_mul_f32 v[24:25], v[24:25], v[26:27] op_sel_hi:[1,0]
	v_pk_mul_f32 v[36:37], v[38:39], v[36:37]
	v_pk_mul_f32 v[18:19], v[18:19], v[26:27] op_sel_hi:[1,0]
	v_pk_mul_f32 v[34:35], v[36:37], v[34:35]
	v_pk_mul_f32 v[20:21], v[20:21], v[26:27] op_sel_hi:[1,0]
	v_cvt_pk_bf16_f32 v33, v34, v35
	global_store_dwordx2 v[28:29], v[32:33], off
	v_mov_b32_e32 v36, v180
	v_mov_b32_e32 v37, v181
	v_pk_mul_f32 v[14:15], v[14:15], v[26:27] op_sel_hi:[1,0]
	v_mov_b32_e32 v32, v208
	v_mov_b32_e32 v33, v209
	v_mov_b32_e32 v34, v210
	v_mov_b32_e32 v35, v211
	v_pk_mul_f32 v[16:17], v[16:17], v[26:27] op_sel_hi:[1,0]
	v_pk_mul_f32 v[10:11], v[10:11], v[26:27] op_sel_hi:[1,0]
	v_pk_mul_f32 v[12:13], v[12:13], v[26:27] op_sel_hi:[1,0]
	v_pk_mul_f32 v[6:7], v[6:7], v[26:27] op_sel_hi:[1,0]
	v_pk_mul_f32 v[8:9], v[8:9], v[26:27] op_sel_hi:[1,0]
	v_pk_mul_f32 v[2:3], v[2:3], v[26:27] op_sel_hi:[1,0]
	v_pk_mul_f32 v[4:5], v[4:5], v[26:27] op_sel_hi:[1,0]
	v_lshlrev_b32_e32 v38, 16, v36
	v_mul_f32_e32 v0, 0xbfb8aa3b, v38
	v_exp_f32_e32 v0, v0
	v_and_b32_e32 v39, 0xffff0000, v36
	v_lshlrev_b32_e32 v36, 16, v37
	v_pk_mul_f32 v[32:33], v[42:43], v[32:33]
	v_add_f32_e32 v0, 1.0, v0
	v_rcp_f32_e32 v40, v0
	v_mul_f32_e32 v0, 0xbfb8aa3b, v39
	v_exp_f32_e32 v0, v0
	v_and_b32_e32 v37, 0xffff0000, v37
	v_add_f32_e32 v0, 1.0, v0
	v_rcp_f32_e32 v41, v0
	v_mul_f32_e32 v0, 0xbfb8aa3b, v36
	v_exp_f32_e32 v0, v0
	v_pk_mul_f32 v[38:39], v[40:41], v[38:39]
	s_nop 0
	v_pk_mul_f32 v[32:33], v[32:33], v[38:39]
	v_add_f32_e32 v0, 1.0, v0
	v_rcp_f32_e32 v38, v0
	v_mul_f32_e32 v0, 0xbfb8aa3b, v37
	v_exp_f32_e32 v0, v0
	v_pk_mul_f32 v[40:41], v[44:45], v[26:27] op_sel_hi:[1,0]
	v_cvt_pk_bf16_f32 v32, v32, v33
	v_pk_mul_f32 v[34:35], v[40:41], v[34:35]
	v_add_f32_e32 v0, 1.0, v0
	v_rcp_f32_e32 v39, v0
	s_nop 0
	v_pk_mul_f32 v[36:37], v[38:39], v[36:37]
	s_nop 0
	v_pk_mul_f32 v[34:35], v[34:35], v[36:37]
	s_nop 0
	v_cvt_pk_bf16_f32 v33, v34, v35
	global_store_dwordx2 v[28:29], v[32:33], off offset:32
	v_mov_b32_e32 v36, v182
	v_mov_b32_e32 v37, v183
	v_lshlrev_b32_e32 v38, 16, v36
	v_mov_b32_e32 v32, v212
	v_mov_b32_e32 v33, v213
	v_mov_b32_e32 v34, v214
	v_mov_b32_e32 v35, v215
	v_mul_f32_e32 v0, 0xbfb8aa3b, v38
	v_exp_f32_e32 v0, v0
	v_and_b32_e32 v39, 0xffff0000, v36
	v_add_f32_e32 v0, 1.0, v0
	v_rcp_f32_e32 v40, v0
	v_mul_f32_e32 v0, 0xbfb8aa3b, v39
	v_exp_f32_e32 v0, v0
	v_pk_mul_f32 v[22:23], v[22:23], v[32:33]
	v_add_f32_e32 v0, 1.0, v0
	v_rcp_f32_e32 v41, v0
	v_pk_mul_f32 v[24:25], v[24:25], v[34:35]
	v_pk_mul_f32 v[32:33], v[40:41], v[38:39]
	s_nop 0
	v_pk_mul_f32 v[22:23], v[22:23], v[32:33]
	v_lshlrev_b32_e32 v32, 16, v37
	v_mul_f32_e32 v0, 0xbfb8aa3b, v32
	v_exp_f32_e32 v0, v0
	v_and_b32_e32 v33, 0xffff0000, v37
	v_cvt_pk_bf16_f32 v22, v22, v23
	v_add_f32_e32 v0, 1.0, v0
	v_rcp_f32_e32 v36, v0
	v_mul_f32_e32 v0, 0xbfb8aa3b, v33
	v_exp_f32_e32 v0, v0
	s_nop 0
	v_add_f32_e32 v0, 1.0, v0
	v_rcp_f32_e32 v37, v0
	s_nop 0
	v_pk_mul_f32 v[32:33], v[36:37], v[32:33]
	s_nop 0
	v_pk_mul_f32 v[24:25], v[24:25], v[32:33]
	s_nop 0
; __device__ __forceinline__ float lo_bf(unsigned u) { return __uint_as_float(u << 16); }
; __device__ __forceinline__ float hi_bf(unsigned u) { return __uint_as_float(u & 0xffff0000u); }
; __device__ __forceinline__ float siluf(float x) { return x * __builtin_amdgcn_rcpf(1.f + __expf(-x)); }
; __device__ __forceinline__ void ret_out_item(const Params& p, int j, int b, int cc, int h, const u16* __restrict__ Z,
;                                              const u16* __restrict__ RVT, const float* __restrict__ U, u16* sVT) {
;     ...
; #pragma unroll
;     for (int eb = 0; eb < 8; ++eb) {
;       const int e = eb * 16 + fq * 4;
;       uint2 gg = *(const uint2*)(Z + (size_t)(r0 + qpos) * 2304 + 1280 + h * 128 + e);
;       float4 rn = *(const float4*)(p.ret_norm + j * 512 + h * 128 + e);
;       f32x4 v;
;       v[0] = o[qb][eb][0] * rstd * rn.x * siluf(lo_bf(gg.x));
;       v[1] = o[qb][eb][1] * rstd * rn.y * siluf(hi_bf(gg.x));
;       v[2] = o[qb][eb][2] * rstd * rn.z * siluf(lo_bf(gg.y));
;       v[3] = o[qb][eb][3] * rstd * rn.w * siluf(hi_bf(gg.y));
;       store4bf(p.XN + (size_t)(r0 + qpos) * 1024 + h * 128 + e, v);
;     }
	v_cvt_pk_bf16_f32 v23, v24, v25
	global_store_dwordx2 v[28:29], v[22:23], off offset:64
	v_mov_b32_e32 v32, v184
	v_mov_b32_e32 v33, v185
	v_lshlrev_b32_e32 v34, 16, v32
	v_mov_b32_e32 v22, v216
	v_mov_b32_e32 v23, v217
	v_mov_b32_e32 v24, v218
	v_mov_b32_e32 v25, v219
	v_mul_f32_e32 v0, 0xbfb8aa3b, v34
	v_exp_f32_e32 v0, v0
	v_and_b32_e32 v35, 0xffff0000, v32
	v_add_f32_e32 v0, 1.0, v0
	v_rcp_f32_e32 v36, v0
	v_mul_f32_e32 v0, 0xbfb8aa3b, v35
	v_exp_f32_e32 v0, v0
	v_pk_mul_f32 v[18:19], v[18:19], v[22:23]
	v_add_f32_e32 v0, 1.0, v0
	v_rcp_f32_e32 v37, v0
	v_pk_mul_f32 v[20:21], v[20:21], v[24:25]
	v_pk_mul_f32 v[22:23], v[36:37], v[34:35]
	s_nop 0
	v_pk_mul_f32 v[18:19], v[18:19], v[22:23]
	v_lshlrev_b32_e32 v22, 16, v33
	v_mul_f32_e32 v0, 0xbfb8aa3b, v22
	v_exp_f32_e32 v0, v0
	v_and_b32_e32 v23, 0xffff0000, v33
	v_cvt_pk_bf16_f32 v18, v18, v19
	v_add_f32_e32 v0, 1.0, v0
	v_rcp_f32_e32 v32, v0
	v_mul_f32_e32 v0, 0xbfb8aa3b, v23
	v_exp_f32_e32 v0, v0
	s_nop 0
	v_add_f32_e32 v0, 1.0, v0
	v_rcp_f32_e32 v33, v0
	s_nop 0
	v_pk_mul_f32 v[22:23], v[32:33], v[22:23]
	s_nop 0
	v_pk_mul_f32 v[20:21], v[20:21], v[22:23]
	s_nop 0
	v_cvt_pk_bf16_f32 v19, v20, v21
	global_store_dwordx2 v[28:29], v[18:19], off offset:96
	v_mov_b32_e32 v22, v186
	v_mov_b32_e32 v23, v187
	v_lshlrev_b32_e32 v24, 16, v22
	v_mov_b32_e32 v18, v220
	v_mov_b32_e32 v19, v221
	v_mov_b32_e32 v20, v222
	v_mov_b32_e32 v21, v223
	v_mul_f32_e32 v0, 0xbfb8aa3b, v24
	v_exp_f32_e32 v0, v0
	v_and_b32_e32 v25, 0xffff0000, v22
	v_add_f32_e32 v0, 1.0, v0
	v_rcp_f32_e32 v32, v0
	v_mul_f32_e32 v0, 0xbfb8aa3b, v25
	v_exp_f32_e32 v0, v0
	v_pk_mul_f32 v[14:15], v[14:15], v[18:19]
	v_add_f32_e32 v0, 1.0, v0
	v_rcp_f32_e32 v33, v0
	v_pk_mul_f32 v[16:17], v[16:17], v[20:21]
	v_pk_mul_f32 v[18:19], v[32:33], v[24:25]
	s_nop 0
	v_pk_mul_f32 v[14:15], v[14:15], v[18:19]
	v_lshlrev_b32_e32 v18, 16, v23
	v_mul_f32_e32 v0, 0xbfb8aa3b, v18
	v_exp_f32_e32 v0, v0
	v_and_b32_e32 v19, 0xffff0000, v23
	v_cvt_pk_bf16_f32 v14, v14, v15
	v_add_f32_e32 v0, 1.0, v0
	v_rcp_f32_e32 v22, v0
	v_mul_f32_e32 v0, 0xbfb8aa3b, v19
	v_exp_f32_e32 v0, v0
	s_nop 0
	v_add_f32_e32 v0, 1.0, v0
	v_rcp_f32_e32 v23, v0
	s_nop 0
	v_pk_mul_f32 v[18:19], v[22:23], v[18:19]
	s_nop 0
	v_pk_mul_f32 v[16:17], v[16:17], v[18:19]
	s_nop 0
	v_cvt_pk_bf16_f32 v15, v16, v17
	global_store_dwordx2 v[28:29], v[14:15], off offset:128
	v_mov_b32_e32 v18, v188
	v_mov_b32_e32 v19, v189
	v_lshlrev_b32_e32 v20, 16, v18
	v_mov_b32_e32 v14, v224
	v_mov_b32_e32 v15, v225
	v_mov_b32_e32 v16, v226
	v_mov_b32_e32 v17, v227
	v_mul_f32_e32 v0, 0xbfb8aa3b, v20
	v_exp_f32_e32 v0, v0
	v_and_b32_e32 v21, 0xffff0000, v18
	v_add_f32_e32 v0, 1.0, v0
	v_rcp_f32_e32 v22, v0
	v_mul_f32_e32 v0, 0xbfb8aa3b, v21
	v_exp_f32_e32 v0, v0
	v_pk_mul_f32 v[10:11], v[10:11], v[14:15]
	v_add_f32_e32 v0, 1.0, v0
	v_rcp_f32_e32 v23, v0
	v_pk_mul_f32 v[12:13], v[12:13], v[16:17]
	v_pk_mul_f32 v[14:15], v[22:23], v[20:21]
	s_nop 0
	v_pk_mul_f32 v[10:11], v[10:11], v[14:15]
	v_lshlrev_b32_e32 v14, 16, v19
	v_mul_f32_e32 v0, 0xbfb8aa3b, v14
	v_exp_f32_e32 v0, v0
	v_and_b32_e32 v15, 0xffff0000, v19
	v_cvt_pk_bf16_f32 v10, v10, v11
	v_add_f32_e32 v0, 1.0, v0
	v_rcp_f32_e32 v18, v0
	v_mul_f32_e32 v0, 0xbfb8aa3b, v15
	v_exp_f32_e32 v0, v0
	s_nop 0
	v_add_f32_e32 v0, 1.0, v0
	v_rcp_f32_e32 v19, v0
	s_nop 0
	v_pk_mul_f32 v[14:15], v[18:19], v[14:15]
	s_nop 0
	v_pk_mul_f32 v[12:13], v[12:13], v[14:15]
	s_nop 0
	v_cvt_pk_bf16_f32 v11, v12, v13
	global_store_dwordx2 v[28:29], v[10:11], off offset:160
	v_mov_b32_e32 v14, v190
	v_mov_b32_e32 v15, v191
	v_lshlrev_b32_e32 v16, 16, v14
	v_mov_b32_e32 v10, v228
	v_mov_b32_e32 v11, v229
	v_mov_b32_e32 v12, v230
	v_mov_b32_e32 v13, v231
	v_mul_f32_e32 v0, 0xbfb8aa3b, v16
	v_exp_f32_e32 v0, v0
	v_and_b32_e32 v17, 0xffff0000, v14
	v_add_f32_e32 v0, 1.0, v0
	v_rcp_f32_e32 v18, v0
	v_mul_f32_e32 v0, 0xbfb8aa3b, v17
	v_exp_f32_e32 v0, v0
	v_pk_mul_f32 v[6:7], v[6:7], v[10:11]
	v_add_f32_e32 v0, 1.0, v0
	v_rcp_f32_e32 v19, v0
	v_pk_mul_f32 v[8:9], v[8:9], v[12:13]
	v_pk_mul_f32 v[10:11], v[18:19], v[16:17]
	s_nop 0
	v_pk_mul_f32 v[6:7], v[6:7], v[10:11]
	v_lshlrev_b32_e32 v10, 16, v15
	v_mul_f32_e32 v0, 0xbfb8aa3b, v10
	v_exp_f32_e32 v0, v0
	v_and_b32_e32 v11, 0xffff0000, v15
	v_cvt_pk_bf16_f32 v6, v6, v7
	v_add_f32_e32 v0, 1.0, v0
	v_rcp_f32_e32 v14, v0
	v_mul_f32_e32 v0, 0xbfb8aa3b, v11
	v_exp_f32_e32 v0, v0
	s_nop 0
	v_add_f32_e32 v0, 1.0, v0
	v_rcp_f32_e32 v15, v0
	s_nop 0
	v_pk_mul_f32 v[10:11], v[14:15], v[10:11]
	s_nop 0
	v_pk_mul_f32 v[8:9], v[8:9], v[10:11]
	s_nop 0
	v_cvt_pk_bf16_f32 v7, v8, v9
	global_store_dwordx2 v[28:29], v[6:7], off offset:192
	v_mov_b32_e32 v10, v192
	v_mov_b32_e32 v11, v193
	v_lshlrev_b32_e32 v12, 16, v10
	v_mov_b32_e32 v6, v232
	v_mov_b32_e32 v7, v233
	v_mov_b32_e32 v8, v234
	v_mov_b32_e32 v9, v235
	v_mul_f32_e32 v0, 0xbfb8aa3b, v12
	v_exp_f32_e32 v0, v0
	v_and_b32_e32 v13, 0xffff0000, v10
	v_add_f32_e32 v0, 1.0, v0
	v_rcp_f32_e32 v14, v0
	v_mul_f32_e32 v0, 0xbfb8aa3b, v13
	v_exp_f32_e32 v0, v0
	v_pk_mul_f32 v[2:3], v[2:3], v[6:7]
	v_add_f32_e32 v0, 1.0, v0
	v_rcp_f32_e32 v15, v0
	v_pk_mul_f32 v[4:5], v[4:5], v[8:9]
	v_pk_mul_f32 v[6:7], v[14:15], v[12:13]
	s_nop 0
	v_pk_mul_f32 v[2:3], v[2:3], v[6:7]
	v_lshlrev_b32_e32 v6, 16, v11
	v_mul_f32_e32 v0, 0xbfb8aa3b, v6
	v_exp_f32_e32 v0, v0
	v_and_b32_e32 v7, 0xffff0000, v11
	v_cvt_pk_bf16_f32 v2, v2, v3
	v_add_f32_e32 v0, 1.0, v0
	v_rcp_f32_e32 v10, v0
	v_mul_f32_e32 v0, 0xbfb8aa3b, v7
	v_exp_f32_e32 v0, v0
	s_nop 0
	v_add_f32_e32 v0, 1.0, v0
	v_rcp_f32_e32 v11, v0
	s_nop 0
	v_pk_mul_f32 v[6:7], v[10:11], v[6:7]
	s_nop 0
	v_pk_mul_f32 v[4:5], v[4:5], v[6:7]
	s_nop 0
	v_cvt_pk_bf16_f32 v3, v4, v5
	global_store_dwordx2 v[28:29], v[2:3], off offset:224

; __device__ __forceinline__ float lo_bf(unsigned u) { return __uint_as_float(u << 16); }
; __device__ __forceinline__ float hi_bf(unsigned u) { return __uint_as_float(u & 0xffff0000u); }
; template <class Epi>
; __device__ __forceinline__ void gemm_tile(const u16* __restrict__ A, int lda, const u16* __restrict__ Wt, int K,
;                                           int m0, int n0, char* sbase, const Epi& epi) {
;     ...
; #pragma unroll
;   for (int ai = 0; ai < 2; ++ai)
; #pragma unroll
;     for (int bj = 0; bj < 2; ++bj)
; #pragma unroll
;       for (int m = 0; m < 4; ++m)
; #pragma unroll
;         for (int n = 0; n < 2; ++n)
;           epi(m0 + ai * 128 + wr * 64 + m * 16 + fr, n0 + bj * 128 + wc * 32 + n * 16 + fq * 4, acc[ai][bj][m][n]);
;   __device__ __forceinline__ void operator()(int m, int n, f32x4 v) const {
;     float4 g = *(const float4*)(gate + (size_t)modrow(m) * 6144 + n);
;     u16* r = p->Rb + (size_t)m * 1024 + n;
;     f32x4 o;
;     if (src_f32) {
;       float4 a = *(const float4*)(inrow(*p, m) + n);
;       o[0] = a.x; o[1] = a.y; o[2] = a.z; o[3] = a.w;
;     } else {
;       uint2 a = *(const uint2*)r;
;       o[0] = lo_bf(a.x); o[1] = hi_bf(a.x); o[2] = lo_bf(a.y); o[3] = hi_bf(a.y);
;     }
;     o[0] += mul * g.x * v[0]; o[1] += mul * g.y * v[1]; o[2] += mul * g.z * v[2]; o[3] += mul * g.w * v[3];
;     store4bf(r, o);
;   }
.LBB0_1622:
	s_or_b64 exec, exec, s[0:1]
	s_lshl_b32 s14, s46, 8
	v_or_b32_e32 v0, s14, v147
	v_lshlrev_b32_e32 v133, 5, v145
	v_lshlrev_b32_e32 v134, 2, v146
	s_mov_b64 s[0:1], -1
	s_andn2_b64 vcc, exec, s[10:11]
	v_add_u32_e32 v132, v0, v148
	v_or3_b32 v162, v133, v134, s34
	v_mov_b32_e32 v252, 0x358637bd
	s_cbranch_vccnz .LBB0_1624
	v_min_i32_e32 v0, 0x10000, v132
	v_ashrrev_i32_e32 v0, 11, v0
	v_mul_hi_i32_i24_e32 v135, 0x6000, v0
	v_mul_i32_i24_e32 v134, 0x6000, v0
	v_ashrrev_i32_e32 v133, 31, v132
	v_cmp_gt_i32_e32 vcc, s74, v132
	v_add_u32_e32 v0, 0xffff0000, v132
	v_readlane_b32 s16, v254, 10
	v_readlane_b32 s0, v254, 8
	v_lshlrev_b64 v[136:137], 11, v[132:133]
	v_cndmask_b32_e32 v138, v0, v132, vcc
	v_lshl_add_u64 v[134:135], s[6:7], 0, v[134:135]
	v_lshlrev_b32_e32 v0, 2, v162
	v_readlane_b32 s17, v254, 11
	v_readlane_b32 s1, v254, 9
	v_cndmask_b32_e32 v139, 0, v133, vcc
	v_lshl_add_u64 v[140:141], v[134:135], 0, v[0:1]
	v_lshl_add_u64 v[134:135], s[38:39], 0, v[136:137]
	v_lshlrev_b32_e32 v136, 1, v162
	v_mov_b32_e32 v137, v1
	v_mov_b32_e32 v133, s17
	v_mov_b32_e32 v163, s1
	v_mov_b32_e32 v164, s16
	v_mov_b32_e32 v165, s0
	v_lshlrev_b64 v[142:143], 12, v[138:139]
	v_lshl_add_u64 v[138:139], v[134:135], 0, v[136:137]
	v_cndmask_b32_e32 v135, v133, v163, vcc
	v_cndmask_b32_e32 v134, v164, v165, vcc
	v_lshl_add_u64 v[134:135], v[134:135], 0, v[142:143]
	v_lshl_add_u64 v[142:143], v[134:135], 0, v[0:1]
	v_mov_b32_e32 v202, v142
	v_mov_b32_e32 v203, v143
	v_mov_b32_e32 v174, 0x0
	v_mov_b32_e32 v175, 0
	v_lshl_add_u64 v[174:175], v[142:143], 0, v[174:175]
	global_load_dwordx4 v[176:179], v[174:175], off
	global_load_dwordx4 v[180:183], v[174:175], off offset:64
	global_load_dwordx4 v[220:223], v[174:175], off offset:512
	global_load_dwordx4 v[224:227], v[174:175], off offset:576
	v_mov_b32_e32 v174, 0x10000
	v_mov_b32_e32 v175, 0
	v_lshl_add_u64 v[174:175], v[142:143], 0, v[174:175]
	global_load_dwordx4 v[184:187], v[174:175], off
	global_load_dwordx4 v[188:191], v[174:175], off offset:64
	global_load_dwordx4 v[228:231], v[174:175], off offset:512
	global_load_dwordx4 v[232:235], v[174:175], off offset:576
	v_mov_b32_e32 v174, 0x20000
	v_mov_b32_e32 v175, 0
	v_lshl_add_u64 v[174:175], v[142:143], 0, v[174:175]
	global_load_dwordx4 v[192:195], v[174:175], off
	global_load_dwordx4 v[208:211], v[174:175], off offset:64
	global_load_dwordx4 v[236:239], v[174:175], off offset:512
	global_load_dwordx4 v[240:243], v[174:175], off offset:576
	v_mov_b32_e32 v174, 0x30000
	v_mov_b32_e32 v175, 0
	v_lshl_add_u64 v[174:175], v[142:143], 0, v[174:175]
	global_load_dwordx4 v[212:215], v[174:175], off
	global_load_dwordx4 v[216:219], v[174:175], off offset:64
	global_load_dwordx4 v[244:247], v[174:175], off offset:512
	global_load_dwordx4 v[248:251], v[174:175], off offset:576
	global_load_dwordx4 v[144:147], v[140:141], off
	s_mov_b32 s0, 0xff80
	s_waitcnt vmcnt(0)
	v_mov_b32_e32 v148, v176
	v_mov_b32_e32 v149, v177
	v_mov_b32_e32 v150, v178
	v_mov_b32_e32 v151, v179
	v_pk_mul_f32 v[134:135], v[130:131], v[144:145]
	v_pk_mul_f32 v[144:145], v[130:131], v[146:147]
	v_pk_fma_f32 v[134:135], v[126:127], v[134:135], v[148:149]
	v_pk_fma_f32 v[144:145], v[128:129], v[144:145], v[150:151]
	v_cvt_pk_bf16_f32 v134, v134, v135
	v_cvt_pk_bf16_f32 v135, v144, v145
	global_store_dwordx2 v[138:139], v[134:135], off
	global_load_dwordx4 v[144:147], v[140:141], off offset:64
	s_waitcnt vmcnt(0)
	v_mov_b32_e32 v148, v180
	v_mov_b32_e32 v149, v181
	v_mov_b32_e32 v150, v182
	v_mov_b32_e32 v151, v183
	v_pk_mul_f32 v[134:135], v[130:131], v[144:145]
	v_pk_mul_f32 v[144:145], v[130:131], v[146:147]
	s_waitcnt vmcnt(0)
	v_pk_fma_f32 v[134:135], v[122:123], v[134:135], v[148:149]
	v_pk_fma_f32 v[144:145], v[124:125], v[144:145], v[150:151]
	v_cvt_pk_bf16_f32 v134, v134, v135
	v_cvt_pk_bf16_f32 v135, v144, v145
	global_store_dwordx2 v[138:139], v[134:135], off offset:32
	v_or_b32_e32 v134, 16, v132
	v_min_i32_e32 v135, 0x10000, v134
	v_ashrrev_i32_e32 v135, 11, v135
	v_mul_hi_i32_i24_e32 v145, 0x6000, v135
	v_mul_i32_i24_e32 v144, 0x6000, v135
	v_ashrrev_i32_e32 v135, 31, v134
	v_cmp_gt_i32_e32 vcc, s74, v134
	v_add_u32_e32 v146, 0xffff0010, v132
	v_lshlrev_b64 v[148:149], 11, v[134:135]
	v_cndmask_b32_e32 v135, 0, v135, vcc
	v_cndmask_b32_e32 v134, v146, v134, vcc
	v_lshl_add_u64 v[144:145], s[6:7], 0, v[144:145]
	v_lshlrev_b64 v[134:135], 12, v[134:135]
	v_lshl_add_u64 v[146:147], v[144:145], 0, v[0:1]
	v_lshl_add_u64 v[144:145], s[38:39], 0, v[148:149]
	v_cndmask_b32_e32 v149, v133, v163, vcc
	v_cndmask_b32_e32 v148, v164, v165, vcc
	v_lshl_add_u64 v[134:135], v[148:149], 0, v[134:135]
	v_lshl_add_u64 v[148:149], v[134:135], 0, v[0:1]
	global_load_dwordx4 v[150:153], v[146:147], off
	v_lshl_add_u64 v[144:145], v[144:145], 0, v[136:137]
	s_waitcnt vmcnt(0)
	v_mov_b32_e32 v154, v184
	v_mov_b32_e32 v155, v185
	v_mov_b32_e32 v156, v186
	v_mov_b32_e32 v157, v187
	v_pk_mul_f32 v[134:135], v[130:131], v[150:151]
	v_pk_mul_f32 v[150:151], v[130:131], v[152:153]
	s_waitcnt vmcnt(0)
	v_pk_fma_f32 v[134:135], v[118:119], v[134:135], v[154:155]
	v_pk_fma_f32 v[150:151], v[120:121], v[150:151], v[156:157]
	v_cvt_pk_bf16_f32 v134, v134, v135
	v_cvt_pk_bf16_f32 v135, v150, v151
	global_store_dwordx2 v[144:145], v[134:135], off
	global_load_dwordx4 v[150:153], v[146:147], off offset:64
	s_waitcnt vmcnt(0)
	v_mov_b32_e32 v154, v188
	v_mov_b32_e32 v155, v189
	v_mov_b32_e32 v156, v190
	v_mov_b32_e32 v157, v191
	v_pk_mul_f32 v[134:135], v[130:131], v[150:151]
	v_pk_mul_f32 v[150:151], v[130:131], v[152:153]
	s_waitcnt vmcnt(0)
; __device__ __forceinline__ float lo_bf(unsigned u) { return __uint_as_float(u << 16); }
; __device__ __forceinline__ float hi_bf(unsigned u) { return __uint_as_float(u & 0xffff0000u); }
; template <class Epi>
; __device__ __forceinline__ void gemm_tile(const u16* __restrict__ A, int lda, const u16* __restrict__ Wt, int K,
;                                           int m0, int n0, char* sbase, const Epi& epi) {
;     ...
; #pragma unroll
;   for (int ai = 0; ai < 2; ++ai)
; #pragma unroll
;     for (int bj = 0; bj < 2; ++bj)
; #pragma unroll
;       for (int m = 0; m < 4; ++m)
; #pragma unroll
;         for (int n = 0; n < 2; ++n)
;           epi(m0 + ai * 128 + wr * 64 + m * 16 + fr, n0 + bj * 128 + wc * 32 + n * 16 + fq * 4, acc[ai][bj][m][n]);
;   __device__ __forceinline__ void operator()(int m, int n, f32x4 v) const {
;     float4 g = *(const float4*)(gate + (size_t)modrow(m) * 6144 + n);
;     u16* r = p->Rb + (size_t)m * 1024 + n;
;     f32x4 o;
;     if (src_f32) {
;       float4 a = *(const float4*)(inrow(*p, m) + n);
;       o[0] = a.x; o[1] = a.y; o[2] = a.z; o[3] = a.w;
;     } else {
;       uint2 a = *(const uint2*)r;
;       o[0] = lo_bf(a.x); o[1] = hi_bf(a.x); o[2] = lo_bf(a.y); o[3] = hi_bf(a.y);
;     }
;     o[0] += mul * g.x * v[0]; o[1] += mul * g.y * v[1]; o[2] += mul * g.z * v[2]; o[3] += mul * g.w * v[3];
;     store4bf(r, o);
;   }
	v_pk_fma_f32 v[134:135], v[114:115], v[134:135], v[154:155]
	v_pk_fma_f32 v[150:151], v[116:117], v[150:151], v[156:157]
	v_cvt_pk_bf16_f32 v134, v134, v135
	v_cvt_pk_bf16_f32 v135, v150, v151
	global_store_dwordx2 v[144:145], v[134:135], off offset:32
	v_or_b32_e32 v134, 32, v132
	v_min_i32_e32 v135, 0x10000, v134
	v_ashrrev_i32_e32 v135, 11, v135
	v_mul_hi_i32_i24_e32 v151, 0x6000, v135
	v_mul_i32_i24_e32 v150, 0x6000, v135
	v_ashrrev_i32_e32 v135, 31, v134
	v_cmp_gt_i32_e32 vcc, s74, v134
	v_add_u32_e32 v152, 0xffff0020, v132
	v_lshlrev_b64 v[154:155], 11, v[134:135]
	v_cndmask_b32_e32 v135, 0, v135, vcc
	v_cndmask_b32_e32 v134, v152, v134, vcc
	v_lshl_add_u64 v[150:151], s[6:7], 0, v[150:151]
	v_lshlrev_b64 v[134:135], 12, v[134:135]
	v_lshl_add_u64 v[152:153], v[150:151], 0, v[0:1]
	v_lshl_add_u64 v[150:151], s[38:39], 0, v[154:155]
	v_cndmask_b32_e32 v155, v133, v163, vcc
	v_cndmask_b32_e32 v154, v164, v165, vcc
	v_lshl_add_u64 v[134:135], v[154:155], 0, v[134:135]
	v_lshl_add_u64 v[154:155], v[134:135], 0, v[0:1]
	global_load_dwordx4 v[156:159], v[152:153], off
	v_lshl_add_u64 v[150:151], v[150:151], 0, v[136:137]
	s_waitcnt vmcnt(0)
	v_mov_b32_e32 v166, v192
	v_mov_b32_e32 v167, v193
	v_mov_b32_e32 v168, v194
	v_mov_b32_e32 v169, v195
	v_pk_mul_f32 v[134:135], v[130:131], v[156:157]
	v_pk_mul_f32 v[156:157], v[130:131], v[158:159]
	s_waitcnt vmcnt(0)
	v_pk_fma_f32 v[134:135], v[110:111], v[134:135], v[166:167]
	v_pk_fma_f32 v[156:157], v[112:113], v[156:157], v[168:169]
	v_cvt_pk_bf16_f32 v134, v134, v135
	v_cvt_pk_bf16_f32 v135, v156, v157
	global_store_dwordx2 v[150:151], v[134:135], off
	global_load_dwordx4 v[156:159], v[152:153], off offset:64
	s_waitcnt vmcnt(0)
	v_mov_b32_e32 v166, v208
	v_mov_b32_e32 v167, v209
	v_mov_b32_e32 v168, v210
	v_mov_b32_e32 v169, v211
	v_pk_mul_f32 v[134:135], v[130:131], v[156:157]
	v_pk_mul_f32 v[156:157], v[130:131], v[158:159]
	s_waitcnt vmcnt(0)
	v_pk_fma_f32 v[134:135], v[106:107], v[134:135], v[166:167]
	v_pk_fma_f32 v[156:157], v[108:109], v[156:157], v[168:169]
	v_cvt_pk_bf16_f32 v134, v134, v135
	v_cvt_pk_bf16_f32 v135, v156, v157
	global_store_dwordx2 v[150:151], v[134:135], off offset:32
	v_or_b32_e32 v134, 48, v132
	v_min_i32_e32 v135, 0x10000, v134
	v_ashrrev_i32_e32 v135, 11, v135
	v_mul_hi_i32_i24_e32 v157, 0x6000, v135
	v_mul_i32_i24_e32 v156, 0x6000, v135
	v_ashrrev_i32_e32 v135, 31, v134
	v_cmp_gt_i32_e32 vcc, s74, v134
	v_add_u32_e32 v158, 0xffff0030, v132
	v_lshlrev_b64 v[160:161], 11, v[134:135]
	v_cndmask_b32_e32 v135, 0, v135, vcc
	v_cndmask_b32_e32 v134, v158, v134, vcc
	v_lshl_add_u64 v[156:157], s[6:7], 0, v[156:157]
	v_lshlrev_b64 v[134:135], 12, v[134:135]
	v_lshl_add_u64 v[158:159], v[156:157], 0, v[0:1]
	v_lshl_add_u64 v[156:157], s[38:39], 0, v[160:161]
	v_cndmask_b32_e32 v161, v133, v163, vcc
	v_cndmask_b32_e32 v160, v164, v165, vcc
	v_lshl_add_u64 v[134:135], v[160:161], 0, v[134:135]
	v_lshl_add_u64 v[160:161], v[134:135], 0, v[0:1]
	global_load_dwordx4 v[166:169], v[158:159], off
	v_lshl_add_u64 v[156:157], v[156:157], 0, v[136:137]
	v_cmp_gt_i32_e32 vcc, s0, v132
	s_mov_b32 s0, 0xff70
	s_waitcnt vmcnt(0)
	v_mov_b32_e32 v170, v212
	v_mov_b32_e32 v171, v213
	v_mov_b32_e32 v172, v214
	v_mov_b32_e32 v173, v215
	v_pk_mul_f32 v[134:135], v[130:131], v[166:167]
	v_pk_mul_f32 v[166:167], v[130:131], v[168:169]
	s_waitcnt vmcnt(0)
	v_pk_fma_f32 v[134:135], v[102:103], v[134:135], v[170:171]
	v_pk_fma_f32 v[166:167], v[104:105], v[166:167], v[172:173]
	v_cvt_pk_bf16_f32 v134, v134, v135
	v_cvt_pk_bf16_f32 v135, v166, v167
	global_store_dwordx2 v[156:157], v[134:135], off
	global_load_dwordx4 v[166:169], v[158:159], off offset:64
	s_waitcnt vmcnt(0)
	v_mov_b32_e32 v170, v216
	v_mov_b32_e32 v171, v217
	v_mov_b32_e32 v172, v218
	v_mov_b32_e32 v173, v219
	v_pk_mul_f32 v[134:135], v[130:131], v[166:167]
	v_pk_mul_f32 v[166:167], v[130:131], v[168:169]
	s_waitcnt vmcnt(0)
	v_pk_fma_f32 v[134:135], v[98:99], v[134:135], v[170:171]
	v_pk_fma_f32 v[166:167], v[100:101], v[166:167], v[172:173]
	v_cvt_pk_bf16_f32 v134, v134, v135
	v_cvt_pk_bf16_f32 v135, v166, v167
	global_store_dwordx2 v[156:157], v[134:135], off offset:32
	global_load_dwordx4 v[166:169], v[140:141], off offset:512
	s_waitcnt vmcnt(0)
	v_mov_b32_e32 v170, v220
	v_mov_b32_e32 v171, v221
	v_mov_b32_e32 v172, v222
	v_mov_b32_e32 v173, v223
	v_pk_mul_f32 v[134:135], v[130:131], v[166:167]
	v_pk_mul_f32 v[166:167], v[130:131], v[168:169]
	s_waitcnt vmcnt(0)
	v_pk_fma_f32 v[134:135], v[94:95], v[134:135], v[170:171]
	v_pk_fma_f32 v[166:167], v[96:97], v[166:167], v[172:173]
	v_cvt_pk_bf16_f32 v134, v134, v135
	v_cvt_pk_bf16_f32 v135, v166, v167
	global_store_dwordx2 v[138:139], v[134:135], off offset:256
	global_load_dwordx4 v[166:169], v[140:141], off offset:576
	s_nop 0
	s_waitcnt vmcnt(0)
	v_mov_b32_e32 v140, v224
	v_mov_b32_e32 v141, v225
	v_mov_b32_e32 v142, v226
	v_mov_b32_e32 v143, v227
	v_pk_mul_f32 v[134:135], v[130:131], v[166:167]
	s_waitcnt vmcnt(0)
	v_pk_fma_f32 v[134:135], v[90:91], v[134:135], v[140:141]
	v_pk_mul_f32 v[140:141], v[130:131], v[168:169]
	v_cvt_pk_bf16_f32 v134, v134, v135
	v_pk_fma_f32 v[140:141], v[92:93], v[140:141], v[142:143]
	s_nop 0
	v_cvt_pk_bf16_f32 v135, v140, v141
	global_store_dwordx2 v[138:139], v[134:135], off offset:288
	global_load_dwordx4 v[138:141], v[146:147], off offset:512
	s_nop 0
	s_waitcnt vmcnt(0)
	v_mov_b32_e32 v166, v228
	v_mov_b32_e32 v167, v229
	v_mov_b32_e32 v168, v230
	v_mov_b32_e32 v169, v231
	v_pk_mul_f32 v[134:135], v[130:131], v[138:139]
	v_pk_mul_f32 v[138:139], v[130:131], v[140:141]
	s_waitcnt vmcnt(0)
; __device__ __forceinline__ float lo_bf(unsigned u) { return __uint_as_float(u << 16); }
; __device__ __forceinline__ float hi_bf(unsigned u) { return __uint_as_float(u & 0xffff0000u); }
; template <class Epi>
; __device__ __forceinline__ void gemm_tile(const u16* __restrict__ A, int lda, const u16* __restrict__ Wt, int K,
;                                           int m0, int n0, char* sbase, const Epi& epi) {
;     ...
; #pragma unroll
;   for (int ai = 0; ai < 2; ++ai)
; #pragma unroll
;     for (int bj = 0; bj < 2; ++bj)
; #pragma unroll
;       for (int m = 0; m < 4; ++m)
; #pragma unroll
;         for (int n = 0; n < 2; ++n)
;           epi(m0 + ai * 128 + wr * 64 + m * 16 + fr, n0 + bj * 128 + wc * 32 + n * 16 + fq * 4, acc[ai][bj][m][n]);
;   __device__ __forceinline__ void operator()(int m, int n, f32x4 v) const {
;     float4 g = *(const float4*)(gate + (size_t)modrow(m) * 6144 + n);
;     u16* r = p->Rb + (size_t)m * 1024 + n;
;     f32x4 o;
;     if (src_f32) {
;       float4 a = *(const float4*)(inrow(*p, m) + n);
;       o[0] = a.x; o[1] = a.y; o[2] = a.z; o[3] = a.w;
;     } else {
;       uint2 a = *(const uint2*)r;
;       o[0] = lo_bf(a.x); o[1] = hi_bf(a.x); o[2] = lo_bf(a.y); o[3] = hi_bf(a.y);
;     }
;     o[0] += mul * g.x * v[0]; o[1] += mul * g.y * v[1]; o[2] += mul * g.z * v[2]; o[3] += mul * g.w * v[3];
;     store4bf(r, o);
;   }
	v_pk_fma_f32 v[134:135], v[86:87], v[134:135], v[166:167]
	v_pk_fma_f32 v[138:139], v[88:89], v[138:139], v[168:169]
	v_cvt_pk_bf16_f32 v134, v134, v135
	v_cvt_pk_bf16_f32 v135, v138, v139
	global_store_dwordx2 v[144:145], v[134:135], off offset:256
	global_load_dwordx4 v[138:141], v[146:147], off offset:576
	s_nop 0
	s_waitcnt vmcnt(0)
	v_mov_b32_e32 v146, v232
	v_mov_b32_e32 v147, v233
	v_mov_b32_e32 v148, v234
	v_mov_b32_e32 v149, v235
	v_pk_mul_f32 v[134:135], v[130:131], v[138:139]
	v_pk_mul_f32 v[138:139], v[130:131], v[140:141]
	s_waitcnt vmcnt(0)
	v_pk_fma_f32 v[134:135], v[82:83], v[134:135], v[146:147]
	v_pk_fma_f32 v[138:139], v[84:85], v[138:139], v[148:149]
	v_cvt_pk_bf16_f32 v134, v134, v135
	v_cvt_pk_bf16_f32 v135, v138, v139
	global_store_dwordx2 v[144:145], v[134:135], off offset:288
	global_load_dwordx4 v[138:141], v[152:153], off offset:512
	s_nop 0
	s_waitcnt vmcnt(0)
	v_mov_b32_e32 v142, v236
	v_mov_b32_e32 v143, v237
	v_mov_b32_e32 v144, v238
	v_mov_b32_e32 v145, v239
	v_pk_mul_f32 v[134:135], v[130:131], v[138:139]
	v_pk_mul_f32 v[138:139], v[130:131], v[140:141]
	s_waitcnt vmcnt(0)
	v_pk_fma_f32 v[134:135], v[78:79], v[134:135], v[142:143]
	v_pk_fma_f32 v[138:139], v[80:81], v[138:139], v[144:145]
	v_cvt_pk_bf16_f32 v134, v134, v135
	v_cvt_pk_bf16_f32 v135, v138, v139
	global_store_dwordx2 v[150:151], v[134:135], off offset:256
	global_load_dwordx4 v[138:141], v[152:153], off offset:576
	s_waitcnt vmcnt(0)
	v_mov_b32_e32 v142, v240
	v_mov_b32_e32 v143, v241
	v_mov_b32_e32 v144, v242
	v_mov_b32_e32 v145, v243
	v_pk_mul_f32 v[134:135], v[130:131], v[138:139]
	v_pk_mul_f32 v[138:139], v[130:131], v[140:141]
	s_waitcnt vmcnt(0)
	v_pk_fma_f32 v[134:135], v[74:75], v[134:135], v[142:143]
	v_pk_fma_f32 v[138:139], v[76:77], v[138:139], v[144:145]
	v_cvt_pk_bf16_f32 v134, v134, v135
	v_cvt_pk_bf16_f32 v135, v138, v139
	global_store_dwordx2 v[150:151], v[134:135], off offset:288
	global_load_dwordx4 v[138:141], v[158:159], off offset:512
	s_waitcnt vmcnt(0)
	v_mov_b32_e32 v142, v244
	v_mov_b32_e32 v143, v245
	v_mov_b32_e32 v144, v246
	v_mov_b32_e32 v145, v247
	v_pk_mul_f32 v[134:135], v[130:131], v[138:139]
	v_pk_mul_f32 v[138:139], v[130:131], v[140:141]
	s_waitcnt vmcnt(0)
	v_pk_fma_f32 v[134:135], v[70:71], v[134:135], v[142:143]
	v_pk_fma_f32 v[138:139], v[72:73], v[138:139], v[144:145]
	v_cvt_pk_bf16_f32 v134, v134, v135
	v_cvt_pk_bf16_f32 v135, v138, v139
	global_store_dwordx2 v[156:157], v[134:135], off offset:256
	global_load_dwordx4 v[138:141], v[158:159], off offset:576
	s_waitcnt vmcnt(0)
	v_mov_b32_e32 v142, v248
	v_mov_b32_e32 v143, v249
	v_mov_b32_e32 v144, v250
	v_mov_b32_e32 v145, v251
	v_pk_mul_f32 v[134:135], v[130:131], v[138:139]
	v_pk_mul_f32 v[138:139], v[130:131], v[140:141]
	s_waitcnt vmcnt(0)
	v_pk_fma_f32 v[134:135], v[66:67], v[134:135], v[142:143]
	v_pk_fma_f32 v[138:139], v[68:69], v[138:139], v[144:145]
	v_cvt_pk_bf16_f32 v134, v134, v135
	v_cvt_pk_bf16_f32 v135, v138, v139
	global_store_dwordx2 v[156:157], v[134:135], off offset:288
	v_add_u32_e32 v134, 0x80, v132
	v_min_i32_e32 v135, 0x10000, v134
	v_ashrrev_i32_e32 v135, 11, v135
	v_mul_hi_i32_i24_e32 v139, 0x6000, v135
	v_mul_i32_i24_e32 v138, 0x6000, v135
	v_ashrrev_i32_e32 v135, 31, v134
	v_add_u32_e32 v140, 0xffff0080, v132
	v_lshlrev_b64 v[142:143], 11, v[134:135]
	v_cndmask_b32_e32 v135, 0, v135, vcc
	v_cndmask_b32_e32 v134, v140, v134, vcc
	v_lshl_add_u64 v[138:139], s[6:7], 0, v[138:139]
	v_lshlrev_b64 v[134:135], 12, v[134:135]
	v_lshl_add_u64 v[140:141], v[138:139], 0, v[0:1]
	v_lshl_add_u64 v[138:139], s[38:39], 0, v[142:143]
	v_cndmask_b32_e32 v143, v133, v163, vcc
	v_cndmask_b32_e32 v142, v164, v165, vcc
	v_lshl_add_u64 v[134:135], v[142:143], 0, v[134:135]
	v_lshl_add_u64 v[142:143], v[134:135], 0, v[0:1]
	v_mov_b32_e32 v174, 0x80000
	v_mov_b32_e32 v175, 0
	v_lshl_add_u64 v[174:175], v[202:203], 0, v[174:175]
	global_load_dwordx4 v[176:179], v[174:175], off
	global_load_dwordx4 v[180:183], v[174:175], off offset:64
	global_load_dwordx4 v[220:223], v[174:175], off offset:512
	global_load_dwordx4 v[224:227], v[174:175], off offset:576
	v_mov_b32_e32 v174, 0x90000
	v_mov_b32_e32 v175, 0
	v_lshl_add_u64 v[174:175], v[202:203], 0, v[174:175]
	global_load_dwordx4 v[184:187], v[174:175], off
	global_load_dwordx4 v[188:191], v[174:175], off offset:64
	global_load_dwordx4 v[228:231], v[174:175], off offset:512
	global_load_dwordx4 v[232:235], v[174:175], off offset:576
	v_mov_b32_e32 v174, 0xa0000
	v_mov_b32_e32 v175, 0
	v_lshl_add_u64 v[174:175], v[202:203], 0, v[174:175]
	global_load_dwordx4 v[192:195], v[174:175], off
	global_load_dwordx4 v[208:211], v[174:175], off offset:64
	global_load_dwordx4 v[236:239], v[174:175], off offset:512
	global_load_dwordx4 v[240:243], v[174:175], off offset:576
	v_mov_b32_e32 v174, 0xb0000
	v_mov_b32_e32 v175, 0
	v_lshl_add_u64 v[174:175], v[202:203], 0, v[174:175]
	global_load_dwordx4 v[212:215], v[174:175], off
	global_load_dwordx4 v[216:219], v[174:175], off offset:64
	global_load_dwordx4 v[244:247], v[174:175], off offset:512
	global_load_dwordx4 v[248:251], v[174:175], off offset:576
	global_load_dwordx4 v[144:147], v[140:141], off
	v_lshl_add_u64 v[138:139], v[138:139], 0, v[136:137]
	v_cmp_gt_i32_e32 vcc, s0, v132
	s_mov_b32 s0, 0xff60
	s_waitcnt vmcnt(0)
	v_mov_b32_e32 v148, v176
	v_mov_b32_e32 v149, v177
	v_mov_b32_e32 v150, v178
	v_mov_b32_e32 v151, v179
	v_pk_mul_f32 v[134:135], v[130:131], v[144:145]
	v_pk_mul_f32 v[144:145], v[130:131], v[146:147]
	s_waitcnt vmcnt(0)
; __device__ __forceinline__ float lo_bf(unsigned u) { return __uint_as_float(u << 16); }
; __device__ __forceinline__ float hi_bf(unsigned u) { return __uint_as_float(u & 0xffff0000u); }
; template <class Epi>
; __device__ __forceinline__ void gemm_tile(const u16* __restrict__ A, int lda, const u16* __restrict__ Wt, int K,
;                                           int m0, int n0, char* sbase, const Epi& epi) {
;     ...
; #pragma unroll
;   for (int ai = 0; ai < 2; ++ai)
; #pragma unroll
;     for (int bj = 0; bj < 2; ++bj)
; #pragma unroll
;       for (int m = 0; m < 4; ++m)
; #pragma unroll
;         for (int n = 0; n < 2; ++n)
;           epi(m0 + ai * 128 + wr * 64 + m * 16 + fr, n0 + bj * 128 + wc * 32 + n * 16 + fq * 4, acc[ai][bj][m][n]);
;   __device__ __forceinline__ void operator()(int m, int n, f32x4 v) const {
;     float4 g = *(const float4*)(gate + (size_t)modrow(m) * 6144 + n);
;     u16* r = p->Rb + (size_t)m * 1024 + n;
;     f32x4 o;
;     if (src_f32) {
;       float4 a = *(const float4*)(inrow(*p, m) + n);
;       o[0] = a.x; o[1] = a.y; o[2] = a.z; o[3] = a.w;
;     } else {
;       uint2 a = *(const uint2*)r;
;       o[0] = lo_bf(a.x); o[1] = hi_bf(a.x); o[2] = lo_bf(a.y); o[3] = hi_bf(a.y);
;     }
;     o[0] += mul * g.x * v[0]; o[1] += mul * g.y * v[1]; o[2] += mul * g.z * v[2]; o[3] += mul * g.w * v[3];
;     store4bf(r, o);
;   }
	v_pk_fma_f32 v[134:135], v[62:63], v[134:135], v[148:149]
	v_pk_fma_f32 v[144:145], v[64:65], v[144:145], v[150:151]
	v_cvt_pk_bf16_f32 v134, v134, v135
	v_cvt_pk_bf16_f32 v135, v144, v145
	global_store_dwordx2 v[138:139], v[134:135], off
	global_load_dwordx4 v[144:147], v[140:141], off offset:64
	s_waitcnt vmcnt(0)
	v_mov_b32_e32 v148, v180
	v_mov_b32_e32 v149, v181
	v_mov_b32_e32 v150, v182
	v_mov_b32_e32 v151, v183
	v_pk_mul_f32 v[134:135], v[130:131], v[144:145]
	v_pk_mul_f32 v[144:145], v[130:131], v[146:147]
	s_waitcnt vmcnt(0)
	v_pk_fma_f32 v[134:135], v[58:59], v[134:135], v[148:149]
	v_pk_fma_f32 v[144:145], v[60:61], v[144:145], v[150:151]
	v_cvt_pk_bf16_f32 v134, v134, v135
	v_cvt_pk_bf16_f32 v135, v144, v145
	global_store_dwordx2 v[138:139], v[134:135], off offset:32
	v_add_u32_e32 v134, 0x90, v132
	v_min_i32_e32 v135, 0x10000, v134
	v_ashrrev_i32_e32 v135, 11, v135
	v_mul_hi_i32_i24_e32 v145, 0x6000, v135
	v_mul_i32_i24_e32 v144, 0x6000, v135
	v_ashrrev_i32_e32 v135, 31, v134
	v_add_u32_e32 v146, 0xffff0090, v132
	v_lshlrev_b64 v[148:149], 11, v[134:135]
	v_cndmask_b32_e32 v135, 0, v135, vcc
	v_cndmask_b32_e32 v134, v146, v134, vcc
	v_lshl_add_u64 v[144:145], s[6:7], 0, v[144:145]
	v_lshlrev_b64 v[134:135], 12, v[134:135]
	v_lshl_add_u64 v[146:147], v[144:145], 0, v[0:1]
	v_lshl_add_u64 v[144:145], s[38:39], 0, v[148:149]
	v_cndmask_b32_e32 v149, v133, v163, vcc
	v_cndmask_b32_e32 v148, v164, v165, vcc
	v_lshl_add_u64 v[134:135], v[148:149], 0, v[134:135]
	v_lshl_add_u64 v[148:149], v[134:135], 0, v[0:1]
	global_load_dwordx4 v[150:153], v[146:147], off
	v_lshl_add_u64 v[144:145], v[144:145], 0, v[136:137]
	v_cmp_gt_i32_e32 vcc, s0, v132
	s_mov_b32 s0, 0xff50
	s_waitcnt vmcnt(0)
	v_mov_b32_e32 v154, v184
	v_mov_b32_e32 v155, v185
	v_mov_b32_e32 v156, v186
	v_mov_b32_e32 v157, v187
	v_pk_mul_f32 v[134:135], v[130:131], v[150:151]
	v_pk_mul_f32 v[150:151], v[130:131], v[152:153]
	s_waitcnt vmcnt(0)
	v_pk_fma_f32 v[134:135], v[54:55], v[134:135], v[154:155]
	v_pk_fma_f32 v[150:151], v[56:57], v[150:151], v[156:157]
	v_cvt_pk_bf16_f32 v134, v134, v135
	v_cvt_pk_bf16_f32 v135, v150, v151
	global_store_dwordx2 v[144:145], v[134:135], off
	global_load_dwordx4 v[150:153], v[146:147], off offset:64
	s_waitcnt vmcnt(0)
	v_mov_b32_e32 v154, v188
	v_mov_b32_e32 v155, v189
	v_mov_b32_e32 v156, v190
	v_mov_b32_e32 v157, v191
	v_pk_mul_f32 v[134:135], v[130:131], v[150:151]
	v_pk_mul_f32 v[150:151], v[130:131], v[152:153]
	s_waitcnt vmcnt(0)
	v_pk_fma_f32 v[134:135], v[50:51], v[134:135], v[154:155]
	v_pk_fma_f32 v[150:151], v[52:53], v[150:151], v[156:157]
	v_cvt_pk_bf16_f32 v134, v134, v135
	v_cvt_pk_bf16_f32 v135, v150, v151
	global_store_dwordx2 v[144:145], v[134:135], off offset:32
	v_add_u32_e32 v134, 0xa0, v132
	v_min_i32_e32 v135, 0x10000, v134
	v_ashrrev_i32_e32 v135, 11, v135
	v_mul_hi_i32_i24_e32 v151, 0x6000, v135
	v_mul_i32_i24_e32 v150, 0x6000, v135
	v_ashrrev_i32_e32 v135, 31, v134
	v_add_u32_e32 v152, 0xffff00a0, v132
	v_lshlrev_b64 v[154:155], 11, v[134:135]
	v_cndmask_b32_e32 v135, 0, v135, vcc
	v_cndmask_b32_e32 v134, v152, v134, vcc
	v_lshl_add_u64 v[150:151], s[6:7], 0, v[150:151]
	v_lshlrev_b64 v[134:135], 12, v[134:135]
	v_lshl_add_u64 v[152:153], v[150:151], 0, v[0:1]
	v_lshl_add_u64 v[150:151], s[38:39], 0, v[154:155]
	v_cndmask_b32_e32 v155, v133, v163, vcc
	v_cndmask_b32_e32 v154, v164, v165, vcc
	v_lshl_add_u64 v[134:135], v[154:155], 0, v[134:135]
	v_lshl_add_u64 v[154:155], v[134:135], 0, v[0:1]
	global_load_dwordx4 v[156:159], v[152:153], off
	v_lshl_add_u64 v[150:151], v[150:151], 0, v[136:137]
	v_cmp_gt_i32_e32 vcc, s0, v132
	s_mov_b64 s[0:1], 0x120
	s_waitcnt vmcnt(0)
	v_mov_b32_e32 v166, v192
	v_mov_b32_e32 v167, v193
	v_mov_b32_e32 v168, v194
	v_mov_b32_e32 v169, v195
	v_pk_mul_f32 v[134:135], v[130:131], v[156:157]
	v_pk_mul_f32 v[156:157], v[130:131], v[158:159]
	s_waitcnt vmcnt(0)
	v_pk_fma_f32 v[134:135], v[46:47], v[134:135], v[166:167]
	v_pk_fma_f32 v[156:157], v[48:49], v[156:157], v[168:169]
	v_cvt_pk_bf16_f32 v134, v134, v135
	v_cvt_pk_bf16_f32 v135, v156, v157
	global_store_dwordx2 v[150:151], v[134:135], off
	global_load_dwordx4 v[156:159], v[152:153], off offset:64
	s_waitcnt vmcnt(0)
	v_mov_b32_e32 v166, v208
	v_mov_b32_e32 v167, v209
	v_mov_b32_e32 v168, v210
	v_mov_b32_e32 v169, v211
	v_pk_mul_f32 v[134:135], v[130:131], v[156:157]
	v_pk_mul_f32 v[156:157], v[130:131], v[158:159]
	s_waitcnt vmcnt(0)
	v_pk_fma_f32 v[134:135], v[42:43], v[134:135], v[166:167]
	v_pk_fma_f32 v[156:157], v[44:45], v[156:157], v[168:169]
	v_cvt_pk_bf16_f32 v134, v134, v135
	v_cvt_pk_bf16_f32 v135, v156, v157
	global_store_dwordx2 v[150:151], v[134:135], off offset:32
	v_add_u32_e32 v134, 0xb0, v132
	v_min_i32_e32 v135, 0x10000, v134
	v_ashrrev_i32_e32 v135, 11, v135
	v_mul_hi_i32_i24_e32 v157, 0x6000, v135
	v_mul_i32_i24_e32 v156, 0x6000, v135
	v_ashrrev_i32_e32 v135, 31, v134
	v_lshlrev_b64 v[160:161], 11, v[134:135]
	v_add_u32_e32 v158, 0xffff00b0, v132
	v_lshl_add_u64 v[156:157], s[6:7], 0, v[156:157]
	v_cndmask_b32_e32 v135, 0, v135, vcc
	v_cndmask_b32_e32 v134, v158, v134, vcc
	v_lshl_add_u64 v[158:159], v[156:157], 0, v[0:1]
	v_lshl_add_u64 v[156:157], s[38:39], 0, v[160:161]
	v_lshlrev_b64 v[134:135], 12, v[134:135]
	v_lshl_add_u64 v[156:157], v[156:157], 0, v[136:137]
	v_cndmask_b32_e32 v137, v133, v163, vcc
	v_cndmask_b32_e32 v136, v164, v165, vcc
	v_lshl_add_u64 v[134:135], v[136:137], 0, v[134:135]
	v_lshl_add_u64 v[160:161], v[134:135], 0, v[0:1]
	global_load_dwordx4 v[164:167], v[158:159], off
	s_waitcnt vmcnt(0)
; __device__ __forceinline__ float lo_bf(unsigned u) { return __uint_as_float(u << 16); }
; __device__ __forceinline__ float hi_bf(unsigned u) { return __uint_as_float(u & 0xffff0000u); }
; template <class Epi>
; __device__ __forceinline__ void gemm_tile(const u16* __restrict__ A, int lda, const u16* __restrict__ Wt, int K,
;                                           int m0, int n0, char* sbase, const Epi& epi) {
;     ...
; #pragma unroll
;   for (int ai = 0; ai < 2; ++ai)
; #pragma unroll
;     for (int bj = 0; bj < 2; ++bj)
; #pragma unroll
;       for (int m = 0; m < 4; ++m)
; #pragma unroll
;         for (int n = 0; n < 2; ++n)
;           epi(m0 + ai * 128 + wr * 64 + m * 16 + fr, n0 + bj * 128 + wc * 32 + n * 16 + fq * 4, acc[ai][bj][m][n]);
;   __device__ __forceinline__ void operator()(int m, int n, f32x4 v) const {
;     float4 g = *(const float4*)(gate + (size_t)modrow(m) * 6144 + n);
;     u16* r = p->Rb + (size_t)m * 1024 + n;
;     f32x4 o;
;     if (src_f32) {
;       float4 a = *(const float4*)(inrow(*p, m) + n);
;       o[0] = a.x; o[1] = a.y; o[2] = a.z; o[3] = a.w;
;     } else {
;       uint2 a = *(const uint2*)r;
;       o[0] = lo_bf(a.x); o[1] = hi_bf(a.x); o[2] = lo_bf(a.y); o[3] = hi_bf(a.y);
;     }
;     o[0] += mul * g.x * v[0]; o[1] += mul * g.y * v[1]; o[2] += mul * g.z * v[2]; o[3] += mul * g.w * v[3];
;     store4bf(r, o);
;   }
	v_mov_b32_e32 v168, v212
	v_mov_b32_e32 v169, v213
	v_mov_b32_e32 v170, v214
	v_mov_b32_e32 v171, v215
	v_pk_mul_f32 v[134:135], v[130:131], v[164:165]
	v_pk_mul_f32 v[136:137], v[130:131], v[166:167]
	s_waitcnt vmcnt(0)
	v_pk_fma_f32 v[134:135], v[38:39], v[134:135], v[168:169]
	v_pk_fma_f32 v[136:137], v[40:41], v[136:137], v[170:171]
	v_cvt_pk_bf16_f32 v134, v134, v135
	v_cvt_pk_bf16_f32 v135, v136, v137
	global_store_dwordx2 v[156:157], v[134:135], off
	global_load_dwordx4 v[164:167], v[158:159], off offset:64
	s_waitcnt vmcnt(0)
	v_mov_b32_e32 v168, v216
	v_mov_b32_e32 v169, v217
	v_mov_b32_e32 v170, v218
	v_mov_b32_e32 v171, v219
	v_pk_mul_f32 v[134:135], v[130:131], v[164:165]
	v_pk_mul_f32 v[136:137], v[130:131], v[166:167]
	s_waitcnt vmcnt(0)
	v_pk_fma_f32 v[134:135], v[34:35], v[134:135], v[168:169]
	v_pk_fma_f32 v[136:137], v[36:37], v[136:137], v[170:171]
	v_cvt_pk_bf16_f32 v134, v134, v135
	v_cvt_pk_bf16_f32 v135, v136, v137
	global_store_dwordx2 v[156:157], v[134:135], off offset:32
	global_load_dwordx4 v[164:167], v[140:141], off offset:512
	s_waitcnt vmcnt(0)
	v_mov_b32_e32 v168, v220
	v_mov_b32_e32 v169, v221
	v_mov_b32_e32 v170, v222
	v_mov_b32_e32 v171, v223
	v_pk_mul_f32 v[134:135], v[130:131], v[164:165]
	v_pk_mul_f32 v[136:137], v[130:131], v[166:167]
	s_waitcnt vmcnt(0)
	v_pk_fma_f32 v[134:135], v[30:31], v[134:135], v[168:169]
	v_pk_fma_f32 v[136:137], v[32:33], v[136:137], v[170:171]
	v_cvt_pk_bf16_f32 v134, v134, v135
	v_cvt_pk_bf16_f32 v135, v136, v137
	global_store_dwordx2 v[138:139], v[134:135], off offset:256
	global_load_dwordx4 v[164:167], v[140:141], off offset:576
	s_nop 0
	s_waitcnt vmcnt(0)
	v_mov_b32_e32 v140, v224
	v_mov_b32_e32 v141, v225
	v_mov_b32_e32 v142, v226
	v_mov_b32_e32 v143, v227
	v_pk_mul_f32 v[134:135], v[130:131], v[164:165]
	v_pk_mul_f32 v[136:137], v[130:131], v[166:167]
	s_waitcnt vmcnt(0)
	v_pk_fma_f32 v[134:135], v[26:27], v[134:135], v[140:141]
	v_pk_fma_f32 v[136:137], v[28:29], v[136:137], v[142:143]
	v_cvt_pk_bf16_f32 v134, v134, v135
	v_cvt_pk_bf16_f32 v135, v136, v137
	global_store_dwordx2 v[138:139], v[134:135], off offset:288
	global_load_dwordx4 v[136:139], v[146:147], off offset:512
	s_nop 0
	s_waitcnt vmcnt(0)
	v_mov_b32_e32 v140, v228
	v_mov_b32_e32 v141, v229
	v_mov_b32_e32 v142, v230
	v_mov_b32_e32 v143, v231
	v_pk_mul_f32 v[134:135], v[130:131], v[136:137]
	v_pk_mul_f32 v[136:137], v[130:131], v[138:139]
	s_waitcnt vmcnt(0)
	v_pk_fma_f32 v[134:135], v[22:23], v[134:135], v[140:141]
	v_pk_fma_f32 v[136:137], v[24:25], v[136:137], v[142:143]
	v_cvt_pk_bf16_f32 v134, v134, v135
	v_cvt_pk_bf16_f32 v135, v136, v137
	global_store_dwordx2 v[144:145], v[134:135], off offset:256
	global_load_dwordx4 v[136:139], v[146:147], off offset:576
	s_waitcnt vmcnt(0)
	v_mov_b32_e32 v140, v232
	v_mov_b32_e32 v141, v233
	v_mov_b32_e32 v142, v234
	v_mov_b32_e32 v143, v235
	v_pk_mul_f32 v[134:135], v[130:131], v[136:137]
	v_pk_mul_f32 v[136:137], v[130:131], v[138:139]
	s_waitcnt vmcnt(0)
	v_pk_fma_f32 v[134:135], v[18:19], v[134:135], v[140:141]
	v_pk_fma_f32 v[136:137], v[20:21], v[136:137], v[142:143]
	v_cvt_pk_bf16_f32 v134, v134, v135
	v_cvt_pk_bf16_f32 v135, v136, v137
	global_store_dwordx2 v[144:145], v[134:135], off offset:288
	global_load_dwordx4 v[136:139], v[152:153], off offset:512
	s_waitcnt vmcnt(0)
	v_mov_b32_e32 v140, v236
	v_mov_b32_e32 v141, v237
	v_mov_b32_e32 v142, v238
	v_mov_b32_e32 v143, v239
	v_pk_mul_f32 v[134:135], v[130:131], v[136:137]
	v_pk_mul_f32 v[136:137], v[130:131], v[138:139]
	s_waitcnt vmcnt(0)
	v_pk_fma_f32 v[134:135], v[14:15], v[134:135], v[140:141]
	v_pk_fma_f32 v[136:137], v[16:17], v[136:137], v[142:143]
	v_cvt_pk_bf16_f32 v134, v134, v135
	v_cvt_pk_bf16_f32 v135, v136, v137
	global_store_dwordx2 v[150:151], v[134:135], off offset:256
	global_load_dwordx4 v[136:139], v[152:153], off offset:576
	s_waitcnt vmcnt(0)
	v_mov_b32_e32 v140, v240
	v_mov_b32_e32 v141, v241
	v_mov_b32_e32 v142, v242
	v_mov_b32_e32 v143, v243
	v_pk_mul_f32 v[134:135], v[130:131], v[136:137]
	v_pk_mul_f32 v[136:137], v[130:131], v[138:139]
	s_waitcnt vmcnt(0)
	v_pk_fma_f32 v[134:135], v[10:11], v[134:135], v[140:141]
	v_pk_fma_f32 v[136:137], v[12:13], v[136:137], v[142:143]
	v_cvt_pk_bf16_f32 v134, v134, v135
	v_cvt_pk_bf16_f32 v135, v136, v137
	global_store_dwordx2 v[150:151], v[134:135], off offset:288
	global_load_dwordx4 v[136:139], v[158:159], off offset:512
	s_waitcnt vmcnt(0)
	v_mov_b32_e32 v140, v244
	v_mov_b32_e32 v141, v245
	v_mov_b32_e32 v142, v246
	v_mov_b32_e32 v143, v247
	v_pk_mul_f32 v[134:135], v[130:131], v[136:137]
	v_pk_mul_f32 v[136:137], v[130:131], v[138:139]
	s_waitcnt vmcnt(0)
	v_pk_fma_f32 v[134:135], v[6:7], v[134:135], v[140:141]
	v_pk_fma_f32 v[136:137], v[8:9], v[136:137], v[142:143]
	v_cvt_pk_bf16_f32 v134, v134, v135
	v_cvt_pk_bf16_f32 v135, v136, v137
	global_store_dwordx2 v[156:157], v[134:135], off offset:256
	global_load_dwordx4 v[138:141], v[158:159], off offset:576
	v_lshl_add_u64 v[136:137], v[156:157], 0, s[0:1]
	s_mov_b64 s[0:1], 0
	s_waitcnt vmcnt(0)
	v_mov_b32_e32 v142, v248
	v_mov_b32_e32 v143, v249
	v_mov_b32_e32 v144, v250
	v_mov_b32_e32 v145, v251
	v_pk_mul_f32 v[134:135], v[130:131], v[138:139]
	s_waitcnt vmcnt(0)
	v_pk_fma_f32 v[134:135], v[2:3], v[134:135], v[142:143]
	v_pk_mul_f32 v[138:139], v[130:131], v[140:141]
	v_cvt_pk_bf16_f32 v0, v134, v135
	v_pk_fma_f32 v[138:139], v[4:5], v[138:139], v[144:145]
	global_store_dword v[156:157], v0, off offset:288

; __device__ __forceinline__ float lo_bf(unsigned u) { return __uint_as_float(u << 16); }
; __device__ __forceinline__ float hi_bf(unsigned u) { return __uint_as_float(u & 0xffff0000u); }
; template <class Epi>
; __device__ __forceinline__ void gemm_tile(const u16* __restrict__ A, int lda, const u16* __restrict__ Wt, int K,
;                                           int m0, int n0, char* sbase, const Epi& epi) {
;     ...
;   if constexpr (Epi::kBatched) {
;     if (!epi.src_f32) {
; #pragma unroll
;       for (int ai = 0; ai < 2; ++ai) {
;         float4 gg[2][2];
;         uint2 rr[2][4][2];
; #pragma unroll
;         for (int bj = 0; bj < 2; ++bj)
; #pragma unroll
;           for (int n = 0; n < 2; ++n) gg[bj][n] = epi.loadG(m0, n0 + bj * 128 + wc * 32 + n * 16 + fq * 4);
; #pragma unroll
;         for (int bj = 0; bj < 2; ++bj)
; #pragma unroll
;           for (int m = 0; m < 4; ++m)
; #pragma unroll
;             for (int n = 0; n < 2; ++n)
;               rr[bj][m][n] = epi.loadR(m0 + ai * 128 + wr * 64 + m * 16 + fr, n0 + bj * 128 + wc * 32 + n * 16 + fq * 4);
; #pragma unroll
;         for (int bj = 0; bj < 2; ++bj)
; #pragma unroll
;           for (int m = 0; m < 4; ++m)
; #pragma unroll
;             for (int n = 0; n < 2; ++n)
;               epi.apply(m0 + ai * 128 + wr * 64 + m * 16 + fr, n0 + bj * 128 + wc * 32 + n * 16 + fq * 4, acc[ai][bj][m][n],
;                         rr[bj][m][n], gg[bj][n]);
;       }
;       return;
;   __device__ __forceinline__ float4 loadG(int m, int n) const { return *(const float4*)(gate + (size_t)modrow(m) * 6144 + n); }
;   __device__ __forceinline__ void apply(int m, int n, f32x4 v, uint2 a, float4 g) const {
;     f32x4 o;
;     o[0] = lo_bf(a.x) + mul * g.x * v[0]; o[1] = hi_bf(a.x) + mul * g.y * v[1];
;     o[2] = lo_bf(a.y) + mul * g.z * v[2]; o[3] = hi_bf(a.y) + mul * g.w * v[3];
;     store4bf(p->Rb + (size_t)m * 1024 + n, o);
;   }
.LBB0_1814:
	s_or_b64 exec, exec, s[0:1]
	v_lshlrev_b32_e32 v0, 5, v146
	v_lshlrev_b32_e32 v132, 2, v147
	v_or3_b32 v0, v0, v132, s49
	v_or_b32_e32 v132, s48, v145
	v_add_u32_e32 v134, v132, v148
	v_or_b32_e32 v132, 48, v134
	v_ashrrev_i32_e32 v133, 31, v132
	v_lshlrev_b64 v[132:133], 11, v[132:133]
	v_ashrrev_i32_e32 v135, 31, v134
	s_min_i32 s0, s48, 0x10000
	v_lshl_add_u64 v[136:137], s[38:39], 0, v[132:133]
	v_lshlrev_b64 v[132:133], 11, v[134:135]
	v_or_b32_e32 v138, 16, v134
	v_or_b32_e32 v134, 32, v134
	s_lshr_b32 s0, s0, 11
	v_ashrrev_i32_e32 v139, 31, v138
	v_ashrrev_i32_e32 v135, 31, v134
	s_mulk_i32 s0, 0x6000
	v_lshlrev_b64 v[138:139], 11, v[138:139]
	v_lshlrev_b64 v[134:135], 11, v[134:135]
	s_add_u32 s12, s19, s0
	v_lshlrev_b32_e32 v160, 2, v0
	v_lshl_add_u64 v[132:133], s[38:39], 0, v[132:133]
	v_lshlrev_b32_e32 v0, 1, v0
	v_lshl_add_u64 v[138:139], s[38:39], 0, v[138:139]
	v_lshl_add_u64 v[134:135], s[38:39], 0, v[134:135]
	s_addc_u32 s13, s20, 0
	v_lshl_add_u64 v[132:133], v[132:133], 0, v[0:1]
	v_lshl_add_u64 v[146:147], v[138:139], 0, v[0:1]
	v_lshl_add_u64 v[140:141], v[134:135], 0, v[0:1]
	v_lshl_add_u64 v[136:137], v[136:137], 0, v[0:1]
	global_load_dwordx2 v[166:167], v[132:133], off
	global_load_dwordx2 v[168:169], v[132:133], off offset:32
	global_load_dwordx2 v[170:171], v[146:147], off
	global_load_dwordx2 v[172:173], v[146:147], off offset:32
	global_load_dwordx2 v[134:135], v[140:141], off
	global_load_dwordx2 v[174:175], v[140:141], off offset:32
	global_load_dwordx2 v[176:177], v[136:137], off
	global_load_dwordx2 v[158:159], v[136:137], off offset:32
	global_load_dwordx2 v[156:157], v[132:133], off offset:256
	global_load_dwordx2 v[154:155], v[132:133], off offset:288
	global_load_dwordx2 v[152:153], v[146:147], off offset:256
	global_load_dwordx2 v[150:151], v[146:147], off offset:288
	global_load_dwordx2 v[148:149], v[140:141], off offset:256
	global_load_dwordx2 v[144:145], v[140:141], off offset:288
	global_load_dwordx2 v[142:143], v[136:137], off offset:256
	global_load_dwordx2 v[138:139], v[136:137], off offset:288
	global_load_dwordx4 v[162:165], v160, s[12:13]
	global_load_dwordx4 v[208:211], v160, s[12:13]
	global_load_dwordx4 v[212:215], v160, s[12:13] offset:64
	global_load_dwordx4 v[216:219], v160, s[12:13] offset:512
	global_load_dwordx4 v[220:223], v160, s[12:13] offset:576
	s_mov_b64 s[0:1], 0x40000
	s_add_i32 s47, s47, s75
	s_add_i32 s46, s46, s44
	s_add_i32 s34, s34, s75
	s_cmp_ge_u32 s47, s21
	v_mov_b32_e32 v252, 0x358637bd
	s_waitcnt vmcnt(0)
	v_lshlrev_b32_e32 v178, 16, v166
	v_and_b32_e32 v179, 0xffff0000, v166
	v_pk_mul_f32 v[180:181], v[130:131], v[162:163]
	v_lshlrev_b32_e32 v162, 16, v167
	v_and_b32_e32 v163, 0xffff0000, v167
	v_pk_mul_f32 v[166:167], v[130:131], v[164:165]
	v_pk_fma_f32 v[126:127], v[126:127], v[180:181], v[178:179]
	v_pk_fma_f32 v[128:129], v[128:129], v[166:167], v[162:163]
	v_mov_b32_e32 v162, v212
	v_mov_b32_e32 v163, v213
	v_mov_b32_e32 v164, v214
	v_mov_b32_e32 v165, v215
	v_cvt_pk_bf16_f32 v126, v126, v127
	v_cvt_pk_bf16_f32 v127, v128, v129
	v_lshlrev_b32_e32 v128, 16, v168
	v_and_b32_e32 v129, 0xffff0000, v168
	v_pk_mul_f32 v[162:163], v[130:131], v[162:163]
	s_nop 0
	v_pk_fma_f32 v[122:123], v[122:123], v[162:163], v[128:129]
	v_lshlrev_b32_e32 v128, 16, v169
	v_and_b32_e32 v129, 0xffff0000, v169
	v_pk_mul_f32 v[164:165], v[130:131], v[164:165]
	v_cvt_pk_bf16_f32 v122, v122, v123
	v_pk_fma_f32 v[124:125], v[124:125], v[164:165], v[128:129]
	s_nop 0
	v_cvt_pk_bf16_f32 v123, v124, v125
	v_lshlrev_b32_e32 v124, 16, v170
	v_and_b32_e32 v125, 0xffff0000, v170
	v_pk_fma_f32 v[118:119], v[118:119], v[180:181], v[124:125]
	v_lshlrev_b32_e32 v124, 16, v171
	v_and_b32_e32 v125, 0xffff0000, v171
	v_pk_fma_f32 v[120:121], v[120:121], v[166:167], v[124:125]
	v_cvt_pk_bf16_f32 v118, v118, v119
	v_cvt_pk_bf16_f32 v119, v120, v121
	v_lshlrev_b32_e32 v120, 16, v172
	v_and_b32_e32 v121, 0xffff0000, v172
	v_pk_fma_f32 v[114:115], v[114:115], v[162:163], v[120:121]
	v_lshlrev_b32_e32 v120, 16, v173
	v_and_b32_e32 v121, 0xffff0000, v173
	v_pk_fma_f32 v[116:117], v[116:117], v[164:165], v[120:121]
	v_cvt_pk_bf16_f32 v114, v114, v115
	v_cvt_pk_bf16_f32 v115, v116, v117
	v_lshlrev_b32_e32 v116, 16, v134
	v_and_b32_e32 v117, 0xffff0000, v134
	v_pk_fma_f32 v[110:111], v[110:111], v[180:181], v[116:117]
	v_lshlrev_b32_e32 v116, 16, v135
	v_and_b32_e32 v117, 0xffff0000, v135
	v_pk_fma_f32 v[112:113], v[112:113], v[166:167], v[116:117]
	v_cvt_pk_bf16_f32 v110, v110, v111
	v_cvt_pk_bf16_f32 v111, v112, v113
	v_lshlrev_b32_e32 v112, 16, v174
	v_and_b32_e32 v113, 0xffff0000, v174
	v_pk_fma_f32 v[106:107], v[106:107], v[162:163], v[112:113]
	v_lshlrev_b32_e32 v112, 16, v175
	v_and_b32_e32 v113, 0xffff0000, v175
	v_pk_fma_f32 v[108:109], v[108:109], v[164:165], v[112:113]
	v_cvt_pk_bf16_f32 v106, v106, v107
	v_cvt_pk_bf16_f32 v107, v108, v109
	v_lshlrev_b32_e32 v108, 16, v176
	v_and_b32_e32 v109, 0xffff0000, v176
	v_pk_fma_f32 v[102:103], v[102:103], v[180:181], v[108:109]
	v_lshlrev_b32_e32 v108, 16, v177
	v_and_b32_e32 v109, 0xffff0000, v177
	v_pk_fma_f32 v[104:105], v[104:105], v[166:167], v[108:109]
	v_cvt_pk_bf16_f32 v102, v102, v103
	v_cvt_pk_bf16_f32 v103, v104, v105
	v_lshlrev_b32_e32 v104, 16, v158
	v_and_b32_e32 v105, 0xffff0000, v158
	v_pk_fma_f32 v[98:99], v[98:99], v[162:163], v[104:105]
	v_lshlrev_b32_e32 v104, 16, v159
	v_and_b32_e32 v105, 0xffff0000, v159
	v_pk_fma_f32 v[100:101], v[100:101], v[164:165], v[104:105]
	v_mov_b32_e32 v162, v216
	v_mov_b32_e32 v163, v217
	v_mov_b32_e32 v164, v218
	v_mov_b32_e32 v165, v219
	v_cvt_pk_bf16_f32 v98, v98, v99
	v_cvt_pk_bf16_f32 v99, v100, v101
; __device__ __forceinline__ float lo_bf(unsigned u) { return __uint_as_float(u << 16); }
; __device__ __forceinline__ float hi_bf(unsigned u) { return __uint_as_float(u & 0xffff0000u); }
; template <class Epi>
; __device__ __forceinline__ void gemm_tile(const u16* __restrict__ A, int lda, const u16* __restrict__ Wt, int K,
;                                           int m0, int n0, char* sbase, const Epi& epi) {
;     ...
;   if constexpr (Epi::kBatched) {
;     if (!epi.src_f32) {
; #pragma unroll
;       for (int ai = 0; ai < 2; ++ai) {
;         float4 gg[2][2];
;         uint2 rr[2][4][2];
; #pragma unroll
;         for (int bj = 0; bj < 2; ++bj)
; #pragma unroll
;           for (int n = 0; n < 2; ++n) gg[bj][n] = epi.loadG(m0, n0 + bj * 128 + wc * 32 + n * 16 + fq * 4);
; #pragma unroll
;         for (int bj = 0; bj < 2; ++bj)
; #pragma unroll
;           for (int m = 0; m < 4; ++m)
; #pragma unroll
;             for (int n = 0; n < 2; ++n)
;               rr[bj][m][n] = epi.loadR(m0 + ai * 128 + wr * 64 + m * 16 + fr, n0 + bj * 128 + wc * 32 + n * 16 + fq * 4);
; #pragma unroll
;         for (int bj = 0; bj < 2; ++bj)
; #pragma unroll
;           for (int m = 0; m < 4; ++m)
; #pragma unroll
;             for (int n = 0; n < 2; ++n)
;               epi.apply(m0 + ai * 128 + wr * 64 + m * 16 + fr, n0 + bj * 128 + wc * 32 + n * 16 + fq * 4, acc[ai][bj][m][n],
;                         rr[bj][m][n], gg[bj][n]);
;       }
;       return;
;   __device__ __forceinline__ float4 loadG(int m, int n) const { return *(const float4*)(gate + (size_t)modrow(m) * 6144 + n); }
;   __device__ __forceinline__ void apply(int m, int n, f32x4 v, uint2 a, float4 g) const {
;     f32x4 o;
;     o[0] = lo_bf(a.x) + mul * g.x * v[0]; o[1] = hi_bf(a.x) + mul * g.y * v[1];
;     o[2] = lo_bf(a.y) + mul * g.z * v[2]; o[3] = hi_bf(a.y) + mul * g.w * v[3];
;     store4bf(p->Rb + (size_t)m * 1024 + n, o);
;   }
	v_lshlrev_b32_e32 v100, 16, v156
	v_and_b32_e32 v101, 0xffff0000, v156
	v_lshlrev_b32_e32 v108, 16, v157
	v_and_b32_e32 v109, 0xffff0000, v157
	v_lshlrev_b32_e32 v112, 16, v154
	v_and_b32_e32 v113, 0xffff0000, v154
	v_pk_mul_f32 v[104:105], v[130:131], v[162:163]
	s_nop 0
	v_pk_fma_f32 v[94:95], v[94:95], v[104:105], v[100:101]
	v_pk_mul_f32 v[100:101], v[130:131], v[164:165]
	s_nop 0
	v_pk_fma_f32 v[96:97], v[96:97], v[100:101], v[108:109]
	v_cvt_pk_bf16_f32 v108, v94, v95
	v_cvt_pk_bf16_f32 v109, v96, v97
	v_mov_b32_e32 v94, v220
	v_mov_b32_e32 v95, v221
	v_mov_b32_e32 v96, v222
	v_mov_b32_e32 v97, v223
	s_nop 0
	global_store_dwordx2 v[132:133], v[126:127], off
	global_store_dwordx2 v[132:133], v[122:123], off offset:32
	global_store_dwordx2 v[146:147], v[118:119], off
	global_store_dwordx2 v[146:147], v[114:115], off offset:32
	global_store_dwordx2 v[140:141], v[110:111], off
	global_store_dwordx2 v[140:141], v[106:107], off offset:32
	global_store_dwordx2 v[136:137], v[102:103], off
	global_store_dwordx2 v[136:137], v[98:99], off offset:32
	global_store_dwordx2 v[132:133], v[108:109], off offset:256
	v_pk_mul_f32 v[94:95], v[130:131], v[94:95]
	s_nop 0
	v_pk_fma_f32 v[90:91], v[90:91], v[94:95], v[112:113]
	v_lshlrev_b32_e32 v112, 16, v155
	v_and_b32_e32 v113, 0xffff0000, v155
	v_pk_mul_f32 v[96:97], v[130:131], v[96:97]
	v_cvt_pk_bf16_f32 v90, v90, v91
	v_pk_fma_f32 v[92:93], v[92:93], v[96:97], v[112:113]
	s_nop 0
	v_cvt_pk_bf16_f32 v91, v92, v93
	global_store_dwordx2 v[132:133], v[90:91], off offset:288
	v_lshlrev_b32_e32 v90, 16, v152
	v_and_b32_e32 v91, 0xffff0000, v152
	v_pk_fma_f32 v[86:87], v[86:87], v[104:105], v[90:91]
	v_lshlrev_b32_e32 v90, 16, v153
	v_and_b32_e32 v91, 0xffff0000, v153
	v_pk_fma_f32 v[88:89], v[88:89], v[100:101], v[90:91]
	v_cvt_pk_bf16_f32 v86, v86, v87
	v_cvt_pk_bf16_f32 v87, v88, v89
	global_store_dwordx2 v[146:147], v[86:87], off offset:256
	v_lshlrev_b32_e32 v86, 16, v150
	v_and_b32_e32 v87, 0xffff0000, v150
	v_pk_fma_f32 v[82:83], v[82:83], v[94:95], v[86:87]
	v_lshlrev_b32_e32 v86, 16, v151
	v_and_b32_e32 v87, 0xffff0000, v151
	v_pk_fma_f32 v[84:85], v[84:85], v[96:97], v[86:87]
	v_cvt_pk_bf16_f32 v82, v82, v83
	v_cvt_pk_bf16_f32 v83, v84, v85
	global_store_dwordx2 v[146:147], v[82:83], off offset:288
	v_lshlrev_b32_e32 v82, 16, v148
	v_and_b32_e32 v83, 0xffff0000, v148
	v_pk_fma_f32 v[78:79], v[78:79], v[104:105], v[82:83]
	v_lshlrev_b32_e32 v82, 16, v149
	v_and_b32_e32 v83, 0xffff0000, v149
	v_pk_fma_f32 v[80:81], v[80:81], v[100:101], v[82:83]
	v_cvt_pk_bf16_f32 v78, v78, v79
	v_cvt_pk_bf16_f32 v79, v80, v81
	global_store_dwordx2 v[140:141], v[78:79], off offset:256
	v_lshlrev_b32_e32 v78, 16, v144
	v_and_b32_e32 v79, 0xffff0000, v144
	v_pk_fma_f32 v[74:75], v[74:75], v[94:95], v[78:79]
	v_lshlrev_b32_e32 v78, 16, v145
	v_and_b32_e32 v79, 0xffff0000, v145
	v_pk_fma_f32 v[76:77], v[76:77], v[96:97], v[78:79]
	v_cvt_pk_bf16_f32 v74, v74, v75
	v_cvt_pk_bf16_f32 v75, v76, v77
	global_store_dwordx2 v[140:141], v[74:75], off offset:288
	v_lshlrev_b32_e32 v74, 16, v142
	v_and_b32_e32 v75, 0xffff0000, v142
	v_pk_fma_f32 v[70:71], v[70:71], v[104:105], v[74:75]
	v_lshlrev_b32_e32 v74, 16, v143
	v_and_b32_e32 v75, 0xffff0000, v143
	v_pk_fma_f32 v[72:73], v[72:73], v[100:101], v[74:75]
	v_lshl_add_u64 v[78:79], v[132:133], 0, s[0:1]
	s_mov_b32 s0, 0x40000
	v_cvt_pk_bf16_f32 v70, v70, v71
	v_cvt_pk_bf16_f32 v71, v72, v73
	v_add_co_u32_e32 v86, vcc, s0, v132
	global_store_dwordx2 v[136:137], v[70:71], off offset:256
	v_lshlrev_b32_e32 v70, 16, v138
	v_and_b32_e32 v71, 0xffff0000, v138
	v_addc_co_u32_e32 v87, vcc, 0, v133, vcc
	s_mov_b32 s0, 0x48000
	v_pk_fma_f32 v[66:67], v[66:67], v[94:95], v[70:71]
	v_lshlrev_b32_e32 v70, 16, v139
	v_and_b32_e32 v71, 0xffff0000, v139
	v_add_co_u32_e32 v88, vcc, s0, v132
	s_mov_b64 s[0:1], 0x50000
	v_pk_fma_f32 v[68:69], v[68:69], v[96:97], v[70:71]
	v_addc_co_u32_e32 v89, vcc, 0, v133, vcc
	v_lshl_add_u64 v[70:71], v[132:133], 0, s[0:1]
	s_mov_b32 s0, 0x50000
	v_cvt_pk_bf16_f32 v66, v66, v67
	v_cvt_pk_bf16_f32 v67, v68, v69
	v_add_co_u32_e32 v90, vcc, s0, v132
	s_mov_b64 s[0:1], 0x58000
	global_store_dwordx2 v[136:137], v[66:67], off offset:288
	v_addc_co_u32_e32 v91, vcc, 0, v133, vcc
	v_lshl_add_u64 v[66:67], v[132:133], 0, s[0:1]
	s_mov_b32 s0, 0x58000
	v_add_co_u32_e32 v92, vcc, s0, v132
	global_load_dwordx2 v[102:103], v[86:87], off
	global_load_dwordx2 v[104:105], v[78:79], off offset:32
	v_addc_co_u32_e32 v93, vcc, 0, v133, vcc
	v_lshl_add_u64 v[74:75], v[132:133], 0, s[28:29]
	global_load_dwordx2 v[106:107], v[88:89], off
	global_load_dwordx2 v[108:109], v[74:75], off offset:32
	global_load_dwordx2 v[110:111], v[90:91], off
	global_load_dwordx2 v[112:113], v[70:71], off offset:32
	global_load_dwordx2 v[114:115], v[92:93], off
	global_load_dwordx2 v[116:117], v[66:67], off offset:32
	global_load_dwordx2 v[96:97], v[78:79], off offset:256
	global_load_dwordx2 v[94:95], v[78:79], off offset:288
	global_load_dwordx2 v[84:85], v[74:75], off offset:256
	global_load_dwordx2 v[82:83], v[74:75], off offset:288
	global_load_dwordx2 v[80:81], v[70:71], off offset:256
	global_load_dwordx2 v[76:77], v[70:71], off offset:288
	global_load_dwordx2 v[72:73], v[66:67], off offset:256
	global_load_dwordx2 v[68:69], v[66:67], off offset:288
	v_mov_b32_e32 v98, v208
	v_mov_b32_e32 v99, v209
	v_mov_b32_e32 v100, v210
	v_mov_b32_e32 v101, v211
	s_waitcnt vmcnt(0)
; __device__ __forceinline__ float lo_bf(unsigned u) { return __uint_as_float(u << 16); }
; __device__ __forceinline__ float hi_bf(unsigned u) { return __uint_as_float(u & 0xffff0000u); }
; template <class Epi>
; __device__ __forceinline__ void gemm_tile(const u16* __restrict__ A, int lda, const u16* __restrict__ Wt, int K,
;                                           int m0, int n0, char* sbase, const Epi& epi) {
;     ...
;   if constexpr (Epi::kBatched) {
;     if (!epi.src_f32) {
; #pragma unroll
;       for (int ai = 0; ai < 2; ++ai) {
;         float4 gg[2][2];
;         uint2 rr[2][4][2];
; #pragma unroll
;         for (int bj = 0; bj < 2; ++bj)
; #pragma unroll
;           for (int n = 0; n < 2; ++n) gg[bj][n] = epi.loadG(m0, n0 + bj * 128 + wc * 32 + n * 16 + fq * 4);
; #pragma unroll
;         for (int bj = 0; bj < 2; ++bj)
; #pragma unroll
;           for (int m = 0; m < 4; ++m)
; #pragma unroll
;             for (int n = 0; n < 2; ++n)
;               rr[bj][m][n] = epi.loadR(m0 + ai * 128 + wr * 64 + m * 16 + fr, n0 + bj * 128 + wc * 32 + n * 16 + fq * 4);
; #pragma unroll
;         for (int bj = 0; bj < 2; ++bj)
; #pragma unroll
;           for (int m = 0; m < 4; ++m)
; #pragma unroll
;             for (int n = 0; n < 2; ++n)
;               epi.apply(m0 + ai * 128 + wr * 64 + m * 16 + fr, n0 + bj * 128 + wc * 32 + n * 16 + fq * 4, acc[ai][bj][m][n],
;                         rr[bj][m][n], gg[bj][n]);
;       }
;       return;
;   __device__ __forceinline__ float4 loadG(int m, int n) const { return *(const float4*)(gate + (size_t)modrow(m) * 6144 + n); }
;   __device__ __forceinline__ void apply(int m, int n, f32x4 v, uint2 a, float4 g) const {
;     f32x4 o;
;     o[0] = lo_bf(a.x) + mul * g.x * v[0]; o[1] = hi_bf(a.x) + mul * g.y * v[1];
;     o[2] = lo_bf(a.y) + mul * g.z * v[2]; o[3] = hi_bf(a.y) + mul * g.w * v[3];
;     store4bf(p->Rb + (size_t)m * 1024 + n, o);
;   }
	v_lshlrev_b32_e32 v118, 16, v102
	v_and_b32_e32 v119, 0xffff0000, v102
	v_pk_mul_f32 v[120:121], v[130:131], v[98:99]
	v_lshlrev_b32_e32 v98, 16, v103
	v_and_b32_e32 v99, 0xffff0000, v103
	v_pk_mul_f32 v[102:103], v[130:131], v[100:101]
	v_pk_fma_f32 v[62:63], v[62:63], v[120:121], v[118:119]
	v_pk_fma_f32 v[64:65], v[64:65], v[102:103], v[98:99]
	v_mov_b32_e32 v98, v212
	v_mov_b32_e32 v99, v213
	v_mov_b32_e32 v100, v214
	v_mov_b32_e32 v101, v215
	v_cvt_pk_bf16_f32 v62, v62, v63
	v_cvt_pk_bf16_f32 v63, v64, v65
	v_lshlrev_b32_e32 v64, 16, v104
	v_and_b32_e32 v65, 0xffff0000, v104
	v_pk_mul_f32 v[98:99], v[130:131], v[98:99]
	s_nop 0
	v_pk_fma_f32 v[58:59], v[58:59], v[98:99], v[64:65]
	v_lshlrev_b32_e32 v64, 16, v105
	v_and_b32_e32 v65, 0xffff0000, v105
	v_pk_mul_f32 v[100:101], v[130:131], v[100:101]
	v_cvt_pk_bf16_f32 v58, v58, v59
	v_pk_fma_f32 v[60:61], v[60:61], v[100:101], v[64:65]
	s_nop 0
	v_cvt_pk_bf16_f32 v59, v60, v61
	v_lshlrev_b32_e32 v60, 16, v106
	v_and_b32_e32 v61, 0xffff0000, v106
	v_pk_fma_f32 v[54:55], v[54:55], v[120:121], v[60:61]
	v_lshlrev_b32_e32 v60, 16, v107
	v_and_b32_e32 v61, 0xffff0000, v107
	v_pk_fma_f32 v[56:57], v[56:57], v[102:103], v[60:61]
	v_cvt_pk_bf16_f32 v54, v54, v55
	v_cvt_pk_bf16_f32 v55, v56, v57
	v_lshlrev_b32_e32 v56, 16, v108
	v_and_b32_e32 v57, 0xffff0000, v108
	v_pk_fma_f32 v[50:51], v[50:51], v[98:99], v[56:57]
	v_lshlrev_b32_e32 v56, 16, v109
	v_and_b32_e32 v57, 0xffff0000, v109
	v_pk_fma_f32 v[52:53], v[52:53], v[100:101], v[56:57]
	v_cvt_pk_bf16_f32 v50, v50, v51
	v_cvt_pk_bf16_f32 v51, v52, v53
	v_lshlrev_b32_e32 v52, 16, v110
	v_and_b32_e32 v53, 0xffff0000, v110
	v_pk_fma_f32 v[46:47], v[46:47], v[120:121], v[52:53]
	v_lshlrev_b32_e32 v52, 16, v111
	v_and_b32_e32 v53, 0xffff0000, v111
	v_pk_fma_f32 v[48:49], v[48:49], v[102:103], v[52:53]
	v_cvt_pk_bf16_f32 v46, v46, v47
	v_cvt_pk_bf16_f32 v47, v48, v49
	v_lshlrev_b32_e32 v48, 16, v112
	v_and_b32_e32 v49, 0xffff0000, v112
	v_pk_fma_f32 v[42:43], v[42:43], v[98:99], v[48:49]
	v_lshlrev_b32_e32 v48, 16, v113
	v_and_b32_e32 v49, 0xffff0000, v113
	v_pk_fma_f32 v[44:45], v[44:45], v[100:101], v[48:49]
	v_cvt_pk_bf16_f32 v42, v42, v43
	v_cvt_pk_bf16_f32 v43, v44, v45
	v_lshlrev_b32_e32 v44, 16, v114
	v_and_b32_e32 v45, 0xffff0000, v114
	v_pk_fma_f32 v[38:39], v[38:39], v[120:121], v[44:45]
	v_lshlrev_b32_e32 v44, 16, v115
	v_and_b32_e32 v45, 0xffff0000, v115
	v_pk_fma_f32 v[40:41], v[40:41], v[102:103], v[44:45]
	v_cvt_pk_bf16_f32 v38, v38, v39
	v_cvt_pk_bf16_f32 v39, v40, v41
	v_lshlrev_b32_e32 v40, 16, v116
	v_and_b32_e32 v41, 0xffff0000, v116
	v_pk_fma_f32 v[34:35], v[34:35], v[98:99], v[40:41]
	v_lshlrev_b32_e32 v40, 16, v117
	v_and_b32_e32 v41, 0xffff0000, v117
	v_pk_fma_f32 v[36:37], v[36:37], v[100:101], v[40:41]
	v_mov_b32_e32 v98, v216
	v_mov_b32_e32 v99, v217
	v_mov_b32_e32 v100, v218
	v_mov_b32_e32 v101, v219
	v_cvt_pk_bf16_f32 v34, v34, v35
	v_cvt_pk_bf16_f32 v35, v36, v37
	v_lshlrev_b32_e32 v36, 16, v96
	v_and_b32_e32 v37, 0xffff0000, v96
	v_lshlrev_b32_e32 v44, 16, v97
	v_and_b32_e32 v45, 0xffff0000, v97
	v_lshlrev_b32_e32 v48, 16, v94
	v_and_b32_e32 v49, 0xffff0000, v94
	v_pk_mul_f32 v[40:41], v[130:131], v[98:99]
	s_nop 0
	v_pk_fma_f32 v[30:31], v[30:31], v[40:41], v[36:37]
	v_pk_mul_f32 v[36:37], v[130:131], v[100:101]
	s_nop 0
	v_pk_fma_f32 v[32:33], v[32:33], v[36:37], v[44:45]
	v_cvt_pk_bf16_f32 v44, v30, v31
	v_cvt_pk_bf16_f32 v45, v32, v33
	v_mov_b32_e32 v30, v220
	v_mov_b32_e32 v31, v221
	v_mov_b32_e32 v32, v222
	v_mov_b32_e32 v33, v223
	s_nop 0
	global_store_dwordx2 v[86:87], v[62:63], off
	global_store_dwordx2 v[78:79], v[58:59], off offset:32
	global_store_dwordx2 v[88:89], v[54:55], off
	global_store_dwordx2 v[74:75], v[50:51], off offset:32
	global_store_dwordx2 v[90:91], v[46:47], off
	global_store_dwordx2 v[70:71], v[42:43], off offset:32
	global_store_dwordx2 v[92:93], v[38:39], off
	global_store_dwordx2 v[66:67], v[34:35], off offset:32
	global_store_dwordx2 v[78:79], v[44:45], off offset:256
	v_pk_mul_f32 v[30:31], v[130:131], v[30:31]
	s_nop 0
	v_pk_fma_f32 v[26:27], v[26:27], v[30:31], v[48:49]
	v_lshlrev_b32_e32 v48, 16, v95
	v_and_b32_e32 v49, 0xffff0000, v95
	v_pk_mul_f32 v[32:33], v[130:131], v[32:33]
	v_cvt_pk_bf16_f32 v26, v26, v27
	v_pk_fma_f32 v[28:29], v[28:29], v[32:33], v[48:49]
	s_nop 0
	v_cvt_pk_bf16_f32 v27, v28, v29
	global_store_dwordx2 v[78:79], v[26:27], off offset:288
	v_lshlrev_b32_e32 v26, 16, v84
	v_and_b32_e32 v27, 0xffff0000, v84
	v_pk_fma_f32 v[22:23], v[22:23], v[40:41], v[26:27]
	v_lshlrev_b32_e32 v26, 16, v85
	v_and_b32_e32 v27, 0xffff0000, v85
	v_pk_fma_f32 v[24:25], v[24:25], v[36:37], v[26:27]
	v_cvt_pk_bf16_f32 v22, v22, v23
	v_cvt_pk_bf16_f32 v23, v24, v25
	global_store_dwordx2 v[74:75], v[22:23], off offset:256
	v_lshlrev_b32_e32 v22, 16, v82
	v_and_b32_e32 v23, 0xffff0000, v82
	v_pk_fma_f32 v[18:19], v[18:19], v[30:31], v[22:23]
	v_lshlrev_b32_e32 v22, 16, v83
	v_and_b32_e32 v23, 0xffff0000, v83
	v_pk_fma_f32 v[20:21], v[20:21], v[32:33], v[22:23]
	v_cvt_pk_bf16_f32 v18, v18, v19
	v_cvt_pk_bf16_f32 v19, v20, v21
	global_store_dwordx2 v[74:75], v[18:19], off offset:288
	v_lshlrev_b32_e32 v18, 16, v80
	v_and_b32_e32 v19, 0xffff0000, v80
	v_pk_fma_f32 v[14:15], v[14:15], v[40:41], v[18:19]
	v_lshlrev_b32_e32 v18, 16, v81
	v_and_b32_e32 v19, 0xffff0000, v81
	v_pk_fma_f32 v[16:17], v[16:17], v[36:37], v[18:19]
	v_cvt_pk_bf16_f32 v14, v14, v15
	v_cvt_pk_bf16_f32 v15, v16, v17
	global_store_dwordx2 v[70:71], v[14:15], off offset:256
	v_lshlrev_b32_e32 v14, 16, v76
	v_and_b32_e32 v15, 0xffff0000, v76
	v_pk_fma_f32 v[10:11], v[10:11], v[30:31], v[14:15]
	v_lshlrev_b32_e32 v14, 16, v77
	v_and_b32_e32 v15, 0xffff0000, v77
	v_pk_fma_f32 v[12:13], v[12:13], v[32:33], v[14:15]
	v_cvt_pk_bf16_f32 v10, v10, v11
	v_cvt_pk_bf16_f32 v11, v12, v13
	global_store_dwordx2 v[70:71], v[10:11], off offset:288
	v_lshlrev_b32_e32 v10, 16, v72
	v_and_b32_e32 v11, 0xffff0000, v72
	v_pk_fma_f32 v[6:7], v[6:7], v[40:41], v[10:11]
	v_lshlrev_b32_e32 v10, 16, v73
	v_and_b32_e32 v11, 0xffff0000, v73
	v_pk_fma_f32 v[8:9], v[8:9], v[36:37], v[10:11]
	v_cvt_pk_bf16_f32 v6, v6, v7
	v_cvt_pk_bf16_f32 v7, v8, v9
	global_store_dwordx2 v[66:67], v[6:7], off offset:256
	v_lshlrev_b32_e32 v6, 16, v68
	v_and_b32_e32 v7, 0xffff0000, v68
	v_pk_fma_f32 v[2:3], v[2:3], v[30:31], v[6:7]
	v_lshlrev_b32_e32 v6, 16, v69
	v_and_b32_e32 v7, 0xffff0000, v69
	v_pk_fma_f32 v[4:5], v[4:5], v[32:33], v[6:7]
	v_cvt_pk_bf16_f32 v2, v2, v3
	v_cvt_pk_bf16_f32 v3, v4, v5
	global_store_dwordx2 v[66:67], v[2:3], off offset:288
	s_cbranch_scc1 .LBB0_1811
